# early GEMM barrier moved 8 MFMAs before block end (was 4); all other changes as previous
# baseline (speedup 1.0000x reference)
; #define PG8_STAGE(bufoff, gbase, voff) do { _Pragma("unroll") for (int _i = 0; _i < 2; ++_i) \
;         __builtin_amdgcn_global_load_lds((const unsigned*)((const char*)(gbase) + (voff)[_i]), (PG8_LAS unsigned*)(lds + (bufoff) + ldsw + _i * 8192), 16, 0, 0); } while (0)
; #define PG8_LDA(dst, b, h) do { _Pragma("unroll") for (int m = 0; m < 4; ++m) _Pragma("unroll") for (int k = 0; k < 2; ++k) dst[m][k] = *(const PG8_LAS bf16x8*)(lds + PG8_SA(b, h) + aoff + m * 2048 + k * 1024); } while (0)
; #define PG8_LDB(dst, b, h) do { _Pragma("unroll") for (int n = 0; n < 2; ++n) _Pragma("unroll") for (int k = 0; k < 2; ++k) dst[n][k] = *(const PG8_LAS bf16x8*)(lds + PG8_SB(b, h) + boff + n * 2048 + k * 1024); } while (0)
; #define PG8_MMA(ai, bj, At, Bt) do { __builtin_amdgcn_s_setprio(1); _Pragma("unroll") for (int m = 0; m < 4; ++m) _Pragma("unroll") for (int n = 0; n < 2; ++n) _Pragma("unroll") for (int k = 0; k < 2; ++k) \
;         acc[ai][bj][m][n] = __builtin_amdgcn_mfma_f32_16x16x32_bf16(Bt[n][k], At[m][k], acc[ai][bj][m][n], 0, 0, 0); __builtin_amdgcn_s_setprio(0); } while (0)
; #define PG8_WAIT_V(n) asm volatile("s_waitcnt vmcnt(" #n ")" ::: "memory")
; #define PG8_WAIT_L(n) asm volatile("s_waitcnt lgkmcnt(" #n ")" ::: "memory")
; #define PG8_BAR __builtin_amdgcn_s_barrier()
; #define PG8_SCHED __builtin_amdgcn_sched_barrier(0)
; template <class Epi, class Sched, bool ALIGN_EPI = false, bool SP2 = false>
; __device__ __forceinline__ void gemm_phase(PG8_LAS unsigned char* lds, const Gemm g, const Sched& S, const Epi& E) {
;     ...
;             PG8_LDB(B0, 0, 0); PG8_LDB(B1, 0, 1); PG8_SCHED; PG8_LDA(At, 0, 0); PG8_STAGE(PG8_SA(1, 1), a1 + hstep, voffA);
;             PG8_WAIT_V(8); PG8_WAIT_L(0); PG8_BAR; PG8_MMA(0, 0, At, B0); PG8_MMA(0, 1, At, B1); PG8_BAR; PG8_SCHED;
;             PG8_LDA(At, 0, 1); PG8_STAGE(PG8_SB(0, 0), b2, voffB); PG8_STAGE(PG8_SB(0, 1), b2 + hstep, voffB); PG8_STAGE(PG8_SA(0, 0), a2, voffA);
;             PG8_WAIT_V(8); PG8_WAIT_L(0); PG8_BAR; PG8_MMA(1, 0, At, B0); PG8_MMA(1, 1, At, B1); PG8_BAR; PG8_SCHED;
.LBB0_48:
	ds_read_b128 v[146:149], v153
	ds_read_b128 v[156:159], v153 offset:1024
	ds_read_b128 v[160:163], v153 offset:2048
	ds_read_b128 v[164:167], v153 offset:3072
	ds_read_b128 v[168:171], v154
	ds_read_b128 v[172:175], v154 offset:1024
	ds_read_b128 v[176:179], v154 offset:2048
	ds_read_b128 v[180:183], v154 offset:3072
	s_add_u32 s22, s20, 0xfff80080
	s_addc_u32 s23, s21, -1
	s_cmp_eq_u32 s53, 28
	s_cselect_b32 s25, s13, s23
	s_cselect_b32 s24, s45, s22
	s_cselect_b32 s23, s11, s52
	s_cselect_b32 s22, s50, s51
	v_lshl_add_u64 v[216:217], s[20:21], 0, v[138:139]
	s_add_i32 m0, s19, 0xc000
	ds_read_b128 v[184:187], v155
	ds_read_b128 v[188:191], v155 offset:1024
	ds_read_b128 v[192:195], v155 offset:2048
	ds_read_b128 v[196:199], v155 offset:3072
	ds_read_b128 v[200:203], v155 offset:4096
	ds_read_b128 v[204:207], v155 offset:5120
	ds_read_b128 v[208:211], v155 offset:6144
	ds_read_b128 v[212:215], v155 offset:7168
	global_load_lds_dwordx4 v[216:217], off
	v_lshl_add_u64 v[216:217], s[20:21], 0, v[140:141]
	s_add_i32 m0, s19, 0xe000
	s_nop 0
	global_load_lds_dwordx4 v[216:217], off
	s_waitcnt vmcnt(8)
	s_waitcnt lgkmcnt(0)
	s_barrier
	s_setprio 1
	s_waitcnt lgkmcnt(0)
	v_mfma_f32_16x16x32_bf16 v[124:127], v[146:149], v[184:187], v[124:127]
	v_mfma_f32_16x16x32_bf16 v[116:119], v[160:163], v[184:187], v[116:119]
	v_mfma_f32_16x16x32_bf16 v[108:111], v[146:149], v[192:195], v[108:111]
	v_mfma_f32_16x16x32_bf16 v[100:103], v[160:163], v[192:195], v[100:103]
	v_mfma_f32_16x16x32_bf16 v[92:95], v[146:149], v[200:203], v[92:95]
	v_mfma_f32_16x16x32_bf16 v[84:87], v[160:163], v[200:203], v[84:87]
	v_mfma_f32_16x16x32_bf16 v[76:79], v[146:149], v[208:211], v[76:79]
	v_mfma_f32_16x16x32_bf16 v[68:71], v[160:163], v[208:211], v[68:71]
	v_mfma_f32_16x16x32_bf16 v[124:127], v[156:159], v[188:191], v[124:127]
	v_mfma_f32_16x16x32_bf16 v[116:119], v[164:167], v[188:191], v[116:119]
	v_mfma_f32_16x16x32_bf16 v[108:111], v[156:159], v[196:199], v[108:111]
	v_mfma_f32_16x16x32_bf16 v[100:103], v[164:167], v[196:199], v[100:103]
	v_mfma_f32_16x16x32_bf16 v[92:95], v[156:159], v[204:207], v[92:95]
	v_mfma_f32_16x16x32_bf16 v[84:87], v[164:167], v[204:207], v[84:87]
	v_mfma_f32_16x16x32_bf16 v[76:79], v[156:159], v[212:215], v[76:79]
	v_mfma_f32_16x16x32_bf16 v[68:71], v[164:167], v[212:215], v[68:71]
	s_setprio 0
	s_setprio 1
	v_mfma_f32_16x16x32_bf16 v[120:123], v[168:171], v[184:187], v[120:123]
	v_mfma_f32_16x16x32_bf16 v[112:115], v[176:179], v[184:187], v[112:115]
	v_mfma_f32_16x16x32_bf16 v[104:107], v[168:171], v[192:195], v[104:107]
	v_mfma_f32_16x16x32_bf16 v[96:99], v[176:179], v[192:195], v[96:99]
	v_mfma_f32_16x16x32_bf16 v[88:91], v[168:171], v[200:203], v[88:91]
	v_mfma_f32_16x16x32_bf16 v[80:83], v[176:179], v[200:203], v[80:83]
	v_mfma_f32_16x16x32_bf16 v[72:75], v[168:171], v[208:211], v[72:75]
	v_mfma_f32_16x16x32_bf16 v[64:67], v[176:179], v[208:211], v[64:67]
	s_setprio 2
	s_barrier
	v_mfma_f32_16x16x32_bf16 v[120:123], v[172:175], v[188:191], v[120:123]
	v_mfma_f32_16x16x32_bf16 v[112:115], v[180:183], v[188:191], v[112:115]
	v_mfma_f32_16x16x32_bf16 v[104:107], v[172:175], v[196:199], v[104:107]
	v_mfma_f32_16x16x32_bf16 v[96:99], v[180:183], v[196:199], v[96:99]
	v_mfma_f32_16x16x32_bf16 v[88:91], v[172:175], v[204:207], v[88:91]
	v_mfma_f32_16x16x32_bf16 v[80:83], v[180:183], v[204:207], v[80:83]
	v_mfma_f32_16x16x32_bf16 v[72:75], v[172:175], v[212:215], v[72:75]
	v_mfma_f32_16x16x32_bf16 v[64:67], v[180:183], v[212:215], v[64:67]
	s_setprio 0
	s_add_i32 s54, s41, s28
	v_lshl_add_u64 v[216:217], s[22:23], 0, v[134:135]
	s_mov_b32 m0, s54
	ds_read_b128 v[184:187], v155 offset:16384
	ds_read_b128 v[188:191], v155 offset:17408
	ds_read_b128 v[192:195], v155 offset:18432
	ds_read_b128 v[196:199], v155 offset:19456
	ds_read_b128 v[200:203], v155 offset:20480
	ds_read_b128 v[204:207], v155 offset:21504
	ds_read_b128 v[208:211], v155 offset:22528
	ds_read_b128 v[212:215], v155 offset:23552
	global_load_lds_dwordx4 v[216:217], off
	s_add_i32 m0, s54, 0x2000
	s_add_u32 s54, s22, 0x80000
	v_lshl_add_u64 v[218:219], s[22:23], 0, v[130:131]
	s_addc_u32 s55, s23, 0
	s_add_i32 s56, s42, s28
	global_load_lds_dwordx4 v[218:219], off
	v_lshl_add_u64 v[220:221], s[54:55], 0, v[134:135]
	s_mov_b32 m0, s56
	v_lshl_add_u64 v[222:223], s[24:25], 0, v[132:133]
	global_load_lds_dwordx4 v[220:221], off
	v_lshl_add_u64 v[220:221], s[54:55], 0, v[130:131]
	s_add_i32 m0, s56, 0x2000
	s_nop 0
	global_load_lds_dwordx4 v[220:221], off
	v_lshl_add_u64 v[220:221], s[24:25], 0, v[136:137]
	s_mov_b32 m0, s19
	s_nop 0
	global_load_lds_dwordx4 v[220:221], off
	s_mov_b32 m0, s31
	s_nop 0
	global_load_lds_dwordx4 v[222:223], off
	s_waitcnt vmcnt(8)
	s_waitcnt lgkmcnt(0)
	s_barrier
	s_setprio 1
	s_waitcnt lgkmcnt(0)
	v_mfma_f32_16x16x32_bf16 v[60:63], v[146:149], v[184:187], v[60:63]
	v_mfma_f32_16x16x32_bf16 v[52:55], v[160:163], v[184:187], v[52:55]
	v_mfma_f32_16x16x32_bf16 v[44:47], v[146:149], v[192:195], v[44:47]
	v_mfma_f32_16x16x32_bf16 v[36:39], v[160:163], v[192:195], v[36:39]
	v_mfma_f32_16x16x32_bf16 v[28:31], v[146:149], v[200:203], v[28:31]
	v_mfma_f32_16x16x32_bf16 v[20:23], v[160:163], v[200:203], v[20:23]
	v_mfma_f32_16x16x32_bf16 v[12:15], v[146:149], v[208:211], v[12:15]
	v_mfma_f32_16x16x32_bf16 v[4:7], v[160:163], v[208:211], v[4:7]
	v_mfma_f32_16x16x32_bf16 v[60:63], v[156:159], v[188:191], v[60:63]
	v_mfma_f32_16x16x32_bf16 v[52:55], v[164:167], v[188:191], v[52:55]
	v_mfma_f32_16x16x32_bf16 v[44:47], v[156:159], v[196:199], v[44:47]
	v_mfma_f32_16x16x32_bf16 v[36:39], v[164:167], v[196:199], v[36:39]
	v_mfma_f32_16x16x32_bf16 v[28:31], v[156:159], v[204:207], v[28:31]
	v_mfma_f32_16x16x32_bf16 v[20:23], v[164:167], v[204:207], v[20:23]
	v_mfma_f32_16x16x32_bf16 v[12:15], v[156:159], v[212:215], v[12:15]
	v_mfma_f32_16x16x32_bf16 v[4:7], v[164:167], v[212:215], v[4:7]
	s_setprio 0
	s_setprio 1
	v_mfma_f32_16x16x32_bf16 v[56:59], v[168:171], v[184:187], v[56:59]
	v_mfma_f32_16x16x32_bf16 v[48:51], v[176:179], v[184:187], v[48:51]
	v_mfma_f32_16x16x32_bf16 v[40:43], v[168:171], v[192:195], v[40:43]
	v_mfma_f32_16x16x32_bf16 v[32:35], v[176:179], v[192:195], v[32:35]
	v_mfma_f32_16x16x32_bf16 v[24:27], v[168:171], v[200:203], v[24:27]
	v_mfma_f32_16x16x32_bf16 v[16:19], v[176:179], v[200:203], v[16:19]
	v_mfma_f32_16x16x32_bf16 v[8:11], v[168:171], v[208:211], v[8:11]
	v_mfma_f32_16x16x32_bf16 v[0:3], v[176:179], v[208:211], v[0:3]
	s_setprio 2
	s_barrier
; #define PG8_STAGE(bufoff, gbase, voff) do { _Pragma("unroll") for (int _i = 0; _i < 2; ++_i) \
;         __builtin_amdgcn_global_load_lds((const unsigned*)((const char*)(gbase) + (voff)[_i]), (PG8_LAS unsigned*)(lds + (bufoff) + ldsw + _i * 8192), 16, 0, 0); } while (0)
; #define PG8_LDA(dst, b, h) do { _Pragma("unroll") for (int m = 0; m < 4; ++m) _Pragma("unroll") for (int k = 0; k < 2; ++k) dst[m][k] = *(const PG8_LAS bf16x8*)(lds + PG8_SA(b, h) + aoff + m * 2048 + k * 1024); } while (0)
; #define PG8_LDB(dst, b, h) do { _Pragma("unroll") for (int n = 0; n < 2; ++n) _Pragma("unroll") for (int k = 0; k < 2; ++k) dst[n][k] = *(const PG8_LAS bf16x8*)(lds + PG8_SB(b, h) + boff + n * 2048 + k * 1024); } while (0)
; #define PG8_MMA(ai, bj, At, Bt) do { __builtin_amdgcn_s_setprio(1); _Pragma("unroll") for (int m = 0; m < 4; ++m) _Pragma("unroll") for (int n = 0; n < 2; ++n) _Pragma("unroll") for (int k = 0; k < 2; ++k) \
;         acc[ai][bj][m][n] = __builtin_amdgcn_mfma_f32_16x16x32_bf16(Bt[n][k], At[m][k], acc[ai][bj][m][n], 0, 0, 0); __builtin_amdgcn_s_setprio(0); } while (0)
; #define PG8_WAIT_V(n) asm volatile("s_waitcnt vmcnt(" #n ")" ::: "memory")
; #define PG8_WAIT_L(n) asm volatile("s_waitcnt lgkmcnt(" #n ")" ::: "memory")
; #define PG8_BAR __builtin_amdgcn_s_barrier()
; #define PG8_SCHED __builtin_amdgcn_sched_barrier(0)
; template <class Epi, class Sched, bool ALIGN_EPI = false, bool SP2 = false>
; __device__ __forceinline__ void gemm_phase(PG8_LAS unsigned char* lds, const Gemm g, const Sched& S, const Epi& E) {
;     ...
;             PG8_WAIT_V(8); PG8_WAIT_L(0); PG8_BAR; PG8_MMA(1, 0, At, B0); PG8_MMA(1, 1, At, B1); PG8_BAR; PG8_SCHED;
;             PG8_LDB(B0, 1, 0); PG8_LDB(B1, 1, 1); PG8_SCHED; PG8_LDA(At, 1, 0); PG8_STAGE(PG8_SA(0, 1), a2 + hstep, voffA);
;             PG8_WAIT_V(8); PG8_WAIT_L(0); PG8_BAR; PG8_MMA(0, 0, At, B0); PG8_MMA(0, 1, At, B1); PG8_BAR; PG8_SCHED;
	v_mfma_f32_16x16x32_bf16 v[56:59], v[172:175], v[188:191], v[56:59]
	v_mfma_f32_16x16x32_bf16 v[48:51], v[180:183], v[188:191], v[48:51]
	v_mfma_f32_16x16x32_bf16 v[40:43], v[172:175], v[196:199], v[40:43]
	v_mfma_f32_16x16x32_bf16 v[32:35], v[180:183], v[196:199], v[32:35]
	v_mfma_f32_16x16x32_bf16 v[24:27], v[172:175], v[204:207], v[24:27]
	v_mfma_f32_16x16x32_bf16 v[16:19], v[180:183], v[204:207], v[16:19]
	v_mfma_f32_16x16x32_bf16 v[8:11], v[172:175], v[212:215], v[8:11]
	v_mfma_f32_16x16x32_bf16 v[0:3], v[180:183], v[212:215], v[0:3]
	s_setprio 0
	s_add_i32 s54, 0, 0x18000
	s_add_i32 s55, 0, 0x1c000
	v_add_u32_e32 v164, s54, v151
	v_add_u32_e32 v180, s55, v151
	ds_read_b128 v[146:149], v164
	ds_read_b128 v[156:159], v164 offset:1024
	ds_read_b128 v[160:163], v164 offset:2048
	ds_read_b128 v[164:167], v164 offset:3072
	ds_read_b128 v[168:171], v180
	ds_read_b128 v[172:175], v180 offset:1024
	ds_read_b128 v[176:179], v180 offset:2048
	ds_read_b128 v[180:183], v180 offset:3072
	s_add_u32 s24, s24, 0x80000
	s_addc_u32 s25, s25, 0
	s_mov_b32 m0, s34
	v_lshl_add_u64 v[224:225], s[24:25], 0, v[136:137]
	ds_read_b128 v[184:187], v155 offset:32768
	ds_read_b128 v[188:191], v155 offset:33792
	ds_read_b128 v[192:195], v155 offset:34816
	ds_read_b128 v[196:199], v155 offset:35840
	ds_read_b128 v[200:203], v155 offset:36864
	ds_read_b128 v[204:207], v155 offset:37888
	ds_read_b128 v[208:211], v155 offset:38912
	ds_read_b128 v[212:215], v155 offset:39936
	global_load_lds_dwordx4 v[224:225], off
	v_lshl_add_u64 v[224:225], s[24:25], 0, v[132:133]
	s_mov_b32 m0, s35
	s_nop 0
	global_load_lds_dwordx4 v[224:225], off
	s_waitcnt vmcnt(8)
	s_waitcnt lgkmcnt(0)
	s_barrier
	s_setprio 1
	s_waitcnt lgkmcnt(0)
	v_mfma_f32_16x16x32_bf16 v[124:127], v[146:149], v[184:187], v[124:127]
	v_mfma_f32_16x16x32_bf16 v[116:119], v[160:163], v[184:187], v[116:119]
	v_mfma_f32_16x16x32_bf16 v[108:111], v[146:149], v[192:195], v[108:111]
	v_mfma_f32_16x16x32_bf16 v[100:103], v[160:163], v[192:195], v[100:103]
	v_mfma_f32_16x16x32_bf16 v[92:95], v[146:149], v[200:203], v[92:95]
	v_mfma_f32_16x16x32_bf16 v[84:87], v[160:163], v[200:203], v[84:87]
	v_mfma_f32_16x16x32_bf16 v[76:79], v[146:149], v[208:211], v[76:79]
	v_mfma_f32_16x16x32_bf16 v[68:71], v[160:163], v[208:211], v[68:71]
	v_mfma_f32_16x16x32_bf16 v[124:127], v[156:159], v[188:191], v[124:127]
	v_mfma_f32_16x16x32_bf16 v[116:119], v[164:167], v[188:191], v[116:119]
	v_mfma_f32_16x16x32_bf16 v[108:111], v[156:159], v[196:199], v[108:111]
	v_mfma_f32_16x16x32_bf16 v[100:103], v[164:167], v[196:199], v[100:103]
	v_mfma_f32_16x16x32_bf16 v[92:95], v[156:159], v[204:207], v[92:95]
	v_mfma_f32_16x16x32_bf16 v[84:87], v[164:167], v[204:207], v[84:87]
	v_mfma_f32_16x16x32_bf16 v[76:79], v[156:159], v[212:215], v[76:79]
	v_mfma_f32_16x16x32_bf16 v[68:71], v[164:167], v[212:215], v[68:71]
	s_setprio 0
	s_setprio 1
	v_mfma_f32_16x16x32_bf16 v[120:123], v[168:171], v[184:187], v[120:123]
	v_mfma_f32_16x16x32_bf16 v[112:115], v[176:179], v[184:187], v[112:115]
	v_mfma_f32_16x16x32_bf16 v[104:107], v[168:171], v[192:195], v[104:107]
	v_mfma_f32_16x16x32_bf16 v[96:99], v[176:179], v[192:195], v[96:99]
	v_mfma_f32_16x16x32_bf16 v[88:91], v[168:171], v[200:203], v[88:91]
	v_mfma_f32_16x16x32_bf16 v[80:83], v[176:179], v[200:203], v[80:83]
	v_mfma_f32_16x16x32_bf16 v[72:75], v[168:171], v[208:211], v[72:75]
	v_mfma_f32_16x16x32_bf16 v[64:67], v[176:179], v[208:211], v[64:67]
	s_setprio 2
	s_barrier
; #define PG8_STAGE(bufoff, gbase, voff) do { _Pragma("unroll") for (int _i = 0; _i < 2; ++_i) \
;         __builtin_amdgcn_global_load_lds((const unsigned*)((const char*)(gbase) + (voff)[_i]), (PG8_LAS unsigned*)(lds + (bufoff) + ldsw + _i * 8192), 16, 0, 0); } while (0)
; #define PG8_LDA(dst, b, h) do { _Pragma("unroll") for (int m = 0; m < 4; ++m) _Pragma("unroll") for (int k = 0; k < 2; ++k) dst[m][k] = *(const PG8_LAS bf16x8*)(lds + PG8_SA(b, h) + aoff + m * 2048 + k * 1024); } while (0)
; #define PG8_MMA(ai, bj, At, Bt) do { __builtin_amdgcn_s_setprio(1); _Pragma("unroll") for (int m = 0; m < 4; ++m) _Pragma("unroll") for (int n = 0; n < 2; ++n) _Pragma("unroll") for (int k = 0; k < 2; ++k) \
;         acc[ai][bj][m][n] = __builtin_amdgcn_mfma_f32_16x16x32_bf16(Bt[n][k], At[m][k], acc[ai][bj][m][n], 0, 0, 0); __builtin_amdgcn_s_setprio(0); } while (0)
; #define PG8_WAIT_V(n) asm volatile("s_waitcnt vmcnt(" #n ")" ::: "memory")
; #define PG8_WAIT_L(n) asm volatile("s_waitcnt lgkmcnt(" #n ")" ::: "memory")
; #define PG8_BAR __builtin_amdgcn_s_barrier()
; #define PG8_SCHED __builtin_amdgcn_sched_barrier(0)
; template <class Epi, class Sched, bool ALIGN_EPI = false, bool SP2 = false>
; __device__ __forceinline__ void gemm_phase(PG8_LAS unsigned char* lds, const Gemm g, const Sched& S, const Epi& E) {
;     ...
;         for (int t = 0; t < nt; t += 2) {
;     ...
;             PG8_WAIT_V(8); PG8_WAIT_L(0); PG8_BAR; PG8_MMA(0, 0, At, B0); PG8_MMA(0, 1, At, B1); PG8_BAR; PG8_SCHED;
;             PG8_LDA(At, 1, 1); PG8_STAGE(PG8_SB(1, 0), b3, voffB); PG8_STAGE(PG8_SB(1, 1), b3 + hstep, voffB); PG8_STAGE(PG8_SA(1, 0), a3, voffA);
;             PG8_WAIT_V(8); PG8_WAIT_L(0); PG8_BAR; PG8_MMA(1, 0, At, B0); PG8_MMA(1, 1, At, B1); PG8_BAR; PG8_SCHED;
	v_mfma_f32_16x16x32_bf16 v[120:123], v[172:175], v[188:191], v[120:123]
	v_mfma_f32_16x16x32_bf16 v[112:115], v[180:183], v[188:191], v[112:115]
	v_mfma_f32_16x16x32_bf16 v[104:107], v[172:175], v[196:199], v[104:107]
	v_mfma_f32_16x16x32_bf16 v[96:99], v[180:183], v[196:199], v[96:99]
	v_mfma_f32_16x16x32_bf16 v[88:91], v[172:175], v[204:207], v[88:91]
	v_mfma_f32_16x16x32_bf16 v[80:83], v[180:183], v[204:207], v[80:83]
	v_mfma_f32_16x16x32_bf16 v[72:75], v[172:175], v[212:215], v[72:75]
	v_mfma_f32_16x16x32_bf16 v[64:67], v[180:183], v[212:215], v[64:67]
	s_setprio 0
	s_add_i32 s24, s54, s28
	v_lshl_add_u64 v[216:217], v[216:217], 0, s[4:5]
	s_mov_b32 m0, s24
	ds_read_b128 v[184:187], v155 offset:49152
	ds_read_b128 v[188:191], v155 offset:50176
	ds_read_b128 v[192:195], v155 offset:51200
	ds_read_b128 v[196:199], v155 offset:52224
	ds_read_b128 v[200:203], v155 offset:53248
	ds_read_b128 v[204:207], v155 offset:54272
	ds_read_b128 v[208:211], v155 offset:55296
	ds_read_b128 v[212:215], v155 offset:56320
	global_load_lds_dwordx4 v[216:217], off
	s_add_i32 m0, s24, 0x2000
	s_add_u32 s22, s22, 0x80080
	v_lshl_add_u64 v[216:217], v[218:219], 0, s[4:5]
	s_addc_u32 s23, s23, 0
	s_add_i32 s24, s55, s28
	global_load_lds_dwordx4 v[216:217], off
	v_lshl_add_u64 v[216:217], s[22:23], 0, v[134:135]
	s_mov_b32 m0, s24
	s_nop 0
	global_load_lds_dwordx4 v[216:217], off
	v_lshl_add_u64 v[216:217], s[22:23], 0, v[130:131]
	s_add_i32 m0, s24, 0x2000
	s_nop 0
	global_load_lds_dwordx4 v[216:217], off
	v_lshl_add_u64 v[216:217], v[220:221], 0, s[4:5]
	s_mov_b32 m0, s37
	s_nop 0
	global_load_lds_dwordx4 v[216:217], off
	v_lshl_add_u64 v[216:217], v[222:223], 0, s[4:5]
	s_mov_b32 m0, s38
	s_nop 0
	global_load_lds_dwordx4 v[216:217], off
	s_waitcnt vmcnt(8)
	s_waitcnt lgkmcnt(0)
	s_barrier
	s_setprio 1
	s_waitcnt lgkmcnt(0)
	v_mfma_f32_16x16x32_bf16 v[60:63], v[146:149], v[184:187], v[60:63]
	v_mfma_f32_16x16x32_bf16 v[52:55], v[160:163], v[184:187], v[52:55]
	v_mfma_f32_16x16x32_bf16 v[44:47], v[146:149], v[192:195], v[44:47]
	v_mfma_f32_16x16x32_bf16 v[36:39], v[160:163], v[192:195], v[36:39]
	v_mfma_f32_16x16x32_bf16 v[28:31], v[146:149], v[200:203], v[28:31]
	v_mfma_f32_16x16x32_bf16 v[20:23], v[160:163], v[200:203], v[20:23]
	v_mfma_f32_16x16x32_bf16 v[12:15], v[146:149], v[208:211], v[12:15]
	v_mfma_f32_16x16x32_bf16 v[4:7], v[160:163], v[208:211], v[4:7]
	v_mfma_f32_16x16x32_bf16 v[60:63], v[156:159], v[188:191], v[60:63]
	v_mfma_f32_16x16x32_bf16 v[52:55], v[164:167], v[188:191], v[52:55]
	v_mfma_f32_16x16x32_bf16 v[44:47], v[156:159], v[196:199], v[44:47]
	v_mfma_f32_16x16x32_bf16 v[36:39], v[164:167], v[196:199], v[36:39]
	v_mfma_f32_16x16x32_bf16 v[28:31], v[156:159], v[204:207], v[28:31]
	v_mfma_f32_16x16x32_bf16 v[20:23], v[164:167], v[204:207], v[20:23]
	v_mfma_f32_16x16x32_bf16 v[12:15], v[156:159], v[212:215], v[12:15]
	v_mfma_f32_16x16x32_bf16 v[4:7], v[164:167], v[212:215], v[4:7]
	s_setprio 0
	s_setprio 1
	v_mfma_f32_16x16x32_bf16 v[56:59], v[168:171], v[184:187], v[56:59]
	v_mfma_f32_16x16x32_bf16 v[48:51], v[176:179], v[184:187], v[48:51]
	v_mfma_f32_16x16x32_bf16 v[40:43], v[168:171], v[192:195], v[40:43]
	v_mfma_f32_16x16x32_bf16 v[32:35], v[176:179], v[192:195], v[32:35]
	v_mfma_f32_16x16x32_bf16 v[24:27], v[168:171], v[200:203], v[24:27]
	v_mfma_f32_16x16x32_bf16 v[16:19], v[176:179], v[200:203], v[16:19]
	v_mfma_f32_16x16x32_bf16 v[8:11], v[168:171], v[208:211], v[8:11]
	v_mfma_f32_16x16x32_bf16 v[0:3], v[176:179], v[208:211], v[0:3]
	s_setprio 2
	s_barrier
	v_mfma_f32_16x16x32_bf16 v[56:59], v[172:175], v[188:191], v[56:59]
	v_mfma_f32_16x16x32_bf16 v[48:51], v[180:183], v[188:191], v[48:51]
	v_mfma_f32_16x16x32_bf16 v[40:43], v[172:175], v[196:199], v[40:43]
	v_mfma_f32_16x16x32_bf16 v[32:35], v[180:183], v[196:199], v[32:35]
	v_mfma_f32_16x16x32_bf16 v[24:27], v[172:175], v[204:207], v[24:27]
	v_mfma_f32_16x16x32_bf16 v[16:19], v[180:183], v[204:207], v[16:19]
	v_mfma_f32_16x16x32_bf16 v[8:11], v[172:175], v[212:215], v[8:11]
	v_mfma_f32_16x16x32_bf16 v[0:3], v[180:183], v[212:215], v[0:3]
	s_setprio 0
	s_add_i32 s53, s53, 2
	s_add_u32 s20, s20, 0x100
	s_addc_u32 s21, s21, 0
	s_add_u32 s51, s51, 0x100
	s_addc_u32 s52, s52, 0
	s_cmp_gt_u32 s53, 29
	s_cbranch_scc0 .LBB0_48
	s_and_b64 vcc, exec, s[8:9]
	s_cbranch_vccz .LBB0_51
	s_barrier

; #define PG8_STAGE(bufoff, gbase, voff) do { _Pragma("unroll") for (int _i = 0; _i < 2; ++_i) \
;         __builtin_amdgcn_global_load_lds((const unsigned*)((const char*)(gbase) + (voff)[_i]), (PG8_LAS unsigned*)(lds + (bufoff) + ldsw + _i * 8192), 16, 0, 0); } while (0)
; #define PG8_LDA(dst, b, h) do { _Pragma("unroll") for (int m = 0; m < 4; ++m) _Pragma("unroll") for (int k = 0; k < 2; ++k) dst[m][k] = *(const PG8_LAS bf16x8*)(lds + PG8_SA(b, h) + aoff + m * 2048 + k * 1024); } while (0)
; #define PG8_LDB(dst, b, h) do { _Pragma("unroll") for (int n = 0; n < 2; ++n) _Pragma("unroll") for (int k = 0; k < 2; ++k) dst[n][k] = *(const PG8_LAS bf16x8*)(lds + PG8_SB(b, h) + boff + n * 2048 + k * 1024); } while (0)
; #define PG8_MMA(ai, bj, At, Bt) do { __builtin_amdgcn_s_setprio(1); _Pragma("unroll") for (int m = 0; m < 4; ++m) _Pragma("unroll") for (int n = 0; n < 2; ++n) _Pragma("unroll") for (int k = 0; k < 2; ++k) \
;         acc[ai][bj][m][n] = __builtin_amdgcn_mfma_f32_16x16x32_bf16(Bt[n][k], At[m][k], acc[ai][bj][m][n], 0, 0, 0); __builtin_amdgcn_s_setprio(0); } while (0)
; #define PG8_WAIT_V(n) asm volatile("s_waitcnt vmcnt(" #n ")" ::: "memory")
; #define PG8_WAIT_L(n) asm volatile("s_waitcnt lgkmcnt(" #n ")" ::: "memory")
; #define PG8_BAR __builtin_amdgcn_s_barrier()
; #define PG8_SCHED __builtin_amdgcn_sched_barrier(0)
; template <class Epi, class Sched, bool ALIGN_EPI = false, bool SP2 = false>
; __device__ __forceinline__ void gemm_phase(PG8_LAS unsigned char* lds, const Gemm g, const Sched& S, const Epi& E) {
;     ...
;             PG8_LDB(B0, 0, 0); PG8_LDB(B1, 0, 1); PG8_SCHED; PG8_LDA(At, 0, 0); PG8_STAGE(PG8_SA(1, 1), a1 + hstep, voffA);
;             PG8_WAIT_V(8); PG8_WAIT_L(0); PG8_BAR; PG8_MMA(0, 0, At, B0); PG8_MMA(0, 1, At, B1); PG8_BAR; PG8_SCHED;
;             PG8_LDA(At, 0, 1); PG8_STAGE(PG8_SB(0, 0), b2, voffB); PG8_STAGE(PG8_SB(0, 1), b2 + hstep, voffB); PG8_STAGE(PG8_SA(0, 0), a2, voffA);
;             PG8_WAIT_V(8); PG8_WAIT_L(0); PG8_BAR; PG8_MMA(1, 0, At, B0); PG8_MMA(1, 1, At, B1); PG8_BAR; PG8_SCHED;
.LBB0_140:
	ds_read_b128 v[158:161], v155
	ds_read_b128 v[162:165], v155 offset:1024
	ds_read_b128 v[166:169], v155 offset:2048
	ds_read_b128 v[170:173], v155 offset:3072
	ds_read_b128 v[174:177], v156
	ds_read_b128 v[178:181], v156 offset:1024
	ds_read_b128 v[182:185], v156 offset:2048
	ds_read_b128 v[186:189], v156 offset:3072
	s_add_u32 s24, s22, 0xffea0080
	s_addc_u32 s25, s23, -1
	s_cmpk_eq_i32 s58, 0x54
	s_cselect_b32 s27, s19, s25
	s_cselect_b32 s26, s18, s24
	s_cselect_b32 s25, s21, s57
	s_cselect_b32 s24, s20, s56
	v_lshl_add_u64 v[222:223], s[22:23], 0, v[138:139]
	s_add_i32 m0, s31, 0xc000
	ds_read_b128 v[190:193], v157
	ds_read_b128 v[194:197], v157 offset:1024
	ds_read_b128 v[198:201], v157 offset:2048
	ds_read_b128 v[202:205], v157 offset:3072
	ds_read_b128 v[206:209], v157 offset:4096
	ds_read_b128 v[210:213], v157 offset:5120
	ds_read_b128 v[214:217], v157 offset:6144
	ds_read_b128 v[218:221], v157 offset:7168
	global_load_lds_dwordx4 v[222:223], off
	v_lshl_add_u64 v[222:223], s[22:23], 0, v[140:141]
	s_add_i32 m0, s31, 0xe000
	s_nop 0
	global_load_lds_dwordx4 v[222:223], off
	s_waitcnt vmcnt(8)
	s_waitcnt lgkmcnt(0)
	s_barrier
	s_setprio 1
	s_waitcnt lgkmcnt(0)
	v_mfma_f32_16x16x32_bf16 v[124:127], v[158:161], v[190:193], v[124:127]
	v_mfma_f32_16x16x32_bf16 v[120:123], v[166:169], v[190:193], v[120:123]
	v_mfma_f32_16x16x32_bf16 v[116:119], v[158:161], v[198:201], v[116:119]
	v_mfma_f32_16x16x32_bf16 v[112:115], v[166:169], v[198:201], v[112:115]
	v_mfma_f32_16x16x32_bf16 v[100:103], v[158:161], v[206:209], v[100:103]
	v_mfma_f32_16x16x32_bf16 v[96:99], v[166:169], v[206:209], v[96:99]
	v_mfma_f32_16x16x32_bf16 v[84:87], v[158:161], v[214:217], v[84:87]
	v_mfma_f32_16x16x32_bf16 v[80:83], v[166:169], v[214:217], v[80:83]
	v_mfma_f32_16x16x32_bf16 v[124:127], v[162:165], v[194:197], v[124:127]
	v_mfma_f32_16x16x32_bf16 v[120:123], v[170:173], v[194:197], v[120:123]
	v_mfma_f32_16x16x32_bf16 v[116:119], v[162:165], v[202:205], v[116:119]
	v_mfma_f32_16x16x32_bf16 v[112:115], v[170:173], v[202:205], v[112:115]
	v_mfma_f32_16x16x32_bf16 v[100:103], v[162:165], v[210:213], v[100:103]
	v_mfma_f32_16x16x32_bf16 v[96:99], v[170:173], v[210:213], v[96:99]
	v_mfma_f32_16x16x32_bf16 v[84:87], v[162:165], v[218:221], v[84:87]
	v_mfma_f32_16x16x32_bf16 v[80:83], v[170:173], v[218:221], v[80:83]
	s_setprio 0
	s_setprio 1
	v_mfma_f32_16x16x32_bf16 v[108:111], v[174:177], v[190:193], v[108:111]
	v_mfma_f32_16x16x32_bf16 v[104:107], v[182:185], v[190:193], v[104:107]
	v_mfma_f32_16x16x32_bf16 v[92:95], v[174:177], v[198:201], v[92:95]
	v_mfma_f32_16x16x32_bf16 v[88:91], v[182:185], v[198:201], v[88:91]
	v_mfma_f32_16x16x32_bf16 v[76:79], v[174:177], v[206:209], v[76:79]
	v_mfma_f32_16x16x32_bf16 v[72:75], v[182:185], v[206:209], v[72:75]
	v_mfma_f32_16x16x32_bf16 v[68:71], v[174:177], v[214:217], v[68:71]
	v_mfma_f32_16x16x32_bf16 v[64:67], v[182:185], v[214:217], v[64:67]
	s_setprio 2
	s_barrier
	v_mfma_f32_16x16x32_bf16 v[108:111], v[178:181], v[194:197], v[108:111]
	v_mfma_f32_16x16x32_bf16 v[104:107], v[186:189], v[194:197], v[104:107]
	v_mfma_f32_16x16x32_bf16 v[92:95], v[178:181], v[202:205], v[92:95]
	v_mfma_f32_16x16x32_bf16 v[88:91], v[186:189], v[202:205], v[88:91]
	v_mfma_f32_16x16x32_bf16 v[76:79], v[178:181], v[210:213], v[76:79]
	v_mfma_f32_16x16x32_bf16 v[72:75], v[186:189], v[210:213], v[72:75]
	v_mfma_f32_16x16x32_bf16 v[68:71], v[178:181], v[218:221], v[68:71]
	v_mfma_f32_16x16x32_bf16 v[64:67], v[186:189], v[218:221], v[64:67]
	s_setprio 0
	s_add_i32 s59, s42, s28
	v_lshl_add_u64 v[222:223], s[24:25], 0, v[132:133]
	s_mov_b32 m0, s59
	ds_read_b128 v[190:193], v157 offset:16384
	ds_read_b128 v[194:197], v157 offset:17408
	ds_read_b128 v[198:201], v157 offset:18432
	ds_read_b128 v[202:205], v157 offset:19456
	ds_read_b128 v[206:209], v157 offset:20480
	ds_read_b128 v[210:213], v157 offset:21504
	ds_read_b128 v[214:217], v157 offset:22528
	ds_read_b128 v[218:221], v157 offset:23552
	global_load_lds_dwordx4 v[222:223], off
	s_add_i32 m0, s59, 0x2000
	s_add_u32 s60, s24, 0x160000
	v_lshl_add_u64 v[224:225], s[24:25], 0, v[136:137]
	s_addc_u32 s61, s25, 0
	s_add_i32 s59, s43, s28
	global_load_lds_dwordx4 v[224:225], off
	v_lshl_add_u64 v[226:227], s[60:61], 0, v[132:133]
	s_mov_b32 m0, s59
	v_lshl_add_u64 v[228:229], s[26:27], 0, v[134:135]
	global_load_lds_dwordx4 v[226:227], off
	v_lshl_add_u64 v[226:227], s[60:61], 0, v[136:137]
	s_add_i32 m0, s59, 0x2000
	s_nop 0
	global_load_lds_dwordx4 v[226:227], off
	v_lshl_add_u64 v[226:227], s[26:27], 0, v[130:131]
	s_mov_b32 m0, s31
	s_nop 0
	global_load_lds_dwordx4 v[226:227], off
	s_mov_b32 m0, s34
	s_nop 0
	global_load_lds_dwordx4 v[228:229], off
	s_waitcnt vmcnt(8)
	s_waitcnt lgkmcnt(0)
	s_barrier
	s_setprio 1
	s_waitcnt lgkmcnt(0)
	v_mfma_f32_16x16x32_bf16 v[60:63], v[158:161], v[190:193], v[60:63]
	v_mfma_f32_16x16x32_bf16 v[56:59], v[166:169], v[190:193], v[56:59]
	v_mfma_f32_16x16x32_bf16 v[52:55], v[158:161], v[198:201], v[52:55]
	v_mfma_f32_16x16x32_bf16 v[48:51], v[166:169], v[198:201], v[48:51]
	v_mfma_f32_16x16x32_bf16 v[36:39], v[158:161], v[206:209], v[36:39]
	v_mfma_f32_16x16x32_bf16 v[32:35], v[166:169], v[206:209], v[32:35]
	v_mfma_f32_16x16x32_bf16 v[20:23], v[158:161], v[214:217], v[20:23]
	v_mfma_f32_16x16x32_bf16 v[16:19], v[166:169], v[214:217], v[16:19]
	v_mfma_f32_16x16x32_bf16 v[60:63], v[162:165], v[194:197], v[60:63]
	v_mfma_f32_16x16x32_bf16 v[56:59], v[170:173], v[194:197], v[56:59]
	v_mfma_f32_16x16x32_bf16 v[52:55], v[162:165], v[202:205], v[52:55]
	v_mfma_f32_16x16x32_bf16 v[48:51], v[170:173], v[202:205], v[48:51]
	v_mfma_f32_16x16x32_bf16 v[36:39], v[162:165], v[210:213], v[36:39]
	v_mfma_f32_16x16x32_bf16 v[32:35], v[170:173], v[210:213], v[32:35]
	v_mfma_f32_16x16x32_bf16 v[20:23], v[162:165], v[218:221], v[20:23]
	v_mfma_f32_16x16x32_bf16 v[16:19], v[170:173], v[218:221], v[16:19]
	s_setprio 0
	s_setprio 1
	v_mfma_f32_16x16x32_bf16 v[44:47], v[174:177], v[190:193], v[44:47]
	v_mfma_f32_16x16x32_bf16 v[40:43], v[182:185], v[190:193], v[40:43]
	v_mfma_f32_16x16x32_bf16 v[28:31], v[174:177], v[198:201], v[28:31]
	v_mfma_f32_16x16x32_bf16 v[24:27], v[182:185], v[198:201], v[24:27]
	v_mfma_f32_16x16x32_bf16 v[12:15], v[174:177], v[206:209], v[12:15]
	v_mfma_f32_16x16x32_bf16 v[8:11], v[182:185], v[206:209], v[8:11]
	v_mfma_f32_16x16x32_bf16 v[4:7], v[174:177], v[214:217], v[4:7]
	v_mfma_f32_16x16x32_bf16 v[0:3], v[182:185], v[214:217], v[0:3]
	s_setprio 2
	s_barrier
; #define PG8_STAGE(bufoff, gbase, voff) do { _Pragma("unroll") for (int _i = 0; _i < 2; ++_i) \
;         __builtin_amdgcn_global_load_lds((const unsigned*)((const char*)(gbase) + (voff)[_i]), (PG8_LAS unsigned*)(lds + (bufoff) + ldsw + _i * 8192), 16, 0, 0); } while (0)
; #define PG8_LDA(dst, b, h) do { _Pragma("unroll") for (int m = 0; m < 4; ++m) _Pragma("unroll") for (int k = 0; k < 2; ++k) dst[m][k] = *(const PG8_LAS bf16x8*)(lds + PG8_SA(b, h) + aoff + m * 2048 + k * 1024); } while (0)
; #define PG8_LDB(dst, b, h) do { _Pragma("unroll") for (int n = 0; n < 2; ++n) _Pragma("unroll") for (int k = 0; k < 2; ++k) dst[n][k] = *(const PG8_LAS bf16x8*)(lds + PG8_SB(b, h) + boff + n * 2048 + k * 1024); } while (0)
; #define PG8_MMA(ai, bj, At, Bt) do { __builtin_amdgcn_s_setprio(1); _Pragma("unroll") for (int m = 0; m < 4; ++m) _Pragma("unroll") for (int n = 0; n < 2; ++n) _Pragma("unroll") for (int k = 0; k < 2; ++k) \
;         acc[ai][bj][m][n] = __builtin_amdgcn_mfma_f32_16x16x32_bf16(Bt[n][k], At[m][k], acc[ai][bj][m][n], 0, 0, 0); __builtin_amdgcn_s_setprio(0); } while (0)
; #define PG8_WAIT_V(n) asm volatile("s_waitcnt vmcnt(" #n ")" ::: "memory")
; #define PG8_WAIT_L(n) asm volatile("s_waitcnt lgkmcnt(" #n ")" ::: "memory")
; #define PG8_BAR __builtin_amdgcn_s_barrier()
; #define PG8_SCHED __builtin_amdgcn_sched_barrier(0)
; template <class Epi, class Sched, bool ALIGN_EPI = false, bool SP2 = false>
; __device__ __forceinline__ void gemm_phase(PG8_LAS unsigned char* lds, const Gemm g, const Sched& S, const Epi& E) {
;     ...
;             PG8_WAIT_V(8); PG8_WAIT_L(0); PG8_BAR; PG8_MMA(1, 0, At, B0); PG8_MMA(1, 1, At, B1); PG8_BAR; PG8_SCHED;
;             PG8_LDB(B0, 1, 0); PG8_LDB(B1, 1, 1); PG8_SCHED; PG8_LDA(At, 1, 0); PG8_STAGE(PG8_SA(0, 1), a2 + hstep, voffA);
;             PG8_WAIT_V(8); PG8_WAIT_L(0); PG8_BAR; PG8_MMA(0, 0, At, B0); PG8_MMA(0, 1, At, B1); PG8_BAR; PG8_SCHED;
	v_mfma_f32_16x16x32_bf16 v[44:47], v[178:181], v[194:197], v[44:47]
	v_mfma_f32_16x16x32_bf16 v[40:43], v[186:189], v[194:197], v[40:43]
	v_mfma_f32_16x16x32_bf16 v[28:31], v[178:181], v[202:205], v[28:31]
	v_mfma_f32_16x16x32_bf16 v[24:27], v[186:189], v[202:205], v[24:27]
	v_mfma_f32_16x16x32_bf16 v[12:15], v[178:181], v[210:213], v[12:15]
	v_mfma_f32_16x16x32_bf16 v[8:11], v[186:189], v[210:213], v[8:11]
	v_mfma_f32_16x16x32_bf16 v[4:7], v[178:181], v[218:221], v[4:7]
	v_mfma_f32_16x16x32_bf16 v[0:3], v[186:189], v[218:221], v[0:3]
	s_setprio 0
	s_add_i32 s59, 0, 0x18000
	s_add_i32 s60, 0, 0x1c000
	v_add_u32_e32 v170, s59, v153
	v_add_u32_e32 v186, s60, v153
	ds_read_b128 v[158:161], v170
	ds_read_b128 v[162:165], v170 offset:1024
	ds_read_b128 v[166:169], v170 offset:2048
	ds_read_b128 v[170:173], v170 offset:3072
	ds_read_b128 v[174:177], v186
	ds_read_b128 v[178:181], v186 offset:1024
	ds_read_b128 v[182:185], v186 offset:2048
	ds_read_b128 v[186:189], v186 offset:3072
	s_add_u32 s26, s26, 0x160000
	s_addc_u32 s27, s27, 0
	s_mov_b32 m0, s35
	v_lshl_add_u64 v[230:231], s[26:27], 0, v[130:131]
	ds_read_b128 v[190:193], v157 offset:32768
	ds_read_b128 v[194:197], v157 offset:33792
	ds_read_b128 v[198:201], v157 offset:34816
	ds_read_b128 v[202:205], v157 offset:35840
	ds_read_b128 v[206:209], v157 offset:36864
	ds_read_b128 v[210:213], v157 offset:37888
	ds_read_b128 v[214:217], v157 offset:38912
	ds_read_b128 v[218:221], v157 offset:39936
	global_load_lds_dwordx4 v[230:231], off
	v_lshl_add_u64 v[230:231], s[26:27], 0, v[134:135]
	s_mov_b32 m0, s36
	s_nop 0
	global_load_lds_dwordx4 v[230:231], off
	s_waitcnt vmcnt(8)
	s_waitcnt lgkmcnt(0)
	s_barrier
	s_setprio 1
	s_waitcnt lgkmcnt(0)
	v_mfma_f32_16x16x32_bf16 v[124:127], v[158:161], v[190:193], v[124:127]
	v_mfma_f32_16x16x32_bf16 v[120:123], v[166:169], v[190:193], v[120:123]
	v_mfma_f32_16x16x32_bf16 v[116:119], v[158:161], v[198:201], v[116:119]
	v_mfma_f32_16x16x32_bf16 v[112:115], v[166:169], v[198:201], v[112:115]
	v_mfma_f32_16x16x32_bf16 v[100:103], v[158:161], v[206:209], v[100:103]
	v_mfma_f32_16x16x32_bf16 v[96:99], v[166:169], v[206:209], v[96:99]
	v_mfma_f32_16x16x32_bf16 v[84:87], v[158:161], v[214:217], v[84:87]
	v_mfma_f32_16x16x32_bf16 v[80:83], v[166:169], v[214:217], v[80:83]
	v_mfma_f32_16x16x32_bf16 v[124:127], v[162:165], v[194:197], v[124:127]
	v_mfma_f32_16x16x32_bf16 v[120:123], v[170:173], v[194:197], v[120:123]
	v_mfma_f32_16x16x32_bf16 v[116:119], v[162:165], v[202:205], v[116:119]
	v_mfma_f32_16x16x32_bf16 v[112:115], v[170:173], v[202:205], v[112:115]
	v_mfma_f32_16x16x32_bf16 v[100:103], v[162:165], v[210:213], v[100:103]
	v_mfma_f32_16x16x32_bf16 v[96:99], v[170:173], v[210:213], v[96:99]
	v_mfma_f32_16x16x32_bf16 v[84:87], v[162:165], v[218:221], v[84:87]
	v_mfma_f32_16x16x32_bf16 v[80:83], v[170:173], v[218:221], v[80:83]
	s_setprio 0
	s_setprio 1
	v_mfma_f32_16x16x32_bf16 v[108:111], v[174:177], v[190:193], v[108:111]
	v_mfma_f32_16x16x32_bf16 v[104:107], v[182:185], v[190:193], v[104:107]
	v_mfma_f32_16x16x32_bf16 v[92:95], v[174:177], v[198:201], v[92:95]
	v_mfma_f32_16x16x32_bf16 v[88:91], v[182:185], v[198:201], v[88:91]
	v_mfma_f32_16x16x32_bf16 v[76:79], v[174:177], v[206:209], v[76:79]
	v_mfma_f32_16x16x32_bf16 v[72:75], v[182:185], v[206:209], v[72:75]
	v_mfma_f32_16x16x32_bf16 v[68:71], v[174:177], v[214:217], v[68:71]
	v_mfma_f32_16x16x32_bf16 v[64:67], v[182:185], v[214:217], v[64:67]
	s_setprio 2
	s_barrier
; #define PG8_STAGE(bufoff, gbase, voff) do { _Pragma("unroll") for (int _i = 0; _i < 2; ++_i) \
;         __builtin_amdgcn_global_load_lds((const unsigned*)((const char*)(gbase) + (voff)[_i]), (PG8_LAS unsigned*)(lds + (bufoff) + ldsw + _i * 8192), 16, 0, 0); } while (0)
; #define PG8_LDA(dst, b, h) do { _Pragma("unroll") for (int m = 0; m < 4; ++m) _Pragma("unroll") for (int k = 0; k < 2; ++k) dst[m][k] = *(const PG8_LAS bf16x8*)(lds + PG8_SA(b, h) + aoff + m * 2048 + k * 1024); } while (0)
; #define PG8_MMA(ai, bj, At, Bt) do { __builtin_amdgcn_s_setprio(1); _Pragma("unroll") for (int m = 0; m < 4; ++m) _Pragma("unroll") for (int n = 0; n < 2; ++n) _Pragma("unroll") for (int k = 0; k < 2; ++k) \
;         acc[ai][bj][m][n] = __builtin_amdgcn_mfma_f32_16x16x32_bf16(Bt[n][k], At[m][k], acc[ai][bj][m][n], 0, 0, 0); __builtin_amdgcn_s_setprio(0); } while (0)
; #define PG8_WAIT_V(n) asm volatile("s_waitcnt vmcnt(" #n ")" ::: "memory")
; #define PG8_WAIT_L(n) asm volatile("s_waitcnt lgkmcnt(" #n ")" ::: "memory")
; #define PG8_BAR __builtin_amdgcn_s_barrier()
; #define PG8_SCHED __builtin_amdgcn_sched_barrier(0)
; template <class Epi, class Sched, bool ALIGN_EPI = false, bool SP2 = false>
; __device__ __forceinline__ void gemm_phase(PG8_LAS unsigned char* lds, const Gemm g, const Sched& S, const Epi& E) {
;     ...
;         for (int t = 0; t < nt; t += 2) {
;     ...
;             PG8_WAIT_V(8); PG8_WAIT_L(0); PG8_BAR; PG8_MMA(0, 0, At, B0); PG8_MMA(0, 1, At, B1); PG8_BAR; PG8_SCHED;
;             PG8_LDA(At, 1, 1); PG8_STAGE(PG8_SB(1, 0), b3, voffB); PG8_STAGE(PG8_SB(1, 1), b3 + hstep, voffB); PG8_STAGE(PG8_SA(1, 0), a3, voffA);
;             PG8_WAIT_V(8); PG8_WAIT_L(0); PG8_BAR; PG8_MMA(1, 0, At, B0); PG8_MMA(1, 1, At, B1); PG8_BAR; PG8_SCHED;
	v_mfma_f32_16x16x32_bf16 v[108:111], v[178:181], v[194:197], v[108:111]
	v_mfma_f32_16x16x32_bf16 v[104:107], v[186:189], v[194:197], v[104:107]
	v_mfma_f32_16x16x32_bf16 v[92:95], v[178:181], v[202:205], v[92:95]
	v_mfma_f32_16x16x32_bf16 v[88:91], v[186:189], v[202:205], v[88:91]
	v_mfma_f32_16x16x32_bf16 v[76:79], v[178:181], v[210:213], v[76:79]
	v_mfma_f32_16x16x32_bf16 v[72:75], v[186:189], v[210:213], v[72:75]
	v_mfma_f32_16x16x32_bf16 v[68:71], v[178:181], v[218:221], v[68:71]
	v_mfma_f32_16x16x32_bf16 v[64:67], v[186:189], v[218:221], v[64:67]
	s_setprio 0
	s_add_i32 s26, s59, s28
	v_lshl_add_u64 v[222:223], v[222:223], 0, s[4:5]
	s_mov_b32 m0, s26
	ds_read_b128 v[190:193], v157 offset:49152
	ds_read_b128 v[194:197], v157 offset:50176
	ds_read_b128 v[198:201], v157 offset:51200
	ds_read_b128 v[202:205], v157 offset:52224
	ds_read_b128 v[206:209], v157 offset:53248
	ds_read_b128 v[210:213], v157 offset:54272
	ds_read_b128 v[214:217], v157 offset:55296
	ds_read_b128 v[218:221], v157 offset:56320
	global_load_lds_dwordx4 v[222:223], off
	s_add_i32 m0, s26, 0x2000
	s_add_u32 s24, s24, 0x160080
	v_lshl_add_u64 v[222:223], v[224:225], 0, s[4:5]
	s_addc_u32 s25, s25, 0
	s_add_i32 s26, s60, s28
	global_load_lds_dwordx4 v[222:223], off
	v_lshl_add_u64 v[222:223], s[24:25], 0, v[132:133]
	s_mov_b32 m0, s26
	s_nop 0
	global_load_lds_dwordx4 v[222:223], off
	v_lshl_add_u64 v[222:223], s[24:25], 0, v[136:137]
	s_add_i32 m0, s26, 0x2000
	s_nop 0
	global_load_lds_dwordx4 v[222:223], off
	v_lshl_add_u64 v[222:223], v[226:227], 0, s[4:5]
	s_mov_b32 m0, s38
	s_nop 0
	global_load_lds_dwordx4 v[222:223], off
	v_lshl_add_u64 v[222:223], v[228:229], 0, s[4:5]
	s_mov_b32 m0, s39
	s_nop 0
	global_load_lds_dwordx4 v[222:223], off
	s_waitcnt vmcnt(8)
	s_waitcnt lgkmcnt(0)
	s_barrier
	s_setprio 1
	s_waitcnt lgkmcnt(0)
	v_mfma_f32_16x16x32_bf16 v[60:63], v[158:161], v[190:193], v[60:63]
	v_mfma_f32_16x16x32_bf16 v[56:59], v[166:169], v[190:193], v[56:59]
	v_mfma_f32_16x16x32_bf16 v[52:55], v[158:161], v[198:201], v[52:55]
	v_mfma_f32_16x16x32_bf16 v[48:51], v[166:169], v[198:201], v[48:51]
	v_mfma_f32_16x16x32_bf16 v[36:39], v[158:161], v[206:209], v[36:39]
	v_mfma_f32_16x16x32_bf16 v[32:35], v[166:169], v[206:209], v[32:35]
	v_mfma_f32_16x16x32_bf16 v[20:23], v[158:161], v[214:217], v[20:23]
	v_mfma_f32_16x16x32_bf16 v[16:19], v[166:169], v[214:217], v[16:19]
	v_mfma_f32_16x16x32_bf16 v[60:63], v[162:165], v[194:197], v[60:63]
	v_mfma_f32_16x16x32_bf16 v[56:59], v[170:173], v[194:197], v[56:59]
	v_mfma_f32_16x16x32_bf16 v[52:55], v[162:165], v[202:205], v[52:55]
	v_mfma_f32_16x16x32_bf16 v[48:51], v[170:173], v[202:205], v[48:51]
	v_mfma_f32_16x16x32_bf16 v[36:39], v[162:165], v[210:213], v[36:39]
	v_mfma_f32_16x16x32_bf16 v[32:35], v[170:173], v[210:213], v[32:35]
	v_mfma_f32_16x16x32_bf16 v[20:23], v[162:165], v[218:221], v[20:23]
	v_mfma_f32_16x16x32_bf16 v[16:19], v[170:173], v[218:221], v[16:19]
	s_setprio 0
	s_setprio 1
	v_mfma_f32_16x16x32_bf16 v[44:47], v[174:177], v[190:193], v[44:47]
	v_mfma_f32_16x16x32_bf16 v[40:43], v[182:185], v[190:193], v[40:43]
	v_mfma_f32_16x16x32_bf16 v[28:31], v[174:177], v[198:201], v[28:31]
	v_mfma_f32_16x16x32_bf16 v[24:27], v[182:185], v[198:201], v[24:27]
	v_mfma_f32_16x16x32_bf16 v[12:15], v[174:177], v[206:209], v[12:15]
	v_mfma_f32_16x16x32_bf16 v[8:11], v[182:185], v[206:209], v[8:11]
	v_mfma_f32_16x16x32_bf16 v[4:7], v[174:177], v[214:217], v[4:7]
	v_mfma_f32_16x16x32_bf16 v[0:3], v[182:185], v[214:217], v[0:3]
	s_setprio 2
	s_barrier
	v_mfma_f32_16x16x32_bf16 v[44:47], v[178:181], v[194:197], v[44:47]
	v_mfma_f32_16x16x32_bf16 v[40:43], v[186:189], v[194:197], v[40:43]
	v_mfma_f32_16x16x32_bf16 v[28:31], v[178:181], v[202:205], v[28:31]
	v_mfma_f32_16x16x32_bf16 v[24:27], v[186:189], v[202:205], v[24:27]
	v_mfma_f32_16x16x32_bf16 v[12:15], v[178:181], v[210:213], v[12:15]
	v_mfma_f32_16x16x32_bf16 v[8:11], v[186:189], v[210:213], v[8:11]
	v_mfma_f32_16x16x32_bf16 v[4:7], v[178:181], v[218:221], v[4:7]
	v_mfma_f32_16x16x32_bf16 v[0:3], v[186:189], v[218:221], v[0:3]
	s_setprio 0
	s_add_i32 s58, s58, 2
	s_add_u32 s22, s22, 0x100
	s_addc_u32 s23, s23, 0
	s_add_u32 s56, s56, 0x100
	s_addc_u32 s57, s57, 0
	s_cmpk_gt_u32 s58, 0x55
	s_cbranch_scc0 .LBB0_140
	s_and_b64 vcc, exec, s[8:9]
	s_cbranch_vccz .LBB0_143
	s_barrier

; #define PG8_STAGE(bufoff, gbase, voff) do { _Pragma("unroll") for (int _i = 0; _i < 2; ++_i) \
;         __builtin_amdgcn_global_load_lds((const unsigned*)((const char*)(gbase) + (voff)[_i]), (PG8_LAS unsigned*)(lds + (bufoff) + ldsw + _i * 8192), 16, 0, 0); } while (0)
; #define PG8_LDA(dst, b, h) do { _Pragma("unroll") for (int m = 0; m < 4; ++m) _Pragma("unroll") for (int k = 0; k < 2; ++k) dst[m][k] = *(const PG8_LAS bf16x8*)(lds + PG8_SA(b, h) + aoff + m * 2048 + k * 1024); } while (0)
; #define PG8_LDB(dst, b, h) do { _Pragma("unroll") for (int n = 0; n < 2; ++n) _Pragma("unroll") for (int k = 0; k < 2; ++k) dst[n][k] = *(const PG8_LAS bf16x8*)(lds + PG8_SB(b, h) + boff + n * 2048 + k * 1024); } while (0)
; template <class Epi, class Sched, bool ALIGN_EPI = false, bool SP2 = false>
; __device__ __forceinline__ void gemm_phase(PG8_LAS unsigned char* lds, const Gemm g, const Sched& S, const Epi& E) {
;     ...
;         for (int t = 0; t < nt; t += 2) {
;             const bool last = (t == nt - 2);
;             const char* a1 = cA + (size_t)(t + 1) * kstep;
;             const char* a2 = last ? nA : cA + (size_t)(t + 2) * kstep; const char* b2 = last ? nB : cB + (size_t)(t + 2) * kstep;
;             const char* a3 = a2 + kstep; const char* b3 = b2 + kstep;
;             if (last && has_next) S.a_ready(nxt);
;             if constexpr (SP2) {
;             PG8_LDB(B0, 0, 0); PG8_LDB(B1, 0, 1); PG8_SCHED; PG8_LDA(At, 0, 0); PG8_STAGE(PG8_SA(1, 1), a1 + hstep, voffA);
;             PG8_WAIT_V(8); PG8_WAIT_L(0); PG8_BAR; PG8_MMA(0, 0, At, B0); PG8_MMA(0, 1, At, B1); PG8_BAR; PG8_SCHED;
;             PG8_LDA(At, 0, 1); PG8_STAGE(PG8_SB(0, 0), b2, voffB); PG8_STAGE(PG8_SB(0, 1), b2 + hstep, voffB); PG8_STAGE(PG8_SA(0, 0), a2, voffA);
;             PG8_WAIT_V(8); PG8_WAIT_L(0); PG8_BAR; PG8_MMA(1, 0, At, B0); PG8_MMA(1, 1, At, B1); PG8_BAR; PG8_SCHED;
;             PG8_LDB(B0, 1, 0); PG8_LDB(B1, 1, 1); PG8_SCHED; PG8_LDA(At, 1, 0); PG8_STAGE(PG8_SA(0, 1), a2 + hstep, voffA);
;             PG8_WAIT_V(8); PG8_WAIT_L(0); PG8_BAR; PG8_MMA(0, 0, At, B0); PG8_MMA(0, 1, At, B1); PG8_BAR; PG8_SCHED;
;             PG8_LDA(At, 1, 1); PG8_STAGE(PG8_SB(1, 0), b3, voffB); PG8_STAGE(PG8_SB(1, 1), b3 + hstep, voffB); PG8_STAGE(PG8_SA(1, 0), a3, voffA);
;             PG8_WAIT_V(8); PG8_WAIT_L(0); PG8_BAR; PG8_MMA(1, 0, At, B0); PG8_MMA(1, 1, At, B1); PG8_BAR; PG8_SCHED;
.LBB0_165:
	ds_read_b128 v[150:153], v139
	ds_read_b128 v[154:157], v139 offset:1024
	ds_read_b128 v[158:161], v139 offset:2048
	ds_read_b128 v[162:165], v139 offset:3072
	ds_read_b128 v[166:169], v145
	ds_read_b128 v[170:173], v145 offset:1024
	ds_read_b128 v[174:177], v145 offset:2048
	ds_read_b128 v[178:181], v145 offset:3072
	s_add_u32 s12, s8, s10
	s_addc_u32 s13, s9, s11
	s_add_u32 s12, s12, 0x13500100
	s_addc_u32 s13, s13, 0
	s_add_u32 s39, s24, s10
	s_addc_u32 s40, s25, s11
	s_cmpk_eq_i32 s10, 0x1500
	s_cselect_b32 s15, s5, s13
	s_cselect_b32 s14, s4, s12
	s_cselect_b32 s13, s3, s40
	s_cselect_b32 s12, s2, s39
	s_mov_b32 m0, s27
	v_lshl_add_u64 v[214:215], v[140:141], 0, s[10:11]
	ds_read_b128 v[182:185], v146
	ds_read_b128 v[186:189], v146 offset:1024
	ds_read_b128 v[190:193], v146 offset:2048
	ds_read_b128 v[194:197], v146 offset:3072
	ds_read_b128 v[198:201], v146 offset:4096
	ds_read_b128 v[202:205], v146 offset:5120
	ds_read_b128 v[206:209], v146 offset:6144
	ds_read_b128 v[210:213], v146 offset:7168
	global_load_lds_dwordx4 v[214:215], off
	v_lshl_add_u64 v[214:215], v[142:143], 0, s[10:11]
	s_mov_b32 m0, s28
	s_nop 0
	global_load_lds_dwordx4 v[214:215], off
	s_waitcnt vmcnt(8)
	s_waitcnt lgkmcnt(0)
	s_barrier
	s_setprio 1
	s_waitcnt lgkmcnt(0)
	v_mfma_f32_16x16x32_bf16 v[124:127], v[150:153], v[182:185], v[124:127]
	v_mfma_f32_16x16x32_bf16 v[120:123], v[158:161], v[182:185], v[120:123]
	v_mfma_f32_16x16x32_bf16 v[116:119], v[150:153], v[190:193], v[116:119]
	v_mfma_f32_16x16x32_bf16 v[112:115], v[158:161], v[190:193], v[112:115]
	v_mfma_f32_16x16x32_bf16 v[108:111], v[150:153], v[198:201], v[108:111]
	v_mfma_f32_16x16x32_bf16 v[104:107], v[158:161], v[198:201], v[104:107]
	v_mfma_f32_16x16x32_bf16 v[96:99], v[150:153], v[206:209], v[96:99]
	v_mfma_f32_16x16x32_bf16 v[88:91], v[158:161], v[206:209], v[88:91]
	v_mfma_f32_16x16x32_bf16 v[124:127], v[154:157], v[186:189], v[124:127]
	v_mfma_f32_16x16x32_bf16 v[120:123], v[162:165], v[186:189], v[120:123]
	v_mfma_f32_16x16x32_bf16 v[116:119], v[154:157], v[194:197], v[116:119]
	v_mfma_f32_16x16x32_bf16 v[112:115], v[162:165], v[194:197], v[112:115]
	v_mfma_f32_16x16x32_bf16 v[108:111], v[154:157], v[202:205], v[108:111]
	v_mfma_f32_16x16x32_bf16 v[104:107], v[162:165], v[202:205], v[104:107]
	v_mfma_f32_16x16x32_bf16 v[96:99], v[154:157], v[210:213], v[96:99]
	v_mfma_f32_16x16x32_bf16 v[88:91], v[162:165], v[210:213], v[88:91]
	s_setprio 0
	s_setprio 1
	v_mfma_f32_16x16x32_bf16 v[100:103], v[166:169], v[182:185], v[100:103]
	v_mfma_f32_16x16x32_bf16 v[92:95], v[174:177], v[182:185], v[92:95]
	v_mfma_f32_16x16x32_bf16 v[84:87], v[166:169], v[190:193], v[84:87]
	v_mfma_f32_16x16x32_bf16 v[80:83], v[174:177], v[190:193], v[80:83]
	v_mfma_f32_16x16x32_bf16 v[76:79], v[166:169], v[198:201], v[76:79]
	v_mfma_f32_16x16x32_bf16 v[72:75], v[174:177], v[198:201], v[72:75]
	v_mfma_f32_16x16x32_bf16 v[68:71], v[166:169], v[206:209], v[68:71]
	v_mfma_f32_16x16x32_bf16 v[64:67], v[174:177], v[206:209], v[64:67]
	s_setprio 2
	s_barrier
	v_mfma_f32_16x16x32_bf16 v[100:103], v[170:173], v[186:189], v[100:103]
	v_mfma_f32_16x16x32_bf16 v[92:95], v[178:181], v[186:189], v[92:95]
	v_mfma_f32_16x16x32_bf16 v[84:87], v[170:173], v[194:197], v[84:87]
	v_mfma_f32_16x16x32_bf16 v[80:83], v[178:181], v[194:197], v[80:83]
	v_mfma_f32_16x16x32_bf16 v[76:79], v[170:173], v[202:205], v[76:79]
	v_mfma_f32_16x16x32_bf16 v[72:75], v[178:181], v[202:205], v[72:75]
	v_mfma_f32_16x16x32_bf16 v[68:71], v[170:173], v[210:213], v[68:71]
	v_mfma_f32_16x16x32_bf16 v[64:67], v[178:181], v[210:213], v[64:67]
	s_setprio 0
	s_mov_b32 m0, s29
	v_lshl_add_u64 v[214:215], s[12:13], 0, v[132:133]
	s_add_u32 s40, s12, 0x160000
	ds_read_b128 v[182:185], v146 offset:16384
	ds_read_b128 v[186:189], v146 offset:17408
	ds_read_b128 v[190:193], v146 offset:18432
	ds_read_b128 v[194:197], v146 offset:19456
	ds_read_b128 v[198:201], v146 offset:20480
	ds_read_b128 v[202:205], v146 offset:21504
	ds_read_b128 v[206:209], v146 offset:22528
	ds_read_b128 v[210:213], v146 offset:23552
	global_load_lds_dwordx4 v[214:215], off
	v_lshl_add_u64 v[216:217], s[12:13], 0, v[136:137]
	s_mov_b32 m0, s30
	s_addc_u32 s41, s13, 0
	global_load_lds_dwordx4 v[216:217], off
	v_lshl_add_u64 v[218:219], s[40:41], 0, v[132:133]
	s_mov_b32 m0, s31
	v_lshl_add_u64 v[220:221], s[14:15], 0, v[134:135]
	global_load_lds_dwordx4 v[218:219], off
	v_lshl_add_u64 v[218:219], s[40:41], 0, v[136:137]
	s_mov_b32 m0, s34
	s_nop 0
	global_load_lds_dwordx4 v[218:219], off
	v_lshl_add_u64 v[218:219], s[14:15], 0, v[130:131]
	s_mov_b32 m0, s17
	s_nop 0
	global_load_lds_dwordx4 v[218:219], off
	s_mov_b32 m0, s18
	s_nop 0
	global_load_lds_dwordx4 v[220:221], off
	s_waitcnt vmcnt(8)
	s_waitcnt lgkmcnt(0)
	s_barrier
	s_setprio 1
	s_waitcnt lgkmcnt(0)
	v_mfma_f32_16x16x32_bf16 v[60:63], v[150:153], v[182:185], v[60:63]
	v_mfma_f32_16x16x32_bf16 v[56:59], v[158:161], v[182:185], v[56:59]
	v_mfma_f32_16x16x32_bf16 v[52:55], v[150:153], v[190:193], v[52:55]
	v_mfma_f32_16x16x32_bf16 v[48:51], v[158:161], v[190:193], v[48:51]
	v_mfma_f32_16x16x32_bf16 v[44:47], v[150:153], v[198:201], v[44:47]
	v_mfma_f32_16x16x32_bf16 v[40:43], v[158:161], v[198:201], v[40:43]
	v_mfma_f32_16x16x32_bf16 v[32:35], v[150:153], v[206:209], v[32:35]
	v_mfma_f32_16x16x32_bf16 v[24:27], v[158:161], v[206:209], v[24:27]
	v_mfma_f32_16x16x32_bf16 v[60:63], v[154:157], v[186:189], v[60:63]
	v_mfma_f32_16x16x32_bf16 v[56:59], v[162:165], v[186:189], v[56:59]
	v_mfma_f32_16x16x32_bf16 v[52:55], v[154:157], v[194:197], v[52:55]
	v_mfma_f32_16x16x32_bf16 v[48:51], v[162:165], v[194:197], v[48:51]
	v_mfma_f32_16x16x32_bf16 v[44:47], v[154:157], v[202:205], v[44:47]
	v_mfma_f32_16x16x32_bf16 v[40:43], v[162:165], v[202:205], v[40:43]
	v_mfma_f32_16x16x32_bf16 v[32:35], v[154:157], v[210:213], v[32:35]
	v_mfma_f32_16x16x32_bf16 v[24:27], v[162:165], v[210:213], v[24:27]
	s_setprio 0
	s_setprio 1
	v_mfma_f32_16x16x32_bf16 v[36:39], v[166:169], v[182:185], v[36:39]
	v_mfma_f32_16x16x32_bf16 v[28:31], v[174:177], v[182:185], v[28:31]
	v_mfma_f32_16x16x32_bf16 v[20:23], v[166:169], v[190:193], v[20:23]
	v_mfma_f32_16x16x32_bf16 v[16:19], v[174:177], v[190:193], v[16:19]
	v_mfma_f32_16x16x32_bf16 v[12:15], v[166:169], v[198:201], v[12:15]
	v_mfma_f32_16x16x32_bf16 v[8:11], v[174:177], v[198:201], v[8:11]
	v_mfma_f32_16x16x32_bf16 v[4:7], v[166:169], v[206:209], v[4:7]
	v_mfma_f32_16x16x32_bf16 v[0:3], v[174:177], v[206:209], v[0:3]
	s_setprio 2
	s_barrier
; #define PG8_STAGE(bufoff, gbase, voff) do { _Pragma("unroll") for (int _i = 0; _i < 2; ++_i) \
;         __builtin_amdgcn_global_load_lds((const unsigned*)((const char*)(gbase) + (voff)[_i]), (PG8_LAS unsigned*)(lds + (bufoff) + ldsw + _i * 8192), 16, 0, 0); } while (0)
; #define PG8_LDA(dst, b, h) do { _Pragma("unroll") for (int m = 0; m < 4; ++m) _Pragma("unroll") for (int k = 0; k < 2; ++k) dst[m][k] = *(const PG8_LAS bf16x8*)(lds + PG8_SA(b, h) + aoff + m * 2048 + k * 1024); } while (0)
; #define PG8_LDB(dst, b, h) do { _Pragma("unroll") for (int n = 0; n < 2; ++n) _Pragma("unroll") for (int k = 0; k < 2; ++k) dst[n][k] = *(const PG8_LAS bf16x8*)(lds + PG8_SB(b, h) + boff + n * 2048 + k * 1024); } while (0)
; #define PG8_BAR __builtin_amdgcn_s_barrier()
; template <class Epi, class Sched, bool ALIGN_EPI = false, bool SP2 = false>
; __device__ __forceinline__ void gemm_phase(PG8_LAS unsigned char* lds, const Gemm g, const Sched& S, const Epi& E) {
;     ...
;             const bool last = (t == nt - 2);
;             const char* a1 = cA + (size_t)(t + 1) * kstep;
;             const char* a2 = last ? nA : cA + (size_t)(t + 2) * kstep; const char* b2 = last ? nB : cB + (size_t)(t + 2) * kstep;
;             const char* a3 = a2 + kstep; const char* b3 = b2 + kstep;
;             if (last && has_next) S.a_ready(nxt);
;             if constexpr (SP2) {
;             PG8_LDB(B0, 0, 0); PG8_LDB(B1, 0, 1); PG8_SCHED; PG8_LDA(At, 0, 0); PG8_STAGE(PG8_SA(1, 1), a1 + hstep, voffA);
;             PG8_WAIT_V(8); PG8_WAIT_L(0); PG8_BAR; PG8_MMA(0, 0, At, B0); PG8_MMA(0, 1, At, B1); PG8_BAR; PG8_SCHED;
;             PG8_LDA(At, 0, 1); PG8_STAGE(PG8_SB(0, 0), b2, voffB); PG8_STAGE(PG8_SB(0, 1), b2 + hstep, voffB); PG8_STAGE(PG8_SA(0, 0), a2, voffA);
;             PG8_WAIT_V(8); PG8_WAIT_L(0); PG8_BAR; PG8_MMA(1, 0, At, B0); PG8_MMA(1, 1, At, B1); PG8_BAR; PG8_SCHED;
;             PG8_LDB(B0, 1, 0); PG8_LDB(B1, 1, 1); PG8_SCHED; PG8_LDA(At, 1, 0); PG8_STAGE(PG8_SA(0, 1), a2 + hstep, voffA);
;             PG8_WAIT_V(8); PG8_WAIT_L(0); PG8_BAR; PG8_MMA(0, 0, At, B0); PG8_MMA(0, 1, At, B1); PG8_BAR; PG8_SCHED;
;             PG8_LDA(At, 1, 1); PG8_STAGE(PG8_SB(1, 0), b3, voffB); PG8_STAGE(PG8_SB(1, 1), b3 + hstep, voffB); PG8_STAGE(PG8_SA(1, 0), a3, voffA);
;             PG8_WAIT_V(8); PG8_WAIT_L(0); PG8_BAR; PG8_MMA(1, 0, At, B0); PG8_MMA(1, 1, At, B1); PG8_BAR; PG8_SCHED;
	v_mfma_f32_16x16x32_bf16 v[36:39], v[170:173], v[186:189], v[36:39]
	v_mfma_f32_16x16x32_bf16 v[28:31], v[178:181], v[186:189], v[28:31]
	v_mfma_f32_16x16x32_bf16 v[20:23], v[170:173], v[194:197], v[20:23]
	v_mfma_f32_16x16x32_bf16 v[16:19], v[178:181], v[194:197], v[16:19]
	v_mfma_f32_16x16x32_bf16 v[12:15], v[170:173], v[202:205], v[12:15]
	v_mfma_f32_16x16x32_bf16 v[8:11], v[178:181], v[202:205], v[8:11]
	v_mfma_f32_16x16x32_bf16 v[4:7], v[170:173], v[210:213], v[4:7]
	v_mfma_f32_16x16x32_bf16 v[0:3], v[178:181], v[210:213], v[0:3]
	s_setprio 0
	ds_read_b128 v[150:153], v147
	ds_read_b128 v[154:157], v147 offset:1024
	ds_read_b128 v[158:161], v147 offset:2048
	ds_read_b128 v[162:165], v147 offset:3072
	ds_read_b128 v[166:169], v148
	ds_read_b128 v[170:173], v148 offset:1024
	ds_read_b128 v[174:177], v148 offset:2048
	ds_read_b128 v[178:181], v148 offset:3072
	s_add_u32 s14, s14, 0x160000
	s_addc_u32 s15, s15, 0
	s_mov_b32 m0, s19
	v_lshl_add_u64 v[222:223], s[14:15], 0, v[130:131]
	ds_read_b128 v[182:185], v146 offset:32768
	ds_read_b128 v[186:189], v146 offset:33792
	ds_read_b128 v[190:193], v146 offset:34816
	ds_read_b128 v[194:197], v146 offset:35840
	ds_read_b128 v[198:201], v146 offset:36864
	ds_read_b128 v[202:205], v146 offset:37888
	ds_read_b128 v[206:209], v146 offset:38912
	ds_read_b128 v[210:213], v146 offset:39936
	global_load_lds_dwordx4 v[222:223], off
	v_lshl_add_u64 v[222:223], s[14:15], 0, v[134:135]
	s_mov_b32 m0, s20
	s_nop 0
	global_load_lds_dwordx4 v[222:223], off
	s_waitcnt vmcnt(8)
	s_waitcnt lgkmcnt(0)
	s_barrier
	s_setprio 1
	s_waitcnt lgkmcnt(0)
	v_mfma_f32_16x16x32_bf16 v[124:127], v[150:153], v[182:185], v[124:127]
	v_mfma_f32_16x16x32_bf16 v[120:123], v[158:161], v[182:185], v[120:123]
	v_mfma_f32_16x16x32_bf16 v[116:119], v[150:153], v[190:193], v[116:119]
	v_mfma_f32_16x16x32_bf16 v[112:115], v[158:161], v[190:193], v[112:115]
	v_mfma_f32_16x16x32_bf16 v[108:111], v[150:153], v[198:201], v[108:111]
	v_mfma_f32_16x16x32_bf16 v[104:107], v[158:161], v[198:201], v[104:107]
	v_mfma_f32_16x16x32_bf16 v[96:99], v[150:153], v[206:209], v[96:99]
	v_mfma_f32_16x16x32_bf16 v[88:91], v[158:161], v[206:209], v[88:91]
	v_mfma_f32_16x16x32_bf16 v[124:127], v[154:157], v[186:189], v[124:127]
	v_mfma_f32_16x16x32_bf16 v[120:123], v[162:165], v[186:189], v[120:123]
	v_mfma_f32_16x16x32_bf16 v[116:119], v[154:157], v[194:197], v[116:119]
	v_mfma_f32_16x16x32_bf16 v[112:115], v[162:165], v[194:197], v[112:115]
	v_mfma_f32_16x16x32_bf16 v[108:111], v[154:157], v[202:205], v[108:111]
	v_mfma_f32_16x16x32_bf16 v[104:107], v[162:165], v[202:205], v[104:107]
	v_mfma_f32_16x16x32_bf16 v[96:99], v[154:157], v[210:213], v[96:99]
	v_mfma_f32_16x16x32_bf16 v[88:91], v[162:165], v[210:213], v[88:91]
	s_setprio 0
	s_setprio 1
	v_mfma_f32_16x16x32_bf16 v[100:103], v[166:169], v[182:185], v[100:103]
	v_mfma_f32_16x16x32_bf16 v[92:95], v[174:177], v[182:185], v[92:95]
	v_mfma_f32_16x16x32_bf16 v[84:87], v[166:169], v[190:193], v[84:87]
	v_mfma_f32_16x16x32_bf16 v[80:83], v[174:177], v[190:193], v[80:83]
	v_mfma_f32_16x16x32_bf16 v[76:79], v[166:169], v[198:201], v[76:79]
	v_mfma_f32_16x16x32_bf16 v[72:75], v[174:177], v[198:201], v[72:75]
	v_mfma_f32_16x16x32_bf16 v[68:71], v[166:169], v[206:209], v[68:71]
	v_mfma_f32_16x16x32_bf16 v[64:67], v[174:177], v[206:209], v[64:67]
	s_setprio 2
	s_barrier
; #define PG8_STAGE(bufoff, gbase, voff) do { _Pragma("unroll") for (int _i = 0; _i < 2; ++_i) \
;         __builtin_amdgcn_global_load_lds((const unsigned*)((const char*)(gbase) + (voff)[_i]), (PG8_LAS unsigned*)(lds + (bufoff) + ldsw + _i * 8192), 16, 0, 0); } while (0)
; #define PG8_LDA(dst, b, h) do { _Pragma("unroll") for (int m = 0; m < 4; ++m) _Pragma("unroll") for (int k = 0; k < 2; ++k) dst[m][k] = *(const PG8_LAS bf16x8*)(lds + PG8_SA(b, h) + aoff + m * 2048 + k * 1024); } while (0)
; #define PG8_WAIT_V(n) asm volatile("s_waitcnt vmcnt(" #n ")" ::: "memory")
; #define PG8_WAIT_L(n) asm volatile("s_waitcnt lgkmcnt(" #n ")" ::: "memory")
; template <class Epi, class Sched, bool ALIGN_EPI = false, bool SP2 = false>
; __device__ __forceinline__ void gemm_phase(PG8_LAS unsigned char* lds, const Gemm g, const Sched& S, const Epi& E) {
;     ...
;         for (int t = 0; t < nt; t += 2) {
;             const bool last = (t == nt - 2);
;             const char* a1 = cA + (size_t)(t + 1) * kstep;
;             const char* a2 = last ? nA : cA + (size_t)(t + 2) * kstep; const char* b2 = last ? nB : cB + (size_t)(t + 2) * kstep;
;             const char* a3 = a2 + kstep; const char* b3 = b2 + kstep;
;             if (last && has_next) S.a_ready(nxt);
;             if constexpr (SP2) {
;             PG8_LDB(B0, 0, 0); PG8_LDB(B1, 0, 1); PG8_SCHED; PG8_LDA(At, 0, 0); PG8_STAGE(PG8_SA(1, 1), a1 + hstep, voffA);
;             PG8_WAIT_V(8); PG8_WAIT_L(0); PG8_BAR; PG8_MMA(0, 0, At, B0); PG8_MMA(0, 1, At, B1); PG8_BAR; PG8_SCHED;
;             PG8_LDA(At, 0, 1); PG8_STAGE(PG8_SB(0, 0), b2, voffB); PG8_STAGE(PG8_SB(0, 1), b2 + hstep, voffB); PG8_STAGE(PG8_SA(0, 0), a2, voffA);
;             PG8_WAIT_V(8); PG8_WAIT_L(0); PG8_BAR; PG8_MMA(1, 0, At, B0); PG8_MMA(1, 1, At, B1); PG8_BAR; PG8_SCHED;
;             PG8_LDB(B0, 1, 0); PG8_LDB(B1, 1, 1); PG8_SCHED; PG8_LDA(At, 1, 0); PG8_STAGE(PG8_SA(0, 1), a2 + hstep, voffA);
;             PG8_WAIT_V(8); PG8_WAIT_L(0); PG8_BAR; PG8_MMA(0, 0, At, B0); PG8_MMA(0, 1, At, B1); PG8_BAR; PG8_SCHED;
;             PG8_LDA(At, 1, 1); PG8_STAGE(PG8_SB(1, 0), b3, voffB); PG8_STAGE(PG8_SB(1, 1), b3 + hstep, voffB); PG8_STAGE(PG8_SA(1, 0), a3, voffA);
;             PG8_WAIT_V(8); PG8_WAIT_L(0); PG8_BAR; PG8_MMA(1, 0, At, B0); PG8_MMA(1, 1, At, B1); PG8_BAR; PG8_SCHED;
;     ...
;         if constexpr (ALIGN_EPI) { if (wr == 0) PG8_BAR; }
	v_mfma_f32_16x16x32_bf16 v[100:103], v[170:173], v[186:189], v[100:103]
	v_mfma_f32_16x16x32_bf16 v[92:95], v[178:181], v[186:189], v[92:95]
	v_mfma_f32_16x16x32_bf16 v[84:87], v[170:173], v[194:197], v[84:87]
	v_mfma_f32_16x16x32_bf16 v[80:83], v[178:181], v[194:197], v[80:83]
	v_mfma_f32_16x16x32_bf16 v[76:79], v[170:173], v[202:205], v[76:79]
	v_mfma_f32_16x16x32_bf16 v[72:75], v[178:181], v[202:205], v[72:75]
	v_mfma_f32_16x16x32_bf16 v[68:71], v[170:173], v[210:213], v[68:71]
	v_mfma_f32_16x16x32_bf16 v[64:67], v[178:181], v[210:213], v[64:67]
	s_setprio 0
	s_mov_b32 m0, s35
	v_lshl_add_u64 v[214:215], v[214:215], 0, s[6:7]
	s_add_u32 s12, s12, 0x160080
	ds_read_b128 v[182:185], v146 offset:49152
	ds_read_b128 v[186:189], v146 offset:50176
	ds_read_b128 v[190:193], v146 offset:51200
	ds_read_b128 v[194:197], v146 offset:52224
	ds_read_b128 v[198:201], v146 offset:53248
	ds_read_b128 v[202:205], v146 offset:54272
	ds_read_b128 v[206:209], v146 offset:55296
	ds_read_b128 v[210:213], v146 offset:56320
	global_load_lds_dwordx4 v[214:215], off
	v_lshl_add_u64 v[214:215], v[216:217], 0, s[6:7]
	s_mov_b32 m0, s36
	s_addc_u32 s13, s13, 0
	global_load_lds_dwordx4 v[214:215], off
	v_lshl_add_u64 v[214:215], s[12:13], 0, v[132:133]
	s_mov_b32 m0, s37
	s_nop 0
	global_load_lds_dwordx4 v[214:215], off
	v_lshl_add_u64 v[214:215], s[12:13], 0, v[136:137]
	s_mov_b32 m0, s38
	s_nop 0
	global_load_lds_dwordx4 v[214:215], off
	v_lshl_add_u64 v[214:215], v[218:219], 0, s[6:7]
	s_mov_b32 m0, s22
	s_nop 0
	global_load_lds_dwordx4 v[214:215], off
	v_lshl_add_u64 v[214:215], v[220:221], 0, s[6:7]
	s_mov_b32 m0, s23
	s_nop 0
	global_load_lds_dwordx4 v[214:215], off
	s_waitcnt vmcnt(8)
	s_waitcnt lgkmcnt(0)
	s_barrier
	s_setprio 1
	s_waitcnt lgkmcnt(0)
	v_mfma_f32_16x16x32_bf16 v[60:63], v[150:153], v[182:185], v[60:63]
	v_mfma_f32_16x16x32_bf16 v[56:59], v[158:161], v[182:185], v[56:59]
	v_mfma_f32_16x16x32_bf16 v[52:55], v[150:153], v[190:193], v[52:55]
	v_mfma_f32_16x16x32_bf16 v[48:51], v[158:161], v[190:193], v[48:51]
	v_mfma_f32_16x16x32_bf16 v[44:47], v[150:153], v[198:201], v[44:47]
	v_mfma_f32_16x16x32_bf16 v[40:43], v[158:161], v[198:201], v[40:43]
	v_mfma_f32_16x16x32_bf16 v[32:35], v[150:153], v[206:209], v[32:35]
	v_mfma_f32_16x16x32_bf16 v[24:27], v[158:161], v[206:209], v[24:27]
	v_mfma_f32_16x16x32_bf16 v[60:63], v[154:157], v[186:189], v[60:63]
	v_mfma_f32_16x16x32_bf16 v[56:59], v[162:165], v[186:189], v[56:59]
	v_mfma_f32_16x16x32_bf16 v[52:55], v[154:157], v[194:197], v[52:55]
	v_mfma_f32_16x16x32_bf16 v[48:51], v[162:165], v[194:197], v[48:51]
	v_mfma_f32_16x16x32_bf16 v[44:47], v[154:157], v[202:205], v[44:47]
	v_mfma_f32_16x16x32_bf16 v[40:43], v[162:165], v[202:205], v[40:43]
	v_mfma_f32_16x16x32_bf16 v[32:35], v[154:157], v[210:213], v[32:35]
	v_mfma_f32_16x16x32_bf16 v[24:27], v[162:165], v[210:213], v[24:27]
	s_setprio 0
	s_setprio 1
	v_mfma_f32_16x16x32_bf16 v[36:39], v[166:169], v[182:185], v[36:39]
	v_mfma_f32_16x16x32_bf16 v[28:31], v[174:177], v[182:185], v[28:31]
	v_mfma_f32_16x16x32_bf16 v[20:23], v[166:169], v[190:193], v[20:23]
	v_mfma_f32_16x16x32_bf16 v[16:19], v[174:177], v[190:193], v[16:19]
	v_mfma_f32_16x16x32_bf16 v[12:15], v[166:169], v[198:201], v[12:15]
	v_mfma_f32_16x16x32_bf16 v[8:11], v[174:177], v[198:201], v[8:11]
	v_mfma_f32_16x16x32_bf16 v[4:7], v[166:169], v[206:209], v[4:7]
	v_mfma_f32_16x16x32_bf16 v[0:3], v[174:177], v[206:209], v[0:3]
	s_setprio 2
	s_barrier
	v_mfma_f32_16x16x32_bf16 v[36:39], v[170:173], v[186:189], v[36:39]
	v_mfma_f32_16x16x32_bf16 v[28:31], v[178:181], v[186:189], v[28:31]
	v_mfma_f32_16x16x32_bf16 v[20:23], v[170:173], v[194:197], v[20:23]
	v_mfma_f32_16x16x32_bf16 v[16:19], v[178:181], v[194:197], v[16:19]
	v_mfma_f32_16x16x32_bf16 v[12:15], v[170:173], v[202:205], v[12:15]
	v_mfma_f32_16x16x32_bf16 v[8:11], v[178:181], v[202:205], v[8:11]
	v_mfma_f32_16x16x32_bf16 v[4:7], v[170:173], v[210:213], v[4:7]
	v_mfma_f32_16x16x32_bf16 v[0:3], v[178:181], v[210:213], v[0:3]
	s_setprio 0
	s_add_i32 s26, s26, 2
	s_add_u32 s10, s10, 0x100
	s_addc_u32 s11, s11, 0
	s_cmp_gt_u32 s26, 41
	s_cbranch_scc0 .LBB0_165
	s_cmpk_lt_u32 s16, 0x100
	s_cbranch_scc0 .LBB0_168
	s_barrier

; #define PG8_STAGE(bufoff, gbase, voff) do { _Pragma("unroll") for (int _i = 0; _i < 2; ++_i) \
;         __builtin_amdgcn_global_load_lds((const unsigned*)((const char*)(gbase) + (voff)[_i]), (PG8_LAS unsigned*)(lds + (bufoff) + ldsw + _i * 8192), 16, 0, 0); } while (0)
; #define PG8_LDA(dst, b, h) do { _Pragma("unroll") for (int m = 0; m < 4; ++m) _Pragma("unroll") for (int k = 0; k < 2; ++k) dst[m][k] = *(const PG8_LAS bf16x8*)(lds + PG8_SA(b, h) + aoff + m * 2048 + k * 1024); } while (0)
; #define PG8_LDB(dst, b, h) do { _Pragma("unroll") for (int n = 0; n < 2; ++n) _Pragma("unroll") for (int k = 0; k < 2; ++k) dst[n][k] = *(const PG8_LAS bf16x8*)(lds + PG8_SB(b, h) + boff + n * 2048 + k * 1024); } while (0)
; #define PG8_BAR __builtin_amdgcn_s_barrier()
; template <class Epi, class Sched, bool ALIGN_EPI = false, bool SP2 = false>
; __device__ __forceinline__ void gemm_phase(PG8_LAS unsigned char* lds, const Gemm g, const Sched& S, const Epi& E) {
;     ...
;             const bool last = (t == nt - 2);
;             const char* a1 = cA + (size_t)(t + 1) * kstep;
;             const char* a2 = last ? nA : cA + (size_t)(t + 2) * kstep; const char* b2 = last ? nB : cB + (size_t)(t + 2) * kstep;
;             const char* a3 = a2 + kstep; const char* b3 = b2 + kstep;
;             if (last && has_next) S.a_ready(nxt);
;             if constexpr (SP2) {
;             PG8_LDB(B0, 0, 0); PG8_LDB(B1, 0, 1); PG8_SCHED; PG8_LDA(At, 0, 0); PG8_STAGE(PG8_SA(1, 1), a1 + hstep, voffA);
;             PG8_WAIT_V(8); PG8_WAIT_L(0); PG8_BAR; PG8_MMA(0, 0, At, B0); PG8_MMA(0, 1, At, B1); PG8_BAR; PG8_SCHED;
;             PG8_LDA(At, 0, 1); PG8_STAGE(PG8_SB(0, 0), b2, voffB); PG8_STAGE(PG8_SB(0, 1), b2 + hstep, voffB); PG8_STAGE(PG8_SA(0, 0), a2, voffA);
;             PG8_WAIT_V(8); PG8_WAIT_L(0); PG8_BAR; PG8_MMA(1, 0, At, B0); PG8_MMA(1, 1, At, B1); PG8_BAR; PG8_SCHED;
;             PG8_LDB(B0, 1, 0); PG8_LDB(B1, 1, 1); PG8_SCHED; PG8_LDA(At, 1, 0); PG8_STAGE(PG8_SA(0, 1), a2 + hstep, voffA);
;             PG8_WAIT_V(8); PG8_WAIT_L(0); PG8_BAR; PG8_MMA(0, 0, At, B0); PG8_MMA(0, 1, At, B1); PG8_BAR; PG8_SCHED;
;             PG8_LDA(At, 1, 1); PG8_STAGE(PG8_SB(1, 0), b3, voffB); PG8_STAGE(PG8_SB(1, 1), b3 + hstep, voffB); PG8_STAGE(PG8_SA(1, 0), a3, voffA);
;             PG8_WAIT_V(8); PG8_WAIT_L(0); PG8_BAR; PG8_MMA(1, 0, At, B0); PG8_MMA(1, 1, At, B1); PG8_BAR; PG8_SCHED;
.LBB0_356:
	ds_read_b128 v[152:155], v149
	ds_read_b128 v[156:159], v149 offset:1024
	ds_read_b128 v[160:163], v149 offset:2048
	ds_read_b128 v[164:167], v149 offset:3072
	ds_read_b128 v[168:171], v150
	ds_read_b128 v[172:175], v150 offset:1024
	ds_read_b128 v[176:179], v150 offset:2048
	ds_read_b128 v[180:183], v150 offset:3072
	s_add_u32 s22, s20, 0xfff80080
	s_addc_u32 s23, s21, -1
	s_cmp_eq_u32 s49, 28
	s_cselect_b32 s25, s15, s23
	s_cselect_b32 s24, s43, s22
	s_cselect_b32 s23, s13, s48
	s_cselect_b32 s22, s44, s45
	v_lshl_add_u64 v[216:217], s[20:21], 0, v[138:139]
	s_add_i32 m0, s11, 0xc000
	ds_read_b128 v[184:187], v151
	ds_read_b128 v[188:191], v151 offset:1024
	ds_read_b128 v[192:195], v151 offset:2048
	ds_read_b128 v[196:199], v151 offset:3072
	ds_read_b128 v[200:203], v151 offset:4096
	ds_read_b128 v[204:207], v151 offset:5120
	ds_read_b128 v[208:211], v151 offset:6144
	ds_read_b128 v[212:215], v151 offset:7168
	global_load_lds_dwordx4 v[216:217], off
	v_lshl_add_u64 v[216:217], s[20:21], 0, v[140:141]
	s_add_i32 m0, s11, 0xe000
	s_nop 0
	global_load_lds_dwordx4 v[216:217], off
	s_waitcnt vmcnt(8)
	s_waitcnt lgkmcnt(0)
	s_barrier
	s_setprio 1
	s_waitcnt lgkmcnt(0)
	v_mfma_f32_16x16x32_bf16 v[124:127], v[152:155], v[184:187], v[124:127]
	v_mfma_f32_16x16x32_bf16 v[120:123], v[160:163], v[184:187], v[120:123]
	v_mfma_f32_16x16x32_bf16 v[116:119], v[152:155], v[192:195], v[116:119]
	v_mfma_f32_16x16x32_bf16 v[112:115], v[160:163], v[192:195], v[112:115]
	v_mfma_f32_16x16x32_bf16 v[100:103], v[152:155], v[200:203], v[100:103]
	v_mfma_f32_16x16x32_bf16 v[96:99], v[160:163], v[200:203], v[96:99]
	v_mfma_f32_16x16x32_bf16 v[84:87], v[152:155], v[208:211], v[84:87]
	v_mfma_f32_16x16x32_bf16 v[80:83], v[160:163], v[208:211], v[80:83]
	v_mfma_f32_16x16x32_bf16 v[124:127], v[156:159], v[188:191], v[124:127]
	v_mfma_f32_16x16x32_bf16 v[120:123], v[164:167], v[188:191], v[120:123]
	v_mfma_f32_16x16x32_bf16 v[116:119], v[156:159], v[196:199], v[116:119]
	v_mfma_f32_16x16x32_bf16 v[112:115], v[164:167], v[196:199], v[112:115]
	v_mfma_f32_16x16x32_bf16 v[100:103], v[156:159], v[204:207], v[100:103]
	v_mfma_f32_16x16x32_bf16 v[96:99], v[164:167], v[204:207], v[96:99]
	v_mfma_f32_16x16x32_bf16 v[84:87], v[156:159], v[212:215], v[84:87]
	v_mfma_f32_16x16x32_bf16 v[80:83], v[164:167], v[212:215], v[80:83]
	s_setprio 0
	s_setprio 1
	v_mfma_f32_16x16x32_bf16 v[108:111], v[168:171], v[184:187], v[108:111]
	v_mfma_f32_16x16x32_bf16 v[104:107], v[176:179], v[184:187], v[104:107]
	v_mfma_f32_16x16x32_bf16 v[92:95], v[168:171], v[192:195], v[92:95]
	v_mfma_f32_16x16x32_bf16 v[88:91], v[176:179], v[192:195], v[88:91]
	v_mfma_f32_16x16x32_bf16 v[76:79], v[168:171], v[200:203], v[76:79]
	v_mfma_f32_16x16x32_bf16 v[72:75], v[176:179], v[200:203], v[72:75]
	v_mfma_f32_16x16x32_bf16 v[68:71], v[168:171], v[208:211], v[68:71]
	v_mfma_f32_16x16x32_bf16 v[64:67], v[176:179], v[208:211], v[64:67]
	s_setprio 2
	s_barrier
	v_mfma_f32_16x16x32_bf16 v[108:111], v[172:175], v[188:191], v[108:111]
	v_mfma_f32_16x16x32_bf16 v[104:107], v[180:183], v[188:191], v[104:107]
	v_mfma_f32_16x16x32_bf16 v[92:95], v[172:175], v[196:199], v[92:95]
	v_mfma_f32_16x16x32_bf16 v[88:91], v[180:183], v[196:199], v[88:91]
	v_mfma_f32_16x16x32_bf16 v[76:79], v[172:175], v[204:207], v[76:79]
	v_mfma_f32_16x16x32_bf16 v[72:75], v[180:183], v[204:207], v[72:75]
	v_mfma_f32_16x16x32_bf16 v[68:71], v[172:175], v[212:215], v[68:71]
	v_mfma_f32_16x16x32_bf16 v[64:67], v[180:183], v[212:215], v[64:67]
	s_setprio 0
	s_add_i32 s50, s39, s26
	v_lshl_add_u64 v[216:217], s[22:23], 0, v[134:135]
	s_mov_b32 m0, s50
	ds_read_b128 v[184:187], v151 offset:16384
	ds_read_b128 v[188:191], v151 offset:17408
	ds_read_b128 v[192:195], v151 offset:18432
	ds_read_b128 v[196:199], v151 offset:19456
	ds_read_b128 v[200:203], v151 offset:20480
	ds_read_b128 v[204:207], v151 offset:21504
	ds_read_b128 v[208:211], v151 offset:22528
	ds_read_b128 v[212:215], v151 offset:23552
	global_load_lds_dwordx4 v[216:217], off
	s_add_i32 m0, s50, 0x2000
	s_add_u32 s50, s22, 0x80000
	v_lshl_add_u64 v[218:219], s[22:23], 0, v[130:131]
	s_addc_u32 s51, s23, 0
	s_add_i32 s52, s40, s26
	global_load_lds_dwordx4 v[218:219], off
	v_lshl_add_u64 v[220:221], s[50:51], 0, v[134:135]
	s_mov_b32 m0, s52
	v_lshl_add_u64 v[222:223], s[24:25], 0, v[132:133]
	global_load_lds_dwordx4 v[220:221], off
	v_lshl_add_u64 v[220:221], s[50:51], 0, v[130:131]
	s_add_i32 m0, s52, 0x2000
	s_nop 0
	global_load_lds_dwordx4 v[220:221], off
	v_lshl_add_u64 v[220:221], s[24:25], 0, v[136:137]
	s_mov_b32 m0, s11
	s_nop 0
	global_load_lds_dwordx4 v[220:221], off
	s_mov_b32 m0, s29
	s_nop 0
	global_load_lds_dwordx4 v[222:223], off
	s_waitcnt vmcnt(8)
	s_waitcnt lgkmcnt(0)
	s_barrier
	s_setprio 1
	s_waitcnt lgkmcnt(0)
	v_mfma_f32_16x16x32_bf16 v[60:63], v[152:155], v[184:187], v[60:63]
	v_mfma_f32_16x16x32_bf16 v[56:59], v[160:163], v[184:187], v[56:59]
	v_mfma_f32_16x16x32_bf16 v[52:55], v[152:155], v[192:195], v[52:55]
	v_mfma_f32_16x16x32_bf16 v[48:51], v[160:163], v[192:195], v[48:51]
	v_mfma_f32_16x16x32_bf16 v[36:39], v[152:155], v[200:203], v[36:39]
	v_mfma_f32_16x16x32_bf16 v[32:35], v[160:163], v[200:203], v[32:35]
	v_mfma_f32_16x16x32_bf16 v[20:23], v[152:155], v[208:211], v[20:23]
	v_mfma_f32_16x16x32_bf16 v[16:19], v[160:163], v[208:211], v[16:19]
	v_mfma_f32_16x16x32_bf16 v[60:63], v[156:159], v[188:191], v[60:63]
	v_mfma_f32_16x16x32_bf16 v[56:59], v[164:167], v[188:191], v[56:59]
	v_mfma_f32_16x16x32_bf16 v[52:55], v[156:159], v[196:199], v[52:55]
	v_mfma_f32_16x16x32_bf16 v[48:51], v[164:167], v[196:199], v[48:51]
	v_mfma_f32_16x16x32_bf16 v[36:39], v[156:159], v[204:207], v[36:39]
	v_mfma_f32_16x16x32_bf16 v[32:35], v[164:167], v[204:207], v[32:35]
	v_mfma_f32_16x16x32_bf16 v[20:23], v[156:159], v[212:215], v[20:23]
	v_mfma_f32_16x16x32_bf16 v[16:19], v[164:167], v[212:215], v[16:19]
	s_setprio 0
	s_setprio 1
	v_mfma_f32_16x16x32_bf16 v[44:47], v[168:171], v[184:187], v[44:47]
	v_mfma_f32_16x16x32_bf16 v[40:43], v[176:179], v[184:187], v[40:43]
	v_mfma_f32_16x16x32_bf16 v[28:31], v[168:171], v[192:195], v[28:31]
	v_mfma_f32_16x16x32_bf16 v[24:27], v[176:179], v[192:195], v[24:27]
	v_mfma_f32_16x16x32_bf16 v[12:15], v[168:171], v[200:203], v[12:15]
	v_mfma_f32_16x16x32_bf16 v[8:11], v[176:179], v[200:203], v[8:11]
	v_mfma_f32_16x16x32_bf16 v[4:7], v[168:171], v[208:211], v[4:7]
	v_mfma_f32_16x16x32_bf16 v[0:3], v[176:179], v[208:211], v[0:3]
	s_setprio 2
	s_barrier
; #define PG8_STAGE(bufoff, gbase, voff) do { _Pragma("unroll") for (int _i = 0; _i < 2; ++_i) \
;         __builtin_amdgcn_global_load_lds((const unsigned*)((const char*)(gbase) + (voff)[_i]), (PG8_LAS unsigned*)(lds + (bufoff) + ldsw + _i * 8192), 16, 0, 0); } while (0)
; #define PG8_LDA(dst, b, h) do { _Pragma("unroll") for (int m = 0; m < 4; ++m) _Pragma("unroll") for (int k = 0; k < 2; ++k) dst[m][k] = *(const PG8_LAS bf16x8*)(lds + PG8_SA(b, h) + aoff + m * 2048 + k * 1024); } while (0)
; #define PG8_LDB(dst, b, h) do { _Pragma("unroll") for (int n = 0; n < 2; ++n) _Pragma("unroll") for (int k = 0; k < 2; ++k) dst[n][k] = *(const PG8_LAS bf16x8*)(lds + PG8_SB(b, h) + boff + n * 2048 + k * 1024); } while (0)
; #define PG8_BAR __builtin_amdgcn_s_barrier()
; template <class Epi, class Sched, bool ALIGN_EPI = false, bool SP2 = false>
; __device__ __forceinline__ void gemm_phase(PG8_LAS unsigned char* lds, const Gemm g, const Sched& S, const Epi& E) {
;     ...
;             const bool last = (t == nt - 2);
;             const char* a1 = cA + (size_t)(t + 1) * kstep;
;             const char* a2 = last ? nA : cA + (size_t)(t + 2) * kstep; const char* b2 = last ? nB : cB + (size_t)(t + 2) * kstep;
;             const char* a3 = a2 + kstep; const char* b3 = b2 + kstep;
;             if (last && has_next) S.a_ready(nxt);
;             if constexpr (SP2) {
;             PG8_LDB(B0, 0, 0); PG8_LDB(B1, 0, 1); PG8_SCHED; PG8_LDA(At, 0, 0); PG8_STAGE(PG8_SA(1, 1), a1 + hstep, voffA);
;             PG8_WAIT_V(8); PG8_WAIT_L(0); PG8_BAR; PG8_MMA(0, 0, At, B0); PG8_MMA(0, 1, At, B1); PG8_BAR; PG8_SCHED;
;             PG8_LDA(At, 0, 1); PG8_STAGE(PG8_SB(0, 0), b2, voffB); PG8_STAGE(PG8_SB(0, 1), b2 + hstep, voffB); PG8_STAGE(PG8_SA(0, 0), a2, voffA);
;             PG8_WAIT_V(8); PG8_WAIT_L(0); PG8_BAR; PG8_MMA(1, 0, At, B0); PG8_MMA(1, 1, At, B1); PG8_BAR; PG8_SCHED;
;             PG8_LDB(B0, 1, 0); PG8_LDB(B1, 1, 1); PG8_SCHED; PG8_LDA(At, 1, 0); PG8_STAGE(PG8_SA(0, 1), a2 + hstep, voffA);
;             PG8_WAIT_V(8); PG8_WAIT_L(0); PG8_BAR; PG8_MMA(0, 0, At, B0); PG8_MMA(0, 1, At, B1); PG8_BAR; PG8_SCHED;
;             PG8_LDA(At, 1, 1); PG8_STAGE(PG8_SB(1, 0), b3, voffB); PG8_STAGE(PG8_SB(1, 1), b3 + hstep, voffB); PG8_STAGE(PG8_SA(1, 0), a3, voffA);
;             PG8_WAIT_V(8); PG8_WAIT_L(0); PG8_BAR; PG8_MMA(1, 0, At, B0); PG8_MMA(1, 1, At, B1); PG8_BAR; PG8_SCHED;
	v_mfma_f32_16x16x32_bf16 v[44:47], v[172:175], v[188:191], v[44:47]
	v_mfma_f32_16x16x32_bf16 v[40:43], v[180:183], v[188:191], v[40:43]
	v_mfma_f32_16x16x32_bf16 v[28:31], v[172:175], v[196:199], v[28:31]
	v_mfma_f32_16x16x32_bf16 v[24:27], v[180:183], v[196:199], v[24:27]
	v_mfma_f32_16x16x32_bf16 v[12:15], v[172:175], v[204:207], v[12:15]
	v_mfma_f32_16x16x32_bf16 v[8:11], v[180:183], v[204:207], v[8:11]
	v_mfma_f32_16x16x32_bf16 v[4:7], v[172:175], v[212:215], v[4:7]
	v_mfma_f32_16x16x32_bf16 v[0:3], v[180:183], v[212:215], v[0:3]
	s_setprio 0
	s_add_i32 s50, 0, 0x18000
	s_add_i32 s51, 0, 0x1c000
	v_add_u32_e32 v164, s50, v147
	v_add_u32_e32 v180, s51, v147
	ds_read_b128 v[152:155], v164
	ds_read_b128 v[156:159], v164 offset:1024
	ds_read_b128 v[160:163], v164 offset:2048
	ds_read_b128 v[164:167], v164 offset:3072
	ds_read_b128 v[168:171], v180
	ds_read_b128 v[172:175], v180 offset:1024
	ds_read_b128 v[176:179], v180 offset:2048
	ds_read_b128 v[180:183], v180 offset:3072
	s_add_u32 s24, s24, 0x80000
	s_addc_u32 s25, s25, 0
	s_mov_b32 m0, s30
	v_lshl_add_u64 v[224:225], s[24:25], 0, v[136:137]
	ds_read_b128 v[184:187], v151 offset:32768
	ds_read_b128 v[188:191], v151 offset:33792
	ds_read_b128 v[192:195], v151 offset:34816
	ds_read_b128 v[196:199], v151 offset:35840
	ds_read_b128 v[200:203], v151 offset:36864
	ds_read_b128 v[204:207], v151 offset:37888
	ds_read_b128 v[208:211], v151 offset:38912
	ds_read_b128 v[212:215], v151 offset:39936
	global_load_lds_dwordx4 v[224:225], off
	v_lshl_add_u64 v[224:225], s[24:25], 0, v[132:133]
	s_mov_b32 m0, s31
	s_nop 0
	global_load_lds_dwordx4 v[224:225], off
	s_waitcnt vmcnt(8)
	s_waitcnt lgkmcnt(0)
	s_barrier
	s_setprio 1
	s_waitcnt lgkmcnt(0)
	v_mfma_f32_16x16x32_bf16 v[124:127], v[152:155], v[184:187], v[124:127]
	v_mfma_f32_16x16x32_bf16 v[120:123], v[160:163], v[184:187], v[120:123]
	v_mfma_f32_16x16x32_bf16 v[116:119], v[152:155], v[192:195], v[116:119]
	v_mfma_f32_16x16x32_bf16 v[112:115], v[160:163], v[192:195], v[112:115]
	v_mfma_f32_16x16x32_bf16 v[100:103], v[152:155], v[200:203], v[100:103]
	v_mfma_f32_16x16x32_bf16 v[96:99], v[160:163], v[200:203], v[96:99]
	v_mfma_f32_16x16x32_bf16 v[84:87], v[152:155], v[208:211], v[84:87]
	v_mfma_f32_16x16x32_bf16 v[80:83], v[160:163], v[208:211], v[80:83]
	v_mfma_f32_16x16x32_bf16 v[124:127], v[156:159], v[188:191], v[124:127]
	v_mfma_f32_16x16x32_bf16 v[120:123], v[164:167], v[188:191], v[120:123]
	v_mfma_f32_16x16x32_bf16 v[116:119], v[156:159], v[196:199], v[116:119]
	v_mfma_f32_16x16x32_bf16 v[112:115], v[164:167], v[196:199], v[112:115]
	v_mfma_f32_16x16x32_bf16 v[100:103], v[156:159], v[204:207], v[100:103]
	v_mfma_f32_16x16x32_bf16 v[96:99], v[164:167], v[204:207], v[96:99]
	v_mfma_f32_16x16x32_bf16 v[84:87], v[156:159], v[212:215], v[84:87]
	v_mfma_f32_16x16x32_bf16 v[80:83], v[164:167], v[212:215], v[80:83]
	s_setprio 0
	s_setprio 1
	v_mfma_f32_16x16x32_bf16 v[108:111], v[168:171], v[184:187], v[108:111]
	v_mfma_f32_16x16x32_bf16 v[104:107], v[176:179], v[184:187], v[104:107]
	v_mfma_f32_16x16x32_bf16 v[92:95], v[168:171], v[192:195], v[92:95]
	v_mfma_f32_16x16x32_bf16 v[88:91], v[176:179], v[192:195], v[88:91]
	v_mfma_f32_16x16x32_bf16 v[76:79], v[168:171], v[200:203], v[76:79]
	v_mfma_f32_16x16x32_bf16 v[72:75], v[176:179], v[200:203], v[72:75]
	v_mfma_f32_16x16x32_bf16 v[68:71], v[168:171], v[208:211], v[68:71]
	v_mfma_f32_16x16x32_bf16 v[64:67], v[176:179], v[208:211], v[64:67]
	s_setprio 2
	s_barrier
; #define PG8_STAGE(bufoff, gbase, voff) do { _Pragma("unroll") for (int _i = 0; _i < 2; ++_i) \
;         __builtin_amdgcn_global_load_lds((const unsigned*)((const char*)(gbase) + (voff)[_i]), (PG8_LAS unsigned*)(lds + (bufoff) + ldsw + _i * 8192), 16, 0, 0); } while (0)
; #define PG8_LDA(dst, b, h) do { _Pragma("unroll") for (int m = 0; m < 4; ++m) _Pragma("unroll") for (int k = 0; k < 2; ++k) dst[m][k] = *(const PG8_LAS bf16x8*)(lds + PG8_SA(b, h) + aoff + m * 2048 + k * 1024); } while (0)
; #define PG8_WAIT_V(n) asm volatile("s_waitcnt vmcnt(" #n ")" ::: "memory")
; #define PG8_WAIT_L(n) asm volatile("s_waitcnt lgkmcnt(" #n ")" ::: "memory")
; template <class Epi, class Sched, bool ALIGN_EPI = false, bool SP2 = false>
; __device__ __forceinline__ void gemm_phase(PG8_LAS unsigned char* lds, const Gemm g, const Sched& S, const Epi& E) {
;     ...
;         for (int t = 0; t < nt; t += 2) {
;             const bool last = (t == nt - 2);
;             const char* a1 = cA + (size_t)(t + 1) * kstep;
;             const char* a2 = last ? nA : cA + (size_t)(t + 2) * kstep; const char* b2 = last ? nB : cB + (size_t)(t + 2) * kstep;
;             const char* a3 = a2 + kstep; const char* b3 = b2 + kstep;
;             if (last && has_next) S.a_ready(nxt);
;             if constexpr (SP2) {
;             PG8_LDB(B0, 0, 0); PG8_LDB(B1, 0, 1); PG8_SCHED; PG8_LDA(At, 0, 0); PG8_STAGE(PG8_SA(1, 1), a1 + hstep, voffA);
;             PG8_WAIT_V(8); PG8_WAIT_L(0); PG8_BAR; PG8_MMA(0, 0, At, B0); PG8_MMA(0, 1, At, B1); PG8_BAR; PG8_SCHED;
;             PG8_LDA(At, 0, 1); PG8_STAGE(PG8_SB(0, 0), b2, voffB); PG8_STAGE(PG8_SB(0, 1), b2 + hstep, voffB); PG8_STAGE(PG8_SA(0, 0), a2, voffA);
;             PG8_WAIT_V(8); PG8_WAIT_L(0); PG8_BAR; PG8_MMA(1, 0, At, B0); PG8_MMA(1, 1, At, B1); PG8_BAR; PG8_SCHED;
;             PG8_LDB(B0, 1, 0); PG8_LDB(B1, 1, 1); PG8_SCHED; PG8_LDA(At, 1, 0); PG8_STAGE(PG8_SA(0, 1), a2 + hstep, voffA);
;             PG8_WAIT_V(8); PG8_WAIT_L(0); PG8_BAR; PG8_MMA(0, 0, At, B0); PG8_MMA(0, 1, At, B1); PG8_BAR; PG8_SCHED;
;             PG8_LDA(At, 1, 1); PG8_STAGE(PG8_SB(1, 0), b3, voffB); PG8_STAGE(PG8_SB(1, 1), b3 + hstep, voffB); PG8_STAGE(PG8_SA(1, 0), a3, voffA);
;             PG8_WAIT_V(8); PG8_WAIT_L(0); PG8_BAR; PG8_MMA(1, 0, At, B0); PG8_MMA(1, 1, At, B1); PG8_BAR; PG8_SCHED;
;     ...
;         if constexpr (ALIGN_EPI) { if (wr == 0) PG8_BAR; }
	v_mfma_f32_16x16x32_bf16 v[108:111], v[172:175], v[188:191], v[108:111]
	v_mfma_f32_16x16x32_bf16 v[104:107], v[180:183], v[188:191], v[104:107]
	v_mfma_f32_16x16x32_bf16 v[92:95], v[172:175], v[196:199], v[92:95]
	v_mfma_f32_16x16x32_bf16 v[88:91], v[180:183], v[196:199], v[88:91]
	v_mfma_f32_16x16x32_bf16 v[76:79], v[172:175], v[204:207], v[76:79]
	v_mfma_f32_16x16x32_bf16 v[72:75], v[180:183], v[204:207], v[72:75]
	v_mfma_f32_16x16x32_bf16 v[68:71], v[172:175], v[212:215], v[68:71]
	v_mfma_f32_16x16x32_bf16 v[64:67], v[180:183], v[212:215], v[64:67]
	s_setprio 0
	s_add_i32 s24, s50, s26
	v_lshl_add_u64 v[216:217], v[216:217], 0, s[4:5]
	s_mov_b32 m0, s24
	ds_read_b128 v[184:187], v151 offset:49152
	ds_read_b128 v[188:191], v151 offset:50176
	ds_read_b128 v[192:195], v151 offset:51200
	ds_read_b128 v[196:199], v151 offset:52224
	ds_read_b128 v[200:203], v151 offset:53248
	ds_read_b128 v[204:207], v151 offset:54272
	ds_read_b128 v[208:211], v151 offset:55296
	ds_read_b128 v[212:215], v151 offset:56320
	global_load_lds_dwordx4 v[216:217], off
	s_add_i32 m0, s24, 0x2000
	s_add_u32 s22, s22, 0x80080
	v_lshl_add_u64 v[216:217], v[218:219], 0, s[4:5]
	s_addc_u32 s23, s23, 0
	s_add_i32 s24, s51, s26
	global_load_lds_dwordx4 v[216:217], off
	v_lshl_add_u64 v[216:217], s[22:23], 0, v[134:135]
	s_mov_b32 m0, s24
	s_nop 0
	global_load_lds_dwordx4 v[216:217], off
	v_lshl_add_u64 v[216:217], s[22:23], 0, v[130:131]
	s_add_i32 m0, s24, 0x2000
	s_nop 0
	global_load_lds_dwordx4 v[216:217], off
	v_lshl_add_u64 v[216:217], v[220:221], 0, s[4:5]
	s_mov_b32 m0, s35
	s_nop 0
	global_load_lds_dwordx4 v[216:217], off
	v_lshl_add_u64 v[216:217], v[222:223], 0, s[4:5]
	s_mov_b32 m0, s36
	s_nop 0
	global_load_lds_dwordx4 v[216:217], off
	s_waitcnt vmcnt(8)
	s_waitcnt lgkmcnt(0)
	s_barrier
	s_setprio 1
	s_waitcnt lgkmcnt(0)
	v_mfma_f32_16x16x32_bf16 v[60:63], v[152:155], v[184:187], v[60:63]
	v_mfma_f32_16x16x32_bf16 v[56:59], v[160:163], v[184:187], v[56:59]
	v_mfma_f32_16x16x32_bf16 v[52:55], v[152:155], v[192:195], v[52:55]
	v_mfma_f32_16x16x32_bf16 v[48:51], v[160:163], v[192:195], v[48:51]
	v_mfma_f32_16x16x32_bf16 v[36:39], v[152:155], v[200:203], v[36:39]
	v_mfma_f32_16x16x32_bf16 v[32:35], v[160:163], v[200:203], v[32:35]
	v_mfma_f32_16x16x32_bf16 v[20:23], v[152:155], v[208:211], v[20:23]
	v_mfma_f32_16x16x32_bf16 v[16:19], v[160:163], v[208:211], v[16:19]
	v_mfma_f32_16x16x32_bf16 v[60:63], v[156:159], v[188:191], v[60:63]
	v_mfma_f32_16x16x32_bf16 v[56:59], v[164:167], v[188:191], v[56:59]
	v_mfma_f32_16x16x32_bf16 v[52:55], v[156:159], v[196:199], v[52:55]
	v_mfma_f32_16x16x32_bf16 v[48:51], v[164:167], v[196:199], v[48:51]
	v_mfma_f32_16x16x32_bf16 v[36:39], v[156:159], v[204:207], v[36:39]
	v_mfma_f32_16x16x32_bf16 v[32:35], v[164:167], v[204:207], v[32:35]
	v_mfma_f32_16x16x32_bf16 v[20:23], v[156:159], v[212:215], v[20:23]
	v_mfma_f32_16x16x32_bf16 v[16:19], v[164:167], v[212:215], v[16:19]
	s_setprio 0
	s_setprio 1
	v_mfma_f32_16x16x32_bf16 v[44:47], v[168:171], v[184:187], v[44:47]
	v_mfma_f32_16x16x32_bf16 v[40:43], v[176:179], v[184:187], v[40:43]
	v_mfma_f32_16x16x32_bf16 v[28:31], v[168:171], v[192:195], v[28:31]
	v_mfma_f32_16x16x32_bf16 v[24:27], v[176:179], v[192:195], v[24:27]
	v_mfma_f32_16x16x32_bf16 v[12:15], v[168:171], v[200:203], v[12:15]
	v_mfma_f32_16x16x32_bf16 v[8:11], v[176:179], v[200:203], v[8:11]
	v_mfma_f32_16x16x32_bf16 v[4:7], v[168:171], v[208:211], v[4:7]
	v_mfma_f32_16x16x32_bf16 v[0:3], v[176:179], v[208:211], v[0:3]
	s_setprio 2
	s_barrier
	v_mfma_f32_16x16x32_bf16 v[44:47], v[172:175], v[188:191], v[44:47]
	v_mfma_f32_16x16x32_bf16 v[40:43], v[180:183], v[188:191], v[40:43]
	v_mfma_f32_16x16x32_bf16 v[28:31], v[172:175], v[196:199], v[28:31]
	v_mfma_f32_16x16x32_bf16 v[24:27], v[180:183], v[196:199], v[24:27]
	v_mfma_f32_16x16x32_bf16 v[12:15], v[172:175], v[204:207], v[12:15]
	v_mfma_f32_16x16x32_bf16 v[8:11], v[180:183], v[204:207], v[8:11]
	v_mfma_f32_16x16x32_bf16 v[4:7], v[172:175], v[212:215], v[4:7]
	v_mfma_f32_16x16x32_bf16 v[0:3], v[180:183], v[212:215], v[0:3]
	s_setprio 0
	s_add_i32 s49, s49, 2
	s_add_u32 s20, s20, 0x100
	s_addc_u32 s21, s21, 0
	s_add_u32 s45, s45, 0x100
	s_addc_u32 s48, s48, 0
	s_cmp_gt_u32 s49, 29
	s_cbranch_scc0 .LBB0_356
	s_and_b64 vcc, exec, s[8:9]
	s_cbranch_vccz .LBB0_359
	s_barrier

; #define PG8_STAGE(bufoff, gbase, voff) do { _Pragma("unroll") for (int _i = 0; _i < 2; ++_i) \
;         __builtin_amdgcn_global_load_lds((const unsigned*)((const char*)(gbase) + (voff)[_i]), (PG8_LAS unsigned*)(lds + (bufoff) + ldsw + _i * 8192), 16, 0, 0); } while (0)
; #define PG8_LDA(dst, b, h) do { _Pragma("unroll") for (int m = 0; m < 4; ++m) _Pragma("unroll") for (int k = 0; k < 2; ++k) dst[m][k] = *(const PG8_LAS bf16x8*)(lds + PG8_SA(b, h) + aoff + m * 2048 + k * 1024); } while (0)
; #define PG8_LDB(dst, b, h) do { _Pragma("unroll") for (int n = 0; n < 2; ++n) _Pragma("unroll") for (int k = 0; k < 2; ++k) dst[n][k] = *(const PG8_LAS bf16x8*)(lds + PG8_SB(b, h) + boff + n * 2048 + k * 1024); } while (0)
; #define PG8_BAR __builtin_amdgcn_s_barrier()
; template <class Epi, class Sched, bool ALIGN_EPI = false, bool SP2 = false>
; __device__ __forceinline__ void gemm_phase(PG8_LAS unsigned char* lds, const Gemm g, const Sched& S, const Epi& E) {
;     ...
;             const bool last = (t == nt - 2);
;             const char* a1 = cA + (size_t)(t + 1) * kstep;
;             const char* a2 = last ? nA : cA + (size_t)(t + 2) * kstep; const char* b2 = last ? nB : cB + (size_t)(t + 2) * kstep;
;             const char* a3 = a2 + kstep; const char* b3 = b2 + kstep;
;             if (last && has_next) S.a_ready(nxt);
;             if constexpr (SP2) {
;             PG8_LDB(B0, 0, 0); PG8_LDB(B1, 0, 1); PG8_SCHED; PG8_LDA(At, 0, 0); PG8_STAGE(PG8_SA(1, 1), a1 + hstep, voffA);
;             PG8_WAIT_V(8); PG8_WAIT_L(0); PG8_BAR; PG8_MMA(0, 0, At, B0); PG8_MMA(0, 1, At, B1); PG8_BAR; PG8_SCHED;
;             PG8_LDA(At, 0, 1); PG8_STAGE(PG8_SB(0, 0), b2, voffB); PG8_STAGE(PG8_SB(0, 1), b2 + hstep, voffB); PG8_STAGE(PG8_SA(0, 0), a2, voffA);
;             PG8_WAIT_V(8); PG8_WAIT_L(0); PG8_BAR; PG8_MMA(1, 0, At, B0); PG8_MMA(1, 1, At, B1); PG8_BAR; PG8_SCHED;
;             PG8_LDB(B0, 1, 0); PG8_LDB(B1, 1, 1); PG8_SCHED; PG8_LDA(At, 1, 0); PG8_STAGE(PG8_SA(0, 1), a2 + hstep, voffA);
;             PG8_WAIT_V(8); PG8_WAIT_L(0); PG8_BAR; PG8_MMA(0, 0, At, B0); PG8_MMA(0, 1, At, B1); PG8_BAR; PG8_SCHED;
;             PG8_LDA(At, 1, 1); PG8_STAGE(PG8_SB(1, 0), b3, voffB); PG8_STAGE(PG8_SB(1, 1), b3 + hstep, voffB); PG8_STAGE(PG8_SA(1, 0), a3, voffA);
;             PG8_WAIT_V(8); PG8_WAIT_L(0); PG8_BAR; PG8_MMA(1, 0, At, B0); PG8_MMA(1, 1, At, B1); PG8_BAR; PG8_SCHED;
.LBB0_818:
	ds_read_b128 v[162:165], v158
	ds_read_b128 v[166:169], v158 offset:1024
	ds_read_b128 v[170:173], v158 offset:2048
	ds_read_b128 v[174:177], v158 offset:3072
	ds_read_b128 v[178:181], v159
	ds_read_b128 v[182:185], v159 offset:1024
	ds_read_b128 v[186:189], v159 offset:2048
	ds_read_b128 v[190:193], v159 offset:3072
	s_add_u32 s34, s30, 0xfff80080
	s_addc_u32 s35, s31, -1
	s_cmp_eq_u32 s59, 28
	s_cselect_b32 s37, s23, s35
	s_cselect_b32 s36, s55, s34
	s_cselect_b32 s35, s21, s58
	s_cselect_b32 s34, s56, s57
	v_lshl_add_u64 v[226:227], s[30:31], 0, v[138:139]
	s_add_i32 m0, s25, 0xc000
	ds_read_b128 v[194:197], v160
	ds_read_b128 v[198:201], v160 offset:1024
	ds_read_b128 v[202:205], v160 offset:2048
	ds_read_b128 v[206:209], v160 offset:3072
	ds_read_b128 v[210:213], v160 offset:4096
	ds_read_b128 v[214:217], v160 offset:5120
	ds_read_b128 v[218:221], v160 offset:6144
	ds_read_b128 v[222:225], v160 offset:7168
	global_load_lds_dwordx4 v[226:227], off
	v_lshl_add_u64 v[226:227], s[30:31], 0, v[140:141]
	s_add_i32 m0, s25, 0xe000
	s_nop 0
	global_load_lds_dwordx4 v[226:227], off
	s_waitcnt vmcnt(8)
	s_waitcnt lgkmcnt(0)
	s_barrier
	s_setprio 1
	s_waitcnt lgkmcnt(0)
	v_mfma_f32_16x16x32_bf16 v[124:127], v[162:165], v[194:197], v[124:127]
	v_mfma_f32_16x16x32_bf16 v[120:123], v[170:173], v[194:197], v[120:123]
	v_mfma_f32_16x16x32_bf16 v[116:119], v[162:165], v[202:205], v[116:119]
	v_mfma_f32_16x16x32_bf16 v[112:115], v[170:173], v[202:205], v[112:115]
	v_mfma_f32_16x16x32_bf16 v[100:103], v[162:165], v[210:213], v[100:103]
	v_mfma_f32_16x16x32_bf16 v[96:99], v[170:173], v[210:213], v[96:99]
	v_mfma_f32_16x16x32_bf16 v[84:87], v[162:165], v[218:221], v[84:87]
	v_mfma_f32_16x16x32_bf16 v[80:83], v[170:173], v[218:221], v[80:83]
	v_mfma_f32_16x16x32_bf16 v[124:127], v[166:169], v[198:201], v[124:127]
	v_mfma_f32_16x16x32_bf16 v[120:123], v[174:177], v[198:201], v[120:123]
	v_mfma_f32_16x16x32_bf16 v[116:119], v[166:169], v[206:209], v[116:119]
	v_mfma_f32_16x16x32_bf16 v[112:115], v[174:177], v[206:209], v[112:115]
	v_mfma_f32_16x16x32_bf16 v[100:103], v[166:169], v[214:217], v[100:103]
	v_mfma_f32_16x16x32_bf16 v[96:99], v[174:177], v[214:217], v[96:99]
	v_mfma_f32_16x16x32_bf16 v[84:87], v[166:169], v[222:225], v[84:87]
	v_mfma_f32_16x16x32_bf16 v[80:83], v[174:177], v[222:225], v[80:83]
	s_setprio 0
	s_setprio 1
	v_mfma_f32_16x16x32_bf16 v[108:111], v[178:181], v[194:197], v[108:111]
	v_mfma_f32_16x16x32_bf16 v[104:107], v[186:189], v[194:197], v[104:107]
	v_mfma_f32_16x16x32_bf16 v[92:95], v[178:181], v[202:205], v[92:95]
	v_mfma_f32_16x16x32_bf16 v[88:91], v[186:189], v[202:205], v[88:91]
	v_mfma_f32_16x16x32_bf16 v[76:79], v[178:181], v[210:213], v[76:79]
	v_mfma_f32_16x16x32_bf16 v[72:75], v[186:189], v[210:213], v[72:75]
	v_mfma_f32_16x16x32_bf16 v[68:71], v[178:181], v[218:221], v[68:71]
	v_mfma_f32_16x16x32_bf16 v[64:67], v[186:189], v[218:221], v[64:67]
	s_setprio 2
	s_barrier
	v_mfma_f32_16x16x32_bf16 v[108:111], v[182:185], v[198:201], v[108:111]
	v_mfma_f32_16x16x32_bf16 v[104:107], v[190:193], v[198:201], v[104:107]
	v_mfma_f32_16x16x32_bf16 v[92:95], v[182:185], v[206:209], v[92:95]
	v_mfma_f32_16x16x32_bf16 v[88:91], v[190:193], v[206:209], v[88:91]
	v_mfma_f32_16x16x32_bf16 v[76:79], v[182:185], v[214:217], v[76:79]
	v_mfma_f32_16x16x32_bf16 v[72:75], v[190:193], v[214:217], v[72:75]
	v_mfma_f32_16x16x32_bf16 v[68:71], v[182:185], v[222:225], v[68:71]
	v_mfma_f32_16x16x32_bf16 v[64:67], v[190:193], v[222:225], v[64:67]
	s_setprio 0
	s_add_i32 s60, s48, s33
	v_lshl_add_u64 v[226:227], s[34:35], 0, v[134:135]
	s_mov_b32 m0, s60
	ds_read_b128 v[194:197], v160 offset:16384
	ds_read_b128 v[198:201], v160 offset:17408
	ds_read_b128 v[202:205], v160 offset:18432
	ds_read_b128 v[206:209], v160 offset:19456
	ds_read_b128 v[210:213], v160 offset:20480
	ds_read_b128 v[214:217], v160 offset:21504
	ds_read_b128 v[218:221], v160 offset:22528
	ds_read_b128 v[222:225], v160 offset:23552
	global_load_lds_dwordx4 v[226:227], off
	s_add_i32 m0, s60, 0x2000
	s_add_u32 s60, s34, 0x80000
	v_lshl_add_u64 v[228:229], s[34:35], 0, v[130:131]
	s_addc_u32 s61, s35, 0
	s_add_i32 s62, s49, s33
	global_load_lds_dwordx4 v[228:229], off
	v_lshl_add_u64 v[230:231], s[60:61], 0, v[134:135]
	s_mov_b32 m0, s62
	v_lshl_add_u64 v[232:233], s[36:37], 0, v[132:133]
	global_load_lds_dwordx4 v[230:231], off
	v_lshl_add_u64 v[230:231], s[60:61], 0, v[130:131]
	s_add_i32 m0, s62, 0x2000
	s_nop 0
	global_load_lds_dwordx4 v[230:231], off
	v_lshl_add_u64 v[230:231], s[36:37], 0, v[136:137]
	s_mov_b32 m0, s25
	s_nop 0
	global_load_lds_dwordx4 v[230:231], off
	s_mov_b32 m0, s40
	s_nop 0
	global_load_lds_dwordx4 v[232:233], off
	s_waitcnt vmcnt(8)
	s_waitcnt lgkmcnt(0)
	s_barrier
	s_setprio 1
	s_waitcnt lgkmcnt(0)
	v_mfma_f32_16x16x32_bf16 v[60:63], v[162:165], v[194:197], v[60:63]
	v_mfma_f32_16x16x32_bf16 v[56:59], v[170:173], v[194:197], v[56:59]
	v_mfma_f32_16x16x32_bf16 v[52:55], v[162:165], v[202:205], v[52:55]
	v_mfma_f32_16x16x32_bf16 v[48:51], v[170:173], v[202:205], v[48:51]
	v_mfma_f32_16x16x32_bf16 v[36:39], v[162:165], v[210:213], v[36:39]
	v_mfma_f32_16x16x32_bf16 v[32:35], v[170:173], v[210:213], v[32:35]
	v_mfma_f32_16x16x32_bf16 v[20:23], v[162:165], v[218:221], v[20:23]
	v_mfma_f32_16x16x32_bf16 v[16:19], v[170:173], v[218:221], v[16:19]
	v_mfma_f32_16x16x32_bf16 v[60:63], v[166:169], v[198:201], v[60:63]
	v_mfma_f32_16x16x32_bf16 v[56:59], v[174:177], v[198:201], v[56:59]
	v_mfma_f32_16x16x32_bf16 v[52:55], v[166:169], v[206:209], v[52:55]
	v_mfma_f32_16x16x32_bf16 v[48:51], v[174:177], v[206:209], v[48:51]
	v_mfma_f32_16x16x32_bf16 v[36:39], v[166:169], v[214:217], v[36:39]
	v_mfma_f32_16x16x32_bf16 v[32:35], v[174:177], v[214:217], v[32:35]
	v_mfma_f32_16x16x32_bf16 v[20:23], v[166:169], v[222:225], v[20:23]
	v_mfma_f32_16x16x32_bf16 v[16:19], v[174:177], v[222:225], v[16:19]
	s_setprio 0
	s_setprio 1
	v_mfma_f32_16x16x32_bf16 v[44:47], v[178:181], v[194:197], v[44:47]
	v_mfma_f32_16x16x32_bf16 v[40:43], v[186:189], v[194:197], v[40:43]
	v_mfma_f32_16x16x32_bf16 v[28:31], v[178:181], v[202:205], v[28:31]
	v_mfma_f32_16x16x32_bf16 v[24:27], v[186:189], v[202:205], v[24:27]
	v_mfma_f32_16x16x32_bf16 v[12:15], v[178:181], v[210:213], v[12:15]
	v_mfma_f32_16x16x32_bf16 v[8:11], v[186:189], v[210:213], v[8:11]
	v_mfma_f32_16x16x32_bf16 v[4:7], v[178:181], v[218:221], v[4:7]
	v_mfma_f32_16x16x32_bf16 v[0:3], v[186:189], v[218:221], v[0:3]
	s_setprio 2
	s_barrier
; #define PG8_STAGE(bufoff, gbase, voff) do { _Pragma("unroll") for (int _i = 0; _i < 2; ++_i) \
;         __builtin_amdgcn_global_load_lds((const unsigned*)((const char*)(gbase) + (voff)[_i]), (PG8_LAS unsigned*)(lds + (bufoff) + ldsw + _i * 8192), 16, 0, 0); } while (0)
; #define PG8_LDA(dst, b, h) do { _Pragma("unroll") for (int m = 0; m < 4; ++m) _Pragma("unroll") for (int k = 0; k < 2; ++k) dst[m][k] = *(const PG8_LAS bf16x8*)(lds + PG8_SA(b, h) + aoff + m * 2048 + k * 1024); } while (0)
; #define PG8_LDB(dst, b, h) do { _Pragma("unroll") for (int n = 0; n < 2; ++n) _Pragma("unroll") for (int k = 0; k < 2; ++k) dst[n][k] = *(const PG8_LAS bf16x8*)(lds + PG8_SB(b, h) + boff + n * 2048 + k * 1024); } while (0)
; #define PG8_BAR __builtin_amdgcn_s_barrier()
; template <class Epi, class Sched, bool ALIGN_EPI = false, bool SP2 = false>
; __device__ __forceinline__ void gemm_phase(PG8_LAS unsigned char* lds, const Gemm g, const Sched& S, const Epi& E) {
;     ...
;             const bool last = (t == nt - 2);
;             const char* a1 = cA + (size_t)(t + 1) * kstep;
;             const char* a2 = last ? nA : cA + (size_t)(t + 2) * kstep; const char* b2 = last ? nB : cB + (size_t)(t + 2) * kstep;
;             const char* a3 = a2 + kstep; const char* b3 = b2 + kstep;
;             if (last && has_next) S.a_ready(nxt);
;             if constexpr (SP2) {
;             PG8_LDB(B0, 0, 0); PG8_LDB(B1, 0, 1); PG8_SCHED; PG8_LDA(At, 0, 0); PG8_STAGE(PG8_SA(1, 1), a1 + hstep, voffA);
;             PG8_WAIT_V(8); PG8_WAIT_L(0); PG8_BAR; PG8_MMA(0, 0, At, B0); PG8_MMA(0, 1, At, B1); PG8_BAR; PG8_SCHED;
;             PG8_LDA(At, 0, 1); PG8_STAGE(PG8_SB(0, 0), b2, voffB); PG8_STAGE(PG8_SB(0, 1), b2 + hstep, voffB); PG8_STAGE(PG8_SA(0, 0), a2, voffA);
;             PG8_WAIT_V(8); PG8_WAIT_L(0); PG8_BAR; PG8_MMA(1, 0, At, B0); PG8_MMA(1, 1, At, B1); PG8_BAR; PG8_SCHED;
;             PG8_LDB(B0, 1, 0); PG8_LDB(B1, 1, 1); PG8_SCHED; PG8_LDA(At, 1, 0); PG8_STAGE(PG8_SA(0, 1), a2 + hstep, voffA);
;             PG8_WAIT_V(8); PG8_WAIT_L(0); PG8_BAR; PG8_MMA(0, 0, At, B0); PG8_MMA(0, 1, At, B1); PG8_BAR; PG8_SCHED;
;             PG8_LDA(At, 1, 1); PG8_STAGE(PG8_SB(1, 0), b3, voffB); PG8_STAGE(PG8_SB(1, 1), b3 + hstep, voffB); PG8_STAGE(PG8_SA(1, 0), a3, voffA);
;             PG8_WAIT_V(8); PG8_WAIT_L(0); PG8_BAR; PG8_MMA(1, 0, At, B0); PG8_MMA(1, 1, At, B1); PG8_BAR; PG8_SCHED;
	v_mfma_f32_16x16x32_bf16 v[44:47], v[182:185], v[198:201], v[44:47]
	v_mfma_f32_16x16x32_bf16 v[40:43], v[190:193], v[198:201], v[40:43]
	v_mfma_f32_16x16x32_bf16 v[28:31], v[182:185], v[206:209], v[28:31]
	v_mfma_f32_16x16x32_bf16 v[24:27], v[190:193], v[206:209], v[24:27]
	v_mfma_f32_16x16x32_bf16 v[12:15], v[182:185], v[214:217], v[12:15]
	v_mfma_f32_16x16x32_bf16 v[8:11], v[190:193], v[214:217], v[8:11]
	v_mfma_f32_16x16x32_bf16 v[4:7], v[182:185], v[222:225], v[4:7]
	v_mfma_f32_16x16x32_bf16 v[0:3], v[190:193], v[222:225], v[0:3]
	s_setprio 0
	s_add_i32 s60, 0, 0x18000
	v_add_u32_e32 v161, s60, v156
	s_add_i32 s61, 0, 0x1c000
	ds_read_b128 v[162:165], v161
	ds_read_b128 v[166:169], v161 offset:1024
	ds_read_b128 v[170:173], v161 offset:2048
	ds_read_b128 v[174:177], v161 offset:3072
	v_add_u32_e32 v161, s61, v156
	ds_read_b128 v[178:181], v161
	ds_read_b128 v[182:185], v161 offset:1024
	ds_read_b128 v[186:189], v161 offset:2048
	ds_read_b128 v[190:193], v161 offset:3072
	s_add_u32 s36, s36, 0x80000
	s_addc_u32 s37, s37, 0
	s_mov_b32 m0, s41
	v_lshl_add_u64 v[234:235], s[36:37], 0, v[136:137]
	ds_read_b128 v[194:197], v160 offset:32768
	ds_read_b128 v[198:201], v160 offset:33792
	ds_read_b128 v[202:205], v160 offset:34816
	ds_read_b128 v[206:209], v160 offset:35840
	ds_read_b128 v[210:213], v160 offset:36864
	ds_read_b128 v[214:217], v160 offset:37888
	ds_read_b128 v[218:221], v160 offset:38912
	ds_read_b128 v[222:225], v160 offset:39936
	global_load_lds_dwordx4 v[234:235], off
	v_lshl_add_u64 v[234:235], s[36:37], 0, v[132:133]
	s_mov_b32 m0, s42
	s_nop 0
	global_load_lds_dwordx4 v[234:235], off
	s_waitcnt vmcnt(8)
	s_waitcnt lgkmcnt(0)
	s_barrier
	s_setprio 1
	s_waitcnt lgkmcnt(0)
	v_mfma_f32_16x16x32_bf16 v[124:127], v[162:165], v[194:197], v[124:127]
	v_mfma_f32_16x16x32_bf16 v[120:123], v[170:173], v[194:197], v[120:123]
	v_mfma_f32_16x16x32_bf16 v[116:119], v[162:165], v[202:205], v[116:119]
	v_mfma_f32_16x16x32_bf16 v[112:115], v[170:173], v[202:205], v[112:115]
	v_mfma_f32_16x16x32_bf16 v[100:103], v[162:165], v[210:213], v[100:103]
	v_mfma_f32_16x16x32_bf16 v[96:99], v[170:173], v[210:213], v[96:99]
	v_mfma_f32_16x16x32_bf16 v[84:87], v[162:165], v[218:221], v[84:87]
	v_mfma_f32_16x16x32_bf16 v[80:83], v[170:173], v[218:221], v[80:83]
	v_mfma_f32_16x16x32_bf16 v[124:127], v[166:169], v[198:201], v[124:127]
	v_mfma_f32_16x16x32_bf16 v[120:123], v[174:177], v[198:201], v[120:123]
	v_mfma_f32_16x16x32_bf16 v[116:119], v[166:169], v[206:209], v[116:119]
	v_mfma_f32_16x16x32_bf16 v[112:115], v[174:177], v[206:209], v[112:115]
	v_mfma_f32_16x16x32_bf16 v[100:103], v[166:169], v[214:217], v[100:103]
	v_mfma_f32_16x16x32_bf16 v[96:99], v[174:177], v[214:217], v[96:99]
	v_mfma_f32_16x16x32_bf16 v[84:87], v[166:169], v[222:225], v[84:87]
	v_mfma_f32_16x16x32_bf16 v[80:83], v[174:177], v[222:225], v[80:83]
	s_setprio 0
	s_setprio 1
	v_mfma_f32_16x16x32_bf16 v[108:111], v[178:181], v[194:197], v[108:111]
	v_mfma_f32_16x16x32_bf16 v[104:107], v[186:189], v[194:197], v[104:107]
	v_mfma_f32_16x16x32_bf16 v[92:95], v[178:181], v[202:205], v[92:95]
	v_mfma_f32_16x16x32_bf16 v[88:91], v[186:189], v[202:205], v[88:91]
	v_mfma_f32_16x16x32_bf16 v[76:79], v[178:181], v[210:213], v[76:79]
	v_mfma_f32_16x16x32_bf16 v[72:75], v[186:189], v[210:213], v[72:75]
	v_mfma_f32_16x16x32_bf16 v[68:71], v[178:181], v[218:221], v[68:71]
	v_mfma_f32_16x16x32_bf16 v[64:67], v[186:189], v[218:221], v[64:67]
	s_setprio 2
	s_barrier
; #define PG8_STAGE(bufoff, gbase, voff) do { _Pragma("unroll") for (int _i = 0; _i < 2; ++_i) \
;         __builtin_amdgcn_global_load_lds((const unsigned*)((const char*)(gbase) + (voff)[_i]), (PG8_LAS unsigned*)(lds + (bufoff) + ldsw + _i * 8192), 16, 0, 0); } while (0)
; #define PG8_LDA(dst, b, h) do { _Pragma("unroll") for (int m = 0; m < 4; ++m) _Pragma("unroll") for (int k = 0; k < 2; ++k) dst[m][k] = *(const PG8_LAS bf16x8*)(lds + PG8_SA(b, h) + aoff + m * 2048 + k * 1024); } while (0)
; #define PG8_WAIT_V(n) asm volatile("s_waitcnt vmcnt(" #n ")" ::: "memory")
; #define PG8_WAIT_L(n) asm volatile("s_waitcnt lgkmcnt(" #n ")" ::: "memory")
; template <class Epi, class Sched, bool ALIGN_EPI = false, bool SP2 = false>
; __device__ __forceinline__ void gemm_phase(PG8_LAS unsigned char* lds, const Gemm g, const Sched& S, const Epi& E) {
;     ...
;         for (int t = 0; t < nt; t += 2) {
;             const bool last = (t == nt - 2);
;             const char* a1 = cA + (size_t)(t + 1) * kstep;
;             const char* a2 = last ? nA : cA + (size_t)(t + 2) * kstep; const char* b2 = last ? nB : cB + (size_t)(t + 2) * kstep;
;             const char* a3 = a2 + kstep; const char* b3 = b2 + kstep;
;             if (last && has_next) S.a_ready(nxt);
;             if constexpr (SP2) {
;             PG8_LDB(B0, 0, 0); PG8_LDB(B1, 0, 1); PG8_SCHED; PG8_LDA(At, 0, 0); PG8_STAGE(PG8_SA(1, 1), a1 + hstep, voffA);
;             PG8_WAIT_V(8); PG8_WAIT_L(0); PG8_BAR; PG8_MMA(0, 0, At, B0); PG8_MMA(0, 1, At, B1); PG8_BAR; PG8_SCHED;
;             PG8_LDA(At, 0, 1); PG8_STAGE(PG8_SB(0, 0), b2, voffB); PG8_STAGE(PG8_SB(0, 1), b2 + hstep, voffB); PG8_STAGE(PG8_SA(0, 0), a2, voffA);
;             PG8_WAIT_V(8); PG8_WAIT_L(0); PG8_BAR; PG8_MMA(1, 0, At, B0); PG8_MMA(1, 1, At, B1); PG8_BAR; PG8_SCHED;
;             PG8_LDB(B0, 1, 0); PG8_LDB(B1, 1, 1); PG8_SCHED; PG8_LDA(At, 1, 0); PG8_STAGE(PG8_SA(0, 1), a2 + hstep, voffA);
;             PG8_WAIT_V(8); PG8_WAIT_L(0); PG8_BAR; PG8_MMA(0, 0, At, B0); PG8_MMA(0, 1, At, B1); PG8_BAR; PG8_SCHED;
;             PG8_LDA(At, 1, 1); PG8_STAGE(PG8_SB(1, 0), b3, voffB); PG8_STAGE(PG8_SB(1, 1), b3 + hstep, voffB); PG8_STAGE(PG8_SA(1, 0), a3, voffA);
;             PG8_WAIT_V(8); PG8_WAIT_L(0); PG8_BAR; PG8_MMA(1, 0, At, B0); PG8_MMA(1, 1, At, B1); PG8_BAR; PG8_SCHED;
;     ...
;         if constexpr (ALIGN_EPI) { if (wr == 0) PG8_BAR; }
	v_mfma_f32_16x16x32_bf16 v[108:111], v[182:185], v[198:201], v[108:111]
	v_mfma_f32_16x16x32_bf16 v[104:107], v[190:193], v[198:201], v[104:107]
	v_mfma_f32_16x16x32_bf16 v[92:95], v[182:185], v[206:209], v[92:95]
	v_mfma_f32_16x16x32_bf16 v[88:91], v[190:193], v[206:209], v[88:91]
	v_mfma_f32_16x16x32_bf16 v[76:79], v[182:185], v[214:217], v[76:79]
	v_mfma_f32_16x16x32_bf16 v[72:75], v[190:193], v[214:217], v[72:75]
	v_mfma_f32_16x16x32_bf16 v[68:71], v[182:185], v[222:225], v[68:71]
	v_mfma_f32_16x16x32_bf16 v[64:67], v[190:193], v[222:225], v[64:67]
	s_setprio 0
	s_add_i32 s36, s60, s33
	v_lshl_add_u64 v[226:227], v[226:227], 0, s[10:11]
	s_mov_b32 m0, s36
	ds_read_b128 v[194:197], v160 offset:49152
	ds_read_b128 v[198:201], v160 offset:50176
	ds_read_b128 v[202:205], v160 offset:51200
	ds_read_b128 v[206:209], v160 offset:52224
	ds_read_b128 v[210:213], v160 offset:53248
	ds_read_b128 v[214:217], v160 offset:54272
	ds_read_b128 v[218:221], v160 offset:55296
	ds_read_b128 v[222:225], v160 offset:56320
	global_load_lds_dwordx4 v[226:227], off
	s_add_i32 m0, s36, 0x2000
	s_add_u32 s34, s34, 0x80080
	v_lshl_add_u64 v[226:227], v[228:229], 0, s[10:11]
	s_addc_u32 s35, s35, 0
	s_add_i32 s36, s61, s33
	global_load_lds_dwordx4 v[226:227], off
	v_lshl_add_u64 v[226:227], s[34:35], 0, v[134:135]
	s_mov_b32 m0, s36
	s_nop 0
	global_load_lds_dwordx4 v[226:227], off
	v_lshl_add_u64 v[226:227], s[34:35], 0, v[130:131]
	s_add_i32 m0, s36, 0x2000
	s_nop 0
	global_load_lds_dwordx4 v[226:227], off
	v_lshl_add_u64 v[226:227], v[230:231], 0, s[10:11]
	s_mov_b32 m0, s44
	s_nop 0
	global_load_lds_dwordx4 v[226:227], off
	v_lshl_add_u64 v[226:227], v[232:233], 0, s[10:11]
	s_mov_b32 m0, s45
	s_nop 0
	global_load_lds_dwordx4 v[226:227], off
	s_waitcnt vmcnt(8)
	s_waitcnt lgkmcnt(0)
	s_barrier
	s_setprio 1
	s_waitcnt lgkmcnt(0)
	v_mfma_f32_16x16x32_bf16 v[60:63], v[162:165], v[194:197], v[60:63]
	v_mfma_f32_16x16x32_bf16 v[56:59], v[170:173], v[194:197], v[56:59]
	v_mfma_f32_16x16x32_bf16 v[52:55], v[162:165], v[202:205], v[52:55]
	v_mfma_f32_16x16x32_bf16 v[48:51], v[170:173], v[202:205], v[48:51]
	v_mfma_f32_16x16x32_bf16 v[36:39], v[162:165], v[210:213], v[36:39]
	v_mfma_f32_16x16x32_bf16 v[32:35], v[170:173], v[210:213], v[32:35]
	v_mfma_f32_16x16x32_bf16 v[20:23], v[162:165], v[218:221], v[20:23]
	v_mfma_f32_16x16x32_bf16 v[16:19], v[170:173], v[218:221], v[16:19]
	v_mfma_f32_16x16x32_bf16 v[60:63], v[166:169], v[198:201], v[60:63]
	v_mfma_f32_16x16x32_bf16 v[56:59], v[174:177], v[198:201], v[56:59]
	v_mfma_f32_16x16x32_bf16 v[52:55], v[166:169], v[206:209], v[52:55]
	v_mfma_f32_16x16x32_bf16 v[48:51], v[174:177], v[206:209], v[48:51]
	v_mfma_f32_16x16x32_bf16 v[36:39], v[166:169], v[214:217], v[36:39]
	v_mfma_f32_16x16x32_bf16 v[32:35], v[174:177], v[214:217], v[32:35]
	v_mfma_f32_16x16x32_bf16 v[20:23], v[166:169], v[222:225], v[20:23]
	v_mfma_f32_16x16x32_bf16 v[16:19], v[174:177], v[222:225], v[16:19]
	s_setprio 0
	s_setprio 1
	v_mfma_f32_16x16x32_bf16 v[44:47], v[178:181], v[194:197], v[44:47]
	v_mfma_f32_16x16x32_bf16 v[40:43], v[186:189], v[194:197], v[40:43]
	v_mfma_f32_16x16x32_bf16 v[28:31], v[178:181], v[202:205], v[28:31]
	v_mfma_f32_16x16x32_bf16 v[24:27], v[186:189], v[202:205], v[24:27]
	v_mfma_f32_16x16x32_bf16 v[12:15], v[178:181], v[210:213], v[12:15]
	v_mfma_f32_16x16x32_bf16 v[8:11], v[186:189], v[210:213], v[8:11]
	v_mfma_f32_16x16x32_bf16 v[4:7], v[178:181], v[218:221], v[4:7]
	v_mfma_f32_16x16x32_bf16 v[0:3], v[186:189], v[218:221], v[0:3]
	s_setprio 2
	s_barrier
	v_mfma_f32_16x16x32_bf16 v[44:47], v[182:185], v[198:201], v[44:47]
	v_mfma_f32_16x16x32_bf16 v[40:43], v[190:193], v[198:201], v[40:43]
	v_mfma_f32_16x16x32_bf16 v[28:31], v[182:185], v[206:209], v[28:31]
	v_mfma_f32_16x16x32_bf16 v[24:27], v[190:193], v[206:209], v[24:27]
	v_mfma_f32_16x16x32_bf16 v[12:15], v[182:185], v[214:217], v[12:15]
	v_mfma_f32_16x16x32_bf16 v[8:11], v[190:193], v[214:217], v[8:11]
	v_mfma_f32_16x16x32_bf16 v[4:7], v[182:185], v[222:225], v[4:7]
	v_mfma_f32_16x16x32_bf16 v[0:3], v[190:193], v[222:225], v[0:3]
	s_setprio 0
	s_add_i32 s59, s59, 2
	s_add_u32 s30, s30, 0x100
	s_addc_u32 s31, s31, 0
	s_add_u32 s57, s57, 0x100
	s_addc_u32 s58, s58, 0
	s_cmp_gt_u32 s59, 29
	s_cbranch_scc0 .LBB0_818
	s_and_b64 vcc, exec, s[12:13]
	s_cbranch_vccz .LBB0_821
	s_barrier

; #define PG8_STAGE(bufoff, gbase, voff) do { _Pragma("unroll") for (int _i = 0; _i < 2; ++_i) \
;         __builtin_amdgcn_global_load_lds((const unsigned*)((const char*)(gbase) + (voff)[_i]), (PG8_LAS unsigned*)(lds + (bufoff) + ldsw + _i * 8192), 16, 0, 0); } while (0)
; #define PG8_LDA(dst, b, h) do { _Pragma("unroll") for (int m = 0; m < 4; ++m) _Pragma("unroll") for (int k = 0; k < 2; ++k) dst[m][k] = *(const PG8_LAS bf16x8*)(lds + PG8_SA(b, h) + aoff + m * 2048 + k * 1024); } while (0)
; #define PG8_BAR __builtin_amdgcn_s_barrier()
; template <class Epi, class Sched, bool ALIGN_EPI = false, bool SP2 = false>
; __device__ __forceinline__ void gemm_phase(PG8_LAS unsigned char* lds, const Gemm g, const Sched& S, const Epi& E) {
;     ...
;         const char* nA = has_next ? (const char*)g.A + (size_t)nxt.pm * tstep : cA; const char* nB = has_next ? (const char*)g.Bt + (size_t)nxt.pn * tstep : cB;
;         for (int t = 0; t < nt; t += 2) {
;             const bool last = (t == nt - 2);
;             const char* a1 = cA + (size_t)(t + 1) * kstep;
;             const char* a2 = last ? nA : cA + (size_t)(t + 2) * kstep; const char* b2 = last ? nB : cB + (size_t)(t + 2) * kstep;
;             const char* a3 = a2 + kstep; const char* b3 = b2 + kstep;
;             if (last && has_next) S.a_ready(nxt);
;             if constexpr (SP2) {
;             PG8_LDB(B0, 0, 0); PG8_LDB(B1, 0, 1); PG8_SCHED; PG8_LDA(At, 0, 0); PG8_STAGE(PG8_SA(1, 1), a1 + hstep, voffA);
;             PG8_WAIT_V(8); PG8_WAIT_L(0); PG8_BAR; PG8_MMA(0, 0, At, B0); PG8_MMA(0, 1, At, B1); PG8_BAR; PG8_SCHED;
;             PG8_LDA(At, 0, 1); PG8_STAGE(PG8_SB(0, 0), b2, voffB); PG8_STAGE(PG8_SB(0, 1), b2 + hstep, voffB); PG8_STAGE(PG8_SA(0, 0), a2, voffA);
;             PG8_WAIT_V(8); PG8_WAIT_L(0); PG8_BAR; PG8_MMA(1, 0, At, B0); PG8_MMA(1, 1, At, B1); PG8_BAR; PG8_SCHED;
;             PG8_LDB(B0, 1, 0); PG8_LDB(B1, 1, 1); PG8_SCHED; PG8_LDA(At, 1, 0); PG8_STAGE(PG8_SA(0, 1), a2 + hstep, voffA);
;             PG8_WAIT_V(8); PG8_WAIT_L(0); PG8_BAR; PG8_MMA(0, 0, At, B0); PG8_MMA(0, 1, At, B1); PG8_BAR; PG8_SCHED;
;             PG8_LDA(At, 1, 1); PG8_STAGE(PG8_SB(1, 0), b3, voffB); PG8_STAGE(PG8_SB(1, 1), b3 + hstep, voffB); PG8_STAGE(PG8_SA(1, 0), a3, voffA);
;             PG8_WAIT_V(8); PG8_WAIT_L(0); PG8_BAR; PG8_MMA(1, 0, At, B0); PG8_MMA(1, 1, At, B1); PG8_BAR; PG8_SCHED;
.LBB0_835:
	s_add_u32 s31, s24, s30
	s_addc_u32 s38, s25, 0
	s_add_u32 s36, s31, 0x100
	s_addc_u32 s37, s38, 0
	s_and_b64 s[34:35], s[28:29], exec
	s_cselect_b32 s35, s15, s37
	s_cselect_b32 s34, s58, s36
	s_add_u32 s30, s18, s30
	s_addc_u32 s36, s19, 0
	s_add_u32 s30, s30, 0x100
	s_addc_u32 s36, s36, 0
	s_and_b64 s[28:29], s[28:29], exec
	s_cselect_b32 s37, s13, s36
	s_cselect_b32 s36, s59, s30
	s_add_u32 s40, s31, 0x10080
	ds_read_b128 v[148:151], v145
	ds_read_b128 v[152:155], v145 offset:1024
	ds_read_b128 v[156:159], v145 offset:2048
	ds_read_b128 v[160:163], v145 offset:3072
	ds_read_b128 v[164:167], v146
	ds_read_b128 v[168:171], v146 offset:1024
	ds_read_b128 v[172:175], v146 offset:2048
	ds_read_b128 v[176:179], v146 offset:3072
	s_addc_u32 s41, s38, 0
	s_add_i32 s69, s55, s42
	s_add_i32 m0, s17, 0xc000
	s_add_i32 s70, s17, 0xe000
	s_add_i32 s66, s69, 0x2000
	s_add_u32 s38, s36, 0x10000
	s_addc_u32 s39, s37, 0
	s_add_i32 s68, s56, s42
	s_add_i32 s67, s68, 0x2000
	s_add_i32 s65, 0, 0x18000
	s_add_i32 s64, 0, 0x1c000
	s_add_u32 s30, s34, 0x10000
	s_addc_u32 s31, s35, 0
	s_add_i32 s63, s65, s42
	s_add_i32 s61, s63, 0x2000
	s_add_u32 s28, s36, 0x10080
	s_addc_u32 s29, s37, 0
	s_add_i32 s62, s64, s42
	s_add_i32 s60, s62, 0x2000
	v_lshl_add_u64 v[212:213], s[40:41], 0, v[136:137]
	ds_read_b128 v[180:183], v147
	ds_read_b128 v[184:187], v147 offset:1024
	ds_read_b128 v[188:191], v147 offset:2048
	ds_read_b128 v[192:195], v147 offset:3072
	ds_read_b128 v[196:199], v147 offset:4096
	ds_read_b128 v[200:203], v147 offset:5120
	ds_read_b128 v[204:207], v147 offset:6144
	ds_read_b128 v[208:211], v147 offset:7168
	global_load_lds_dwordx4 v[212:213], off
	v_lshl_add_u64 v[212:213], s[40:41], 0, v[132:133]
	s_mov_b32 m0, s70
	s_nop 0
	global_load_lds_dwordx4 v[212:213], off
	s_waitcnt vmcnt(8)
	s_waitcnt lgkmcnt(0)
	s_barrier
	s_setprio 1
	s_waitcnt lgkmcnt(0)
	v_mfma_f32_16x16x32_bf16 v[124:127], v[148:151], v[180:183], v[124:127]
	v_mfma_f32_16x16x32_bf16 v[120:123], v[156:159], v[180:183], v[120:123]
	v_mfma_f32_16x16x32_bf16 v[116:119], v[148:151], v[188:191], v[116:119]
	v_mfma_f32_16x16x32_bf16 v[112:115], v[156:159], v[188:191], v[112:115]
	v_mfma_f32_16x16x32_bf16 v[100:103], v[148:151], v[196:199], v[100:103]
	v_mfma_f32_16x16x32_bf16 v[96:99], v[156:159], v[196:199], v[96:99]
	v_mfma_f32_16x16x32_bf16 v[84:87], v[148:151], v[204:207], v[84:87]
	v_mfma_f32_16x16x32_bf16 v[80:83], v[156:159], v[204:207], v[80:83]
	v_mfma_f32_16x16x32_bf16 v[124:127], v[152:155], v[184:187], v[124:127]
	v_mfma_f32_16x16x32_bf16 v[120:123], v[160:163], v[184:187], v[120:123]
	v_mfma_f32_16x16x32_bf16 v[116:119], v[152:155], v[192:195], v[116:119]
	v_mfma_f32_16x16x32_bf16 v[112:115], v[160:163], v[192:195], v[112:115]
	v_mfma_f32_16x16x32_bf16 v[100:103], v[152:155], v[200:203], v[100:103]
	v_mfma_f32_16x16x32_bf16 v[96:99], v[160:163], v[200:203], v[96:99]
	v_mfma_f32_16x16x32_bf16 v[84:87], v[152:155], v[208:211], v[84:87]
	v_mfma_f32_16x16x32_bf16 v[80:83], v[160:163], v[208:211], v[80:83]
	s_setprio 0
	s_setprio 1
	v_mfma_f32_16x16x32_bf16 v[108:111], v[164:167], v[180:183], v[108:111]
	v_mfma_f32_16x16x32_bf16 v[104:107], v[172:175], v[180:183], v[104:107]
	v_mfma_f32_16x16x32_bf16 v[92:95], v[164:167], v[188:191], v[92:95]
	v_mfma_f32_16x16x32_bf16 v[88:91], v[172:175], v[188:191], v[88:91]
	v_mfma_f32_16x16x32_bf16 v[76:79], v[164:167], v[196:199], v[76:79]
	v_mfma_f32_16x16x32_bf16 v[72:75], v[172:175], v[196:199], v[72:75]
	v_mfma_f32_16x16x32_bf16 v[68:71], v[164:167], v[204:207], v[68:71]
	v_mfma_f32_16x16x32_bf16 v[64:67], v[172:175], v[204:207], v[64:67]
	s_setprio 2
	s_barrier
	v_mfma_f32_16x16x32_bf16 v[108:111], v[168:171], v[184:187], v[108:111]
	v_mfma_f32_16x16x32_bf16 v[104:107], v[176:179], v[184:187], v[104:107]
	v_mfma_f32_16x16x32_bf16 v[92:95], v[168:171], v[192:195], v[92:95]
	v_mfma_f32_16x16x32_bf16 v[88:91], v[176:179], v[192:195], v[88:91]
	v_mfma_f32_16x16x32_bf16 v[76:79], v[168:171], v[200:203], v[76:79]
	v_mfma_f32_16x16x32_bf16 v[72:75], v[176:179], v[200:203], v[72:75]
	v_mfma_f32_16x16x32_bf16 v[68:71], v[168:171], v[208:211], v[68:71]
	v_mfma_f32_16x16x32_bf16 v[64:67], v[176:179], v[208:211], v[64:67]
	s_setprio 0
	s_mov_b32 m0, s69
	v_lshl_add_u64 v[212:213], s[36:37], 0, v[134:135]
	ds_read_b128 v[180:183], v147 offset:16384
	ds_read_b128 v[184:187], v147 offset:17408
	ds_read_b128 v[188:191], v147 offset:18432
	ds_read_b128 v[192:195], v147 offset:19456
	ds_read_b128 v[196:199], v147 offset:20480
	ds_read_b128 v[200:203], v147 offset:21504
	ds_read_b128 v[204:207], v147 offset:22528
	ds_read_b128 v[208:211], v147 offset:23552
	global_load_lds_dwordx4 v[212:213], off
	v_lshl_add_u64 v[214:215], s[36:37], 0, v[130:131]
	s_mov_b32 m0, s66
	v_lshl_add_u64 v[216:217], s[38:39], 0, v[134:135]
	global_load_lds_dwordx4 v[214:215], off
	s_mov_b32 m0, s68
	v_lshl_add_u64 v[218:219], s[34:35], 0, v[132:133]
	global_load_lds_dwordx4 v[216:217], off
	v_lshl_add_u64 v[216:217], s[38:39], 0, v[130:131]
	s_mov_b32 m0, s67
	s_nop 0
	global_load_lds_dwordx4 v[216:217], off
	v_lshl_add_u64 v[216:217], s[34:35], 0, v[136:137]
	s_mov_b32 m0, s17
	s_nop 0
	global_load_lds_dwordx4 v[216:217], off
	s_mov_b32 m0, s47
	s_nop 0
	global_load_lds_dwordx4 v[218:219], off
	s_waitcnt vmcnt(8)
	s_waitcnt lgkmcnt(0)
	s_barrier
; #define PG8_STAGE(bufoff, gbase, voff) do { _Pragma("unroll") for (int _i = 0; _i < 2; ++_i) \
;         __builtin_amdgcn_global_load_lds((const unsigned*)((const char*)(gbase) + (voff)[_i]), (PG8_LAS unsigned*)(lds + (bufoff) + ldsw + _i * 8192), 16, 0, 0); } while (0)
; #define PG8_LDA(dst, b, h) do { _Pragma("unroll") for (int m = 0; m < 4; ++m) _Pragma("unroll") for (int k = 0; k < 2; ++k) dst[m][k] = *(const PG8_LAS bf16x8*)(lds + PG8_SA(b, h) + aoff + m * 2048 + k * 1024); } while (0)
; #define PG8_LDB(dst, b, h) do { _Pragma("unroll") for (int n = 0; n < 2; ++n) _Pragma("unroll") for (int k = 0; k < 2; ++k) dst[n][k] = *(const PG8_LAS bf16x8*)(lds + PG8_SB(b, h) + boff + n * 2048 + k * 1024); } while (0)
; #define PG8_BAR __builtin_amdgcn_s_barrier()
; template <class Epi, class Sched, bool ALIGN_EPI = false, bool SP2 = false>
; __device__ __forceinline__ void gemm_phase(PG8_LAS unsigned char* lds, const Gemm g, const Sched& S, const Epi& E) {
;     ...
;             const bool last = (t == nt - 2);
;             const char* a1 = cA + (size_t)(t + 1) * kstep;
;             const char* a2 = last ? nA : cA + (size_t)(t + 2) * kstep; const char* b2 = last ? nB : cB + (size_t)(t + 2) * kstep;
;             const char* a3 = a2 + kstep; const char* b3 = b2 + kstep;
;             if (last && has_next) S.a_ready(nxt);
;             if constexpr (SP2) {
;             PG8_LDB(B0, 0, 0); PG8_LDB(B1, 0, 1); PG8_SCHED; PG8_LDA(At, 0, 0); PG8_STAGE(PG8_SA(1, 1), a1 + hstep, voffA);
;             PG8_WAIT_V(8); PG8_WAIT_L(0); PG8_BAR; PG8_MMA(0, 0, At, B0); PG8_MMA(0, 1, At, B1); PG8_BAR; PG8_SCHED;
;             PG8_LDA(At, 0, 1); PG8_STAGE(PG8_SB(0, 0), b2, voffB); PG8_STAGE(PG8_SB(0, 1), b2 + hstep, voffB); PG8_STAGE(PG8_SA(0, 0), a2, voffA);
;             PG8_WAIT_V(8); PG8_WAIT_L(0); PG8_BAR; PG8_MMA(1, 0, At, B0); PG8_MMA(1, 1, At, B1); PG8_BAR; PG8_SCHED;
;             PG8_LDB(B0, 1, 0); PG8_LDB(B1, 1, 1); PG8_SCHED; PG8_LDA(At, 1, 0); PG8_STAGE(PG8_SA(0, 1), a2 + hstep, voffA);
;             PG8_WAIT_V(8); PG8_WAIT_L(0); PG8_BAR; PG8_MMA(0, 0, At, B0); PG8_MMA(0, 1, At, B1); PG8_BAR; PG8_SCHED;
;             PG8_LDA(At, 1, 1); PG8_STAGE(PG8_SB(1, 0), b3, voffB); PG8_STAGE(PG8_SB(1, 1), b3 + hstep, voffB); PG8_STAGE(PG8_SA(1, 0), a3, voffA);
;             PG8_WAIT_V(8); PG8_WAIT_L(0); PG8_BAR; PG8_MMA(1, 0, At, B0); PG8_MMA(1, 1, At, B1); PG8_BAR; PG8_SCHED;
	s_setprio 1
	s_waitcnt lgkmcnt(0)
	v_mfma_f32_16x16x32_bf16 v[60:63], v[148:151], v[180:183], v[60:63]
	v_mfma_f32_16x16x32_bf16 v[56:59], v[156:159], v[180:183], v[56:59]
	v_mfma_f32_16x16x32_bf16 v[52:55], v[148:151], v[188:191], v[52:55]
	v_mfma_f32_16x16x32_bf16 v[48:51], v[156:159], v[188:191], v[48:51]
	v_mfma_f32_16x16x32_bf16 v[36:39], v[148:151], v[196:199], v[36:39]
	v_mfma_f32_16x16x32_bf16 v[32:35], v[156:159], v[196:199], v[32:35]
	v_mfma_f32_16x16x32_bf16 v[20:23], v[148:151], v[204:207], v[20:23]
	v_mfma_f32_16x16x32_bf16 v[16:19], v[156:159], v[204:207], v[16:19]
	v_mfma_f32_16x16x32_bf16 v[60:63], v[152:155], v[184:187], v[60:63]
	v_mfma_f32_16x16x32_bf16 v[56:59], v[160:163], v[184:187], v[56:59]
	v_mfma_f32_16x16x32_bf16 v[52:55], v[152:155], v[192:195], v[52:55]
	v_mfma_f32_16x16x32_bf16 v[48:51], v[160:163], v[192:195], v[48:51]
	v_mfma_f32_16x16x32_bf16 v[36:39], v[152:155], v[200:203], v[36:39]
	v_mfma_f32_16x16x32_bf16 v[32:35], v[160:163], v[200:203], v[32:35]
	v_mfma_f32_16x16x32_bf16 v[20:23], v[152:155], v[208:211], v[20:23]
	v_mfma_f32_16x16x32_bf16 v[16:19], v[160:163], v[208:211], v[16:19]
	s_setprio 0
	s_setprio 1
	v_mfma_f32_16x16x32_bf16 v[44:47], v[164:167], v[180:183], v[44:47]
	v_mfma_f32_16x16x32_bf16 v[40:43], v[172:175], v[180:183], v[40:43]
	v_mfma_f32_16x16x32_bf16 v[28:31], v[164:167], v[188:191], v[28:31]
	v_mfma_f32_16x16x32_bf16 v[24:27], v[172:175], v[188:191], v[24:27]
	v_mfma_f32_16x16x32_bf16 v[12:15], v[164:167], v[196:199], v[12:15]
	v_mfma_f32_16x16x32_bf16 v[8:11], v[172:175], v[196:199], v[8:11]
	v_mfma_f32_16x16x32_bf16 v[4:7], v[164:167], v[204:207], v[4:7]
	v_mfma_f32_16x16x32_bf16 v[0:3], v[172:175], v[204:207], v[0:3]
	s_setprio 2
	s_barrier
	v_mfma_f32_16x16x32_bf16 v[44:47], v[168:171], v[184:187], v[44:47]
	v_mfma_f32_16x16x32_bf16 v[40:43], v[176:179], v[184:187], v[40:43]
	v_mfma_f32_16x16x32_bf16 v[28:31], v[168:171], v[192:195], v[28:31]
	v_mfma_f32_16x16x32_bf16 v[24:27], v[176:179], v[192:195], v[24:27]
	v_mfma_f32_16x16x32_bf16 v[12:15], v[168:171], v[200:203], v[12:15]
	v_mfma_f32_16x16x32_bf16 v[8:11], v[176:179], v[200:203], v[8:11]
	v_mfma_f32_16x16x32_bf16 v[4:7], v[168:171], v[208:211], v[4:7]
	v_mfma_f32_16x16x32_bf16 v[0:3], v[176:179], v[208:211], v[0:3]
	s_setprio 0
	v_add_u32_e32 v160, s65, v143
	v_add_u32_e32 v176, s64, v143
	ds_read_b128 v[148:151], v160
	ds_read_b128 v[152:155], v160 offset:1024
	ds_read_b128 v[156:159], v160 offset:2048
	ds_read_b128 v[160:163], v160 offset:3072
	ds_read_b128 v[164:167], v176
	ds_read_b128 v[168:171], v176 offset:1024
	ds_read_b128 v[172:175], v176 offset:2048
	ds_read_b128 v[176:179], v176 offset:3072
	s_mov_b32 m0, s48
	v_lshl_add_u64 v[220:221], s[30:31], 0, v[136:137]
	ds_read_b128 v[180:183], v147 offset:32768
	ds_read_b128 v[184:187], v147 offset:33792
	ds_read_b128 v[188:191], v147 offset:34816
	ds_read_b128 v[192:195], v147 offset:35840
	ds_read_b128 v[196:199], v147 offset:36864
	ds_read_b128 v[200:203], v147 offset:37888
	ds_read_b128 v[204:207], v147 offset:38912
	ds_read_b128 v[208:211], v147 offset:39936
	global_load_lds_dwordx4 v[220:221], off
	v_lshl_add_u64 v[220:221], s[30:31], 0, v[132:133]
	s_mov_b32 m0, s49
	s_nop 0
	global_load_lds_dwordx4 v[220:221], off
	s_waitcnt vmcnt(8)
	s_waitcnt lgkmcnt(0)
	s_barrier
	s_setprio 1
	s_waitcnt lgkmcnt(0)
	v_mfma_f32_16x16x32_bf16 v[124:127], v[148:151], v[180:183], v[124:127]
	v_mfma_f32_16x16x32_bf16 v[120:123], v[156:159], v[180:183], v[120:123]
	v_mfma_f32_16x16x32_bf16 v[116:119], v[148:151], v[188:191], v[116:119]
	v_mfma_f32_16x16x32_bf16 v[112:115], v[156:159], v[188:191], v[112:115]
	v_mfma_f32_16x16x32_bf16 v[100:103], v[148:151], v[196:199], v[100:103]
	v_mfma_f32_16x16x32_bf16 v[96:99], v[156:159], v[196:199], v[96:99]
	v_mfma_f32_16x16x32_bf16 v[84:87], v[148:151], v[204:207], v[84:87]
	v_mfma_f32_16x16x32_bf16 v[80:83], v[156:159], v[204:207], v[80:83]
	v_mfma_f32_16x16x32_bf16 v[124:127], v[152:155], v[184:187], v[124:127]
	v_mfma_f32_16x16x32_bf16 v[120:123], v[160:163], v[184:187], v[120:123]
	v_mfma_f32_16x16x32_bf16 v[116:119], v[152:155], v[192:195], v[116:119]
	v_mfma_f32_16x16x32_bf16 v[112:115], v[160:163], v[192:195], v[112:115]
	v_mfma_f32_16x16x32_bf16 v[100:103], v[152:155], v[200:203], v[100:103]
	v_mfma_f32_16x16x32_bf16 v[96:99], v[160:163], v[200:203], v[96:99]
	v_mfma_f32_16x16x32_bf16 v[84:87], v[152:155], v[208:211], v[84:87]
	v_mfma_f32_16x16x32_bf16 v[80:83], v[160:163], v[208:211], v[80:83]
	s_setprio 0
	s_setprio 1
	v_mfma_f32_16x16x32_bf16 v[108:111], v[164:167], v[180:183], v[108:111]
	v_mfma_f32_16x16x32_bf16 v[104:107], v[172:175], v[180:183], v[104:107]
	v_mfma_f32_16x16x32_bf16 v[92:95], v[164:167], v[188:191], v[92:95]
	v_mfma_f32_16x16x32_bf16 v[88:91], v[172:175], v[188:191], v[88:91]
	v_mfma_f32_16x16x32_bf16 v[76:79], v[164:167], v[196:199], v[76:79]
	v_mfma_f32_16x16x32_bf16 v[72:75], v[172:175], v[196:199], v[72:75]
	v_mfma_f32_16x16x32_bf16 v[68:71], v[164:167], v[204:207], v[68:71]
	v_mfma_f32_16x16x32_bf16 v[64:67], v[172:175], v[204:207], v[64:67]
	s_setprio 2
	s_barrier
; #define PG8_STAGE(bufoff, gbase, voff) do { _Pragma("unroll") for (int _i = 0; _i < 2; ++_i) \
;         __builtin_amdgcn_global_load_lds((const unsigned*)((const char*)(gbase) + (voff)[_i]), (PG8_LAS unsigned*)(lds + (bufoff) + ldsw + _i * 8192), 16, 0, 0); } while (0)
; #define PG8_LDA(dst, b, h) do { _Pragma("unroll") for (int m = 0; m < 4; ++m) _Pragma("unroll") for (int k = 0; k < 2; ++k) dst[m][k] = *(const PG8_LAS bf16x8*)(lds + PG8_SA(b, h) + aoff + m * 2048 + k * 1024); } while (0)
; #define PG8_WAIT_V(n) asm volatile("s_waitcnt vmcnt(" #n ")" ::: "memory")
; #define PG8_WAIT_L(n) asm volatile("s_waitcnt lgkmcnt(" #n ")" ::: "memory")
; template <class Epi, class Sched, bool ALIGN_EPI = false, bool SP2 = false>
; __device__ __forceinline__ void gemm_phase(PG8_LAS unsigned char* lds, const Gemm g, const Sched& S, const Epi& E) {
;     ...
;         for (int t = 0; t < nt; t += 2) {
;             const bool last = (t == nt - 2);
;             const char* a1 = cA + (size_t)(t + 1) * kstep;
;             const char* a2 = last ? nA : cA + (size_t)(t + 2) * kstep; const char* b2 = last ? nB : cB + (size_t)(t + 2) * kstep;
;             const char* a3 = a2 + kstep; const char* b3 = b2 + kstep;
;             if (last && has_next) S.a_ready(nxt);
;             if constexpr (SP2) {
;             PG8_LDB(B0, 0, 0); PG8_LDB(B1, 0, 1); PG8_SCHED; PG8_LDA(At, 0, 0); PG8_STAGE(PG8_SA(1, 1), a1 + hstep, voffA);
;             PG8_WAIT_V(8); PG8_WAIT_L(0); PG8_BAR; PG8_MMA(0, 0, At, B0); PG8_MMA(0, 1, At, B1); PG8_BAR; PG8_SCHED;
;             PG8_LDA(At, 0, 1); PG8_STAGE(PG8_SB(0, 0), b2, voffB); PG8_STAGE(PG8_SB(0, 1), b2 + hstep, voffB); PG8_STAGE(PG8_SA(0, 0), a2, voffA);
;             PG8_WAIT_V(8); PG8_WAIT_L(0); PG8_BAR; PG8_MMA(1, 0, At, B0); PG8_MMA(1, 1, At, B1); PG8_BAR; PG8_SCHED;
;             PG8_LDB(B0, 1, 0); PG8_LDB(B1, 1, 1); PG8_SCHED; PG8_LDA(At, 1, 0); PG8_STAGE(PG8_SA(0, 1), a2 + hstep, voffA);
;             PG8_WAIT_V(8); PG8_WAIT_L(0); PG8_BAR; PG8_MMA(0, 0, At, B0); PG8_MMA(0, 1, At, B1); PG8_BAR; PG8_SCHED;
;             PG8_LDA(At, 1, 1); PG8_STAGE(PG8_SB(1, 0), b3, voffB); PG8_STAGE(PG8_SB(1, 1), b3 + hstep, voffB); PG8_STAGE(PG8_SA(1, 0), a3, voffA);
;             PG8_WAIT_V(8); PG8_WAIT_L(0); PG8_BAR; PG8_MMA(1, 0, At, B0); PG8_MMA(1, 1, At, B1); PG8_BAR; PG8_SCHED;
;     ...
;         if constexpr (ALIGN_EPI) { if (wr == 0) PG8_BAR; }
	v_mfma_f32_16x16x32_bf16 v[108:111], v[168:171], v[184:187], v[108:111]
	v_mfma_f32_16x16x32_bf16 v[104:107], v[176:179], v[184:187], v[104:107]
	v_mfma_f32_16x16x32_bf16 v[92:95], v[168:171], v[192:195], v[92:95]
	v_mfma_f32_16x16x32_bf16 v[88:91], v[176:179], v[192:195], v[88:91]
	v_mfma_f32_16x16x32_bf16 v[76:79], v[168:171], v[200:203], v[76:79]
	v_mfma_f32_16x16x32_bf16 v[72:75], v[176:179], v[200:203], v[72:75]
	v_mfma_f32_16x16x32_bf16 v[68:71], v[168:171], v[208:211], v[68:71]
	v_mfma_f32_16x16x32_bf16 v[64:67], v[176:179], v[208:211], v[64:67]
	s_setprio 0
	s_mov_b32 m0, s63
	v_lshl_add_u64 v[212:213], v[212:213], 0, s[4:5]
	ds_read_b128 v[180:183], v147 offset:49152
	ds_read_b128 v[184:187], v147 offset:50176
	ds_read_b128 v[188:191], v147 offset:51200
	ds_read_b128 v[192:195], v147 offset:52224
	ds_read_b128 v[196:199], v147 offset:53248
	ds_read_b128 v[200:203], v147 offset:54272
	ds_read_b128 v[204:207], v147 offset:55296
	ds_read_b128 v[208:211], v147 offset:56320
	global_load_lds_dwordx4 v[212:213], off
	v_lshl_add_u64 v[212:213], v[214:215], 0, s[4:5]
	s_mov_b32 m0, s61
	s_nop 0
	global_load_lds_dwordx4 v[212:213], off
	v_lshl_add_u64 v[212:213], s[28:29], 0, v[134:135]
	s_mov_b32 m0, s62
	s_nop 0
	global_load_lds_dwordx4 v[212:213], off
	v_lshl_add_u64 v[212:213], s[28:29], 0, v[130:131]
	s_mov_b32 m0, s60
	s_nop 0
	global_load_lds_dwordx4 v[212:213], off
	v_lshl_add_u64 v[212:213], v[216:217], 0, s[4:5]
	s_mov_b32 m0, s52
	s_nop 0
	global_load_lds_dwordx4 v[212:213], off
	v_lshl_add_u64 v[212:213], v[218:219], 0, s[4:5]
	s_mov_b32 m0, s53
	s_nop 0
	global_load_lds_dwordx4 v[212:213], off
	s_waitcnt vmcnt(8)
	s_waitcnt lgkmcnt(0)
	s_barrier
	s_setprio 1
	s_waitcnt lgkmcnt(0)
	v_mfma_f32_16x16x32_bf16 v[60:63], v[148:151], v[180:183], v[60:63]
	v_mfma_f32_16x16x32_bf16 v[56:59], v[156:159], v[180:183], v[56:59]
	v_mfma_f32_16x16x32_bf16 v[52:55], v[148:151], v[188:191], v[52:55]
	v_mfma_f32_16x16x32_bf16 v[48:51], v[156:159], v[188:191], v[48:51]
	v_mfma_f32_16x16x32_bf16 v[36:39], v[148:151], v[196:199], v[36:39]
	v_mfma_f32_16x16x32_bf16 v[32:35], v[156:159], v[196:199], v[32:35]
	v_mfma_f32_16x16x32_bf16 v[20:23], v[148:151], v[204:207], v[20:23]
	v_mfma_f32_16x16x32_bf16 v[16:19], v[156:159], v[204:207], v[16:19]
	v_mfma_f32_16x16x32_bf16 v[60:63], v[152:155], v[184:187], v[60:63]
	v_mfma_f32_16x16x32_bf16 v[56:59], v[160:163], v[184:187], v[56:59]
	v_mfma_f32_16x16x32_bf16 v[52:55], v[152:155], v[192:195], v[52:55]
	v_mfma_f32_16x16x32_bf16 v[48:51], v[160:163], v[192:195], v[48:51]
	v_mfma_f32_16x16x32_bf16 v[36:39], v[152:155], v[200:203], v[36:39]
	v_mfma_f32_16x16x32_bf16 v[32:35], v[160:163], v[200:203], v[32:35]
	v_mfma_f32_16x16x32_bf16 v[20:23], v[152:155], v[208:211], v[20:23]
	v_mfma_f32_16x16x32_bf16 v[16:19], v[160:163], v[208:211], v[16:19]
	s_setprio 0
	s_setprio 1
	v_mfma_f32_16x16x32_bf16 v[44:47], v[164:167], v[180:183], v[44:47]
	v_mfma_f32_16x16x32_bf16 v[40:43], v[172:175], v[180:183], v[40:43]
	v_mfma_f32_16x16x32_bf16 v[28:31], v[164:167], v[188:191], v[28:31]
	v_mfma_f32_16x16x32_bf16 v[24:27], v[172:175], v[188:191], v[24:27]
	v_mfma_f32_16x16x32_bf16 v[12:15], v[164:167], v[196:199], v[12:15]
	v_mfma_f32_16x16x32_bf16 v[8:11], v[172:175], v[196:199], v[8:11]
	v_mfma_f32_16x16x32_bf16 v[4:7], v[164:167], v[204:207], v[4:7]
	v_mfma_f32_16x16x32_bf16 v[0:3], v[172:175], v[204:207], v[0:3]
	s_setprio 2
	s_barrier
	v_mfma_f32_16x16x32_bf16 v[44:47], v[168:171], v[184:187], v[44:47]
	v_mfma_f32_16x16x32_bf16 v[40:43], v[176:179], v[184:187], v[40:43]
	v_mfma_f32_16x16x32_bf16 v[28:31], v[168:171], v[192:195], v[28:31]
	v_mfma_f32_16x16x32_bf16 v[24:27], v[176:179], v[192:195], v[24:27]
	v_mfma_f32_16x16x32_bf16 v[12:15], v[168:171], v[200:203], v[12:15]
	v_mfma_f32_16x16x32_bf16 v[8:11], v[176:179], v[200:203], v[8:11]
	v_mfma_f32_16x16x32_bf16 v[4:7], v[168:171], v[208:211], v[4:7]
	v_mfma_f32_16x16x32_bf16 v[0:3], v[176:179], v[208:211], v[0:3]
	s_setprio 0
	s_movk_i32 s30, 0x100
	s_andn2_b64 vcc, exec, s[26:27]
	s_mov_b64 s[28:29], -1
	s_mov_b64 s[26:27], 0
	s_cbranch_vccz .LBB0_835
	s_and_b64 vcc, exec, s[10:11]
	s_cbranch_vccz .LBB0_838
	s_barrier

; #define PG8_STAGE(bufoff, gbase, voff) do { _Pragma("unroll") for (int _i = 0; _i < 2; ++_i) \
;         __builtin_amdgcn_global_load_lds((const unsigned*)((const char*)(gbase) + (voff)[_i]), (PG8_LAS unsigned*)(lds + (bufoff) + ldsw + _i * 8192), 16, 0, 0); } while (0)
; #define PG8_LDA(dst, b, h) do { _Pragma("unroll") for (int m = 0; m < 4; ++m) _Pragma("unroll") for (int k = 0; k < 2; ++k) dst[m][k] = *(const PG8_LAS bf16x8*)(lds + PG8_SA(b, h) + aoff + m * 2048 + k * 1024); } while (0)
; #define PG8_LDB(dst, b, h) do { _Pragma("unroll") for (int n = 0; n < 2; ++n) _Pragma("unroll") for (int k = 0; k < 2; ++k) dst[n][k] = *(const PG8_LAS bf16x8*)(lds + PG8_SB(b, h) + boff + n * 2048 + k * 1024); } while (0)
; #define PG8_BAR __builtin_amdgcn_s_barrier()
; template <class Epi, class Sched, bool ALIGN_EPI = false, bool SP2 = false>
; __device__ __forceinline__ void gemm_phase(PG8_LAS unsigned char* lds, const Gemm g, const Sched& S, const Epi& E) {
;     ...
;             const bool last = (t == nt - 2);
;             const char* a1 = cA + (size_t)(t + 1) * kstep;
;             const char* a2 = last ? nA : cA + (size_t)(t + 2) * kstep; const char* b2 = last ? nB : cB + (size_t)(t + 2) * kstep;
;             const char* a3 = a2 + kstep; const char* b3 = b2 + kstep;
;             if (last && has_next) S.a_ready(nxt);
;             if constexpr (SP2) {
;             PG8_LDB(B0, 0, 0); PG8_LDB(B1, 0, 1); PG8_SCHED; PG8_LDA(At, 0, 0); PG8_STAGE(PG8_SA(1, 1), a1 + hstep, voffA);
;             PG8_WAIT_V(8); PG8_WAIT_L(0); PG8_BAR; PG8_MMA(0, 0, At, B0); PG8_MMA(0, 1, At, B1); PG8_BAR; PG8_SCHED;
;             PG8_LDA(At, 0, 1); PG8_STAGE(PG8_SB(0, 0), b2, voffB); PG8_STAGE(PG8_SB(0, 1), b2 + hstep, voffB); PG8_STAGE(PG8_SA(0, 0), a2, voffA);
;             PG8_WAIT_V(8); PG8_WAIT_L(0); PG8_BAR; PG8_MMA(1, 0, At, B0); PG8_MMA(1, 1, At, B1); PG8_BAR; PG8_SCHED;
;             PG8_LDB(B0, 1, 0); PG8_LDB(B1, 1, 1); PG8_SCHED; PG8_LDA(At, 1, 0); PG8_STAGE(PG8_SA(0, 1), a2 + hstep, voffA);
;             PG8_WAIT_V(8); PG8_WAIT_L(0); PG8_BAR; PG8_MMA(0, 0, At, B0); PG8_MMA(0, 1, At, B1); PG8_BAR; PG8_SCHED;
;             PG8_LDA(At, 1, 1); PG8_STAGE(PG8_SB(1, 0), b3, voffB); PG8_STAGE(PG8_SB(1, 1), b3 + hstep, voffB); PG8_STAGE(PG8_SA(1, 0), a3, voffA);
;             PG8_WAIT_V(8); PG8_WAIT_L(0); PG8_BAR; PG8_MMA(1, 0, At, B0); PG8_MMA(1, 1, At, B1); PG8_BAR; PG8_SCHED;
.LBB0_966:
	ds_read_b128 v[146:149], v153
	ds_read_b128 v[156:159], v153 offset:1024
	ds_read_b128 v[160:163], v153 offset:2048
	ds_read_b128 v[164:167], v153 offset:3072
	ds_read_b128 v[168:171], v154
	ds_read_b128 v[172:175], v154 offset:1024
	ds_read_b128 v[176:179], v154 offset:2048
	ds_read_b128 v[180:183], v154 offset:3072
	s_add_u32 s24, s22, 0xfff80080
	s_addc_u32 s25, s23, -1
	s_cmp_eq_u32 s52, 28
	s_cselect_b32 s27, s15, s25
	s_cselect_b32 s26, s45, s24
	s_cselect_b32 s25, s13, s51
	s_cselect_b32 s24, s46, s47
	v_lshl_add_u64 v[216:217], s[22:23], 0, v[138:139]
	s_add_i32 m0, s21, 0xc000
	ds_read_b128 v[184:187], v155
	ds_read_b128 v[188:191], v155 offset:1024
	ds_read_b128 v[192:195], v155 offset:2048
	ds_read_b128 v[196:199], v155 offset:3072
	ds_read_b128 v[200:203], v155 offset:4096
	ds_read_b128 v[204:207], v155 offset:5120
	ds_read_b128 v[208:211], v155 offset:6144
	ds_read_b128 v[212:215], v155 offset:7168
	global_load_lds_dwordx4 v[216:217], off
	v_lshl_add_u64 v[216:217], s[22:23], 0, v[140:141]
	s_add_i32 m0, s21, 0xe000
	s_nop 0
	global_load_lds_dwordx4 v[216:217], off
	s_waitcnt vmcnt(8)
	s_waitcnt lgkmcnt(0)
	s_barrier
	s_setprio 1
	s_waitcnt lgkmcnt(0)
	v_mfma_f32_16x16x32_bf16 v[124:127], v[146:149], v[184:187], v[124:127]
	v_mfma_f32_16x16x32_bf16 v[116:119], v[160:163], v[184:187], v[116:119]
	v_mfma_f32_16x16x32_bf16 v[108:111], v[146:149], v[192:195], v[108:111]
	v_mfma_f32_16x16x32_bf16 v[100:103], v[160:163], v[192:195], v[100:103]
	v_mfma_f32_16x16x32_bf16 v[92:95], v[146:149], v[200:203], v[92:95]
	v_mfma_f32_16x16x32_bf16 v[84:87], v[160:163], v[200:203], v[84:87]
	v_mfma_f32_16x16x32_bf16 v[76:79], v[146:149], v[208:211], v[76:79]
	v_mfma_f32_16x16x32_bf16 v[68:71], v[160:163], v[208:211], v[68:71]
	v_mfma_f32_16x16x32_bf16 v[124:127], v[156:159], v[188:191], v[124:127]
	v_mfma_f32_16x16x32_bf16 v[116:119], v[164:167], v[188:191], v[116:119]
	v_mfma_f32_16x16x32_bf16 v[108:111], v[156:159], v[196:199], v[108:111]
	v_mfma_f32_16x16x32_bf16 v[100:103], v[164:167], v[196:199], v[100:103]
	v_mfma_f32_16x16x32_bf16 v[92:95], v[156:159], v[204:207], v[92:95]
	v_mfma_f32_16x16x32_bf16 v[84:87], v[164:167], v[204:207], v[84:87]
	v_mfma_f32_16x16x32_bf16 v[76:79], v[156:159], v[212:215], v[76:79]
	v_mfma_f32_16x16x32_bf16 v[68:71], v[164:167], v[212:215], v[68:71]
	s_setprio 0
	s_setprio 1
	v_mfma_f32_16x16x32_bf16 v[120:123], v[168:171], v[184:187], v[120:123]
	v_mfma_f32_16x16x32_bf16 v[112:115], v[176:179], v[184:187], v[112:115]
	v_mfma_f32_16x16x32_bf16 v[104:107], v[168:171], v[192:195], v[104:107]
	v_mfma_f32_16x16x32_bf16 v[96:99], v[176:179], v[192:195], v[96:99]
	v_mfma_f32_16x16x32_bf16 v[88:91], v[168:171], v[200:203], v[88:91]
	v_mfma_f32_16x16x32_bf16 v[80:83], v[176:179], v[200:203], v[80:83]
	v_mfma_f32_16x16x32_bf16 v[72:75], v[168:171], v[208:211], v[72:75]
	v_mfma_f32_16x16x32_bf16 v[64:67], v[176:179], v[208:211], v[64:67]
	s_setprio 2
	s_barrier
	v_mfma_f32_16x16x32_bf16 v[120:123], v[172:175], v[188:191], v[120:123]
	v_mfma_f32_16x16x32_bf16 v[112:115], v[180:183], v[188:191], v[112:115]
	v_mfma_f32_16x16x32_bf16 v[104:107], v[172:175], v[196:199], v[104:107]
	v_mfma_f32_16x16x32_bf16 v[96:99], v[180:183], v[196:199], v[96:99]
	v_mfma_f32_16x16x32_bf16 v[88:91], v[172:175], v[204:207], v[88:91]
	v_mfma_f32_16x16x32_bf16 v[80:83], v[180:183], v[204:207], v[80:83]
	v_mfma_f32_16x16x32_bf16 v[72:75], v[172:175], v[212:215], v[72:75]
	v_mfma_f32_16x16x32_bf16 v[64:67], v[180:183], v[212:215], v[64:67]
	s_setprio 0
	s_add_i32 s53, s41, s28
	v_lshl_add_u64 v[216:217], s[24:25], 0, v[134:135]
	s_mov_b32 m0, s53
	ds_read_b128 v[184:187], v155 offset:16384
	ds_read_b128 v[188:191], v155 offset:17408
	ds_read_b128 v[192:195], v155 offset:18432
	ds_read_b128 v[196:199], v155 offset:19456
	ds_read_b128 v[200:203], v155 offset:20480
	ds_read_b128 v[204:207], v155 offset:21504
	ds_read_b128 v[208:211], v155 offset:22528
	ds_read_b128 v[212:215], v155 offset:23552
	global_load_lds_dwordx4 v[216:217], off
	s_add_i32 m0, s53, 0x2000
	s_add_u32 s54, s24, 0x80000
	v_lshl_add_u64 v[218:219], s[24:25], 0, v[130:131]
	s_addc_u32 s55, s25, 0
	s_add_i32 s53, s42, s28
	global_load_lds_dwordx4 v[218:219], off
	v_lshl_add_u64 v[220:221], s[54:55], 0, v[134:135]
	s_mov_b32 m0, s53
	v_lshl_add_u64 v[222:223], s[26:27], 0, v[132:133]
	global_load_lds_dwordx4 v[220:221], off
	v_lshl_add_u64 v[220:221], s[54:55], 0, v[130:131]
	s_add_i32 m0, s53, 0x2000
	s_nop 0
	global_load_lds_dwordx4 v[220:221], off
	v_lshl_add_u64 v[220:221], s[26:27], 0, v[136:137]
	s_mov_b32 m0, s21
	s_nop 0
	global_load_lds_dwordx4 v[220:221], off
	s_mov_b32 m0, s31
	s_nop 0
	global_load_lds_dwordx4 v[222:223], off
	s_waitcnt vmcnt(8)
	s_waitcnt lgkmcnt(0)
	s_barrier
	s_setprio 1
	s_waitcnt lgkmcnt(0)
	v_mfma_f32_16x16x32_bf16 v[60:63], v[146:149], v[184:187], v[60:63]
	v_mfma_f32_16x16x32_bf16 v[52:55], v[160:163], v[184:187], v[52:55]
	v_mfma_f32_16x16x32_bf16 v[44:47], v[146:149], v[192:195], v[44:47]
	v_mfma_f32_16x16x32_bf16 v[36:39], v[160:163], v[192:195], v[36:39]
	v_mfma_f32_16x16x32_bf16 v[28:31], v[146:149], v[200:203], v[28:31]
	v_mfma_f32_16x16x32_bf16 v[20:23], v[160:163], v[200:203], v[20:23]
	v_mfma_f32_16x16x32_bf16 v[12:15], v[146:149], v[208:211], v[12:15]
	v_mfma_f32_16x16x32_bf16 v[4:7], v[160:163], v[208:211], v[4:7]
	v_mfma_f32_16x16x32_bf16 v[60:63], v[156:159], v[188:191], v[60:63]
	v_mfma_f32_16x16x32_bf16 v[52:55], v[164:167], v[188:191], v[52:55]
	v_mfma_f32_16x16x32_bf16 v[44:47], v[156:159], v[196:199], v[44:47]
	v_mfma_f32_16x16x32_bf16 v[36:39], v[164:167], v[196:199], v[36:39]
	v_mfma_f32_16x16x32_bf16 v[28:31], v[156:159], v[204:207], v[28:31]
	v_mfma_f32_16x16x32_bf16 v[20:23], v[164:167], v[204:207], v[20:23]
	v_mfma_f32_16x16x32_bf16 v[12:15], v[156:159], v[212:215], v[12:15]
	v_mfma_f32_16x16x32_bf16 v[4:7], v[164:167], v[212:215], v[4:7]
	s_setprio 0
	s_setprio 1
	v_mfma_f32_16x16x32_bf16 v[56:59], v[168:171], v[184:187], v[56:59]
	v_mfma_f32_16x16x32_bf16 v[48:51], v[176:179], v[184:187], v[48:51]
	v_mfma_f32_16x16x32_bf16 v[40:43], v[168:171], v[192:195], v[40:43]
	v_mfma_f32_16x16x32_bf16 v[32:35], v[176:179], v[192:195], v[32:35]
	v_mfma_f32_16x16x32_bf16 v[24:27], v[168:171], v[200:203], v[24:27]
	v_mfma_f32_16x16x32_bf16 v[16:19], v[176:179], v[200:203], v[16:19]
	v_mfma_f32_16x16x32_bf16 v[8:11], v[168:171], v[208:211], v[8:11]
	v_mfma_f32_16x16x32_bf16 v[0:3], v[176:179], v[208:211], v[0:3]
	s_setprio 2
	s_barrier
; #define PG8_STAGE(bufoff, gbase, voff) do { _Pragma("unroll") for (int _i = 0; _i < 2; ++_i) \
;         __builtin_amdgcn_global_load_lds((const unsigned*)((const char*)(gbase) + (voff)[_i]), (PG8_LAS unsigned*)(lds + (bufoff) + ldsw + _i * 8192), 16, 0, 0); } while (0)
; #define PG8_LDA(dst, b, h) do { _Pragma("unroll") for (int m = 0; m < 4; ++m) _Pragma("unroll") for (int k = 0; k < 2; ++k) dst[m][k] = *(const PG8_LAS bf16x8*)(lds + PG8_SA(b, h) + aoff + m * 2048 + k * 1024); } while (0)
; #define PG8_LDB(dst, b, h) do { _Pragma("unroll") for (int n = 0; n < 2; ++n) _Pragma("unroll") for (int k = 0; k < 2; ++k) dst[n][k] = *(const PG8_LAS bf16x8*)(lds + PG8_SB(b, h) + boff + n * 2048 + k * 1024); } while (0)
; #define PG8_BAR __builtin_amdgcn_s_barrier()
; template <class Epi, class Sched, bool ALIGN_EPI = false, bool SP2 = false>
; __device__ __forceinline__ void gemm_phase(PG8_LAS unsigned char* lds, const Gemm g, const Sched& S, const Epi& E) {
;     ...
;             const bool last = (t == nt - 2);
;             const char* a1 = cA + (size_t)(t + 1) * kstep;
;             const char* a2 = last ? nA : cA + (size_t)(t + 2) * kstep; const char* b2 = last ? nB : cB + (size_t)(t + 2) * kstep;
;             const char* a3 = a2 + kstep; const char* b3 = b2 + kstep;
;             if (last && has_next) S.a_ready(nxt);
;             if constexpr (SP2) {
;             PG8_LDB(B0, 0, 0); PG8_LDB(B1, 0, 1); PG8_SCHED; PG8_LDA(At, 0, 0); PG8_STAGE(PG8_SA(1, 1), a1 + hstep, voffA);
;             PG8_WAIT_V(8); PG8_WAIT_L(0); PG8_BAR; PG8_MMA(0, 0, At, B0); PG8_MMA(0, 1, At, B1); PG8_BAR; PG8_SCHED;
;             PG8_LDA(At, 0, 1); PG8_STAGE(PG8_SB(0, 0), b2, voffB); PG8_STAGE(PG8_SB(0, 1), b2 + hstep, voffB); PG8_STAGE(PG8_SA(0, 0), a2, voffA);
;             PG8_WAIT_V(8); PG8_WAIT_L(0); PG8_BAR; PG8_MMA(1, 0, At, B0); PG8_MMA(1, 1, At, B1); PG8_BAR; PG8_SCHED;
;             PG8_LDB(B0, 1, 0); PG8_LDB(B1, 1, 1); PG8_SCHED; PG8_LDA(At, 1, 0); PG8_STAGE(PG8_SA(0, 1), a2 + hstep, voffA);
;             PG8_WAIT_V(8); PG8_WAIT_L(0); PG8_BAR; PG8_MMA(0, 0, At, B0); PG8_MMA(0, 1, At, B1); PG8_BAR; PG8_SCHED;
;             PG8_LDA(At, 1, 1); PG8_STAGE(PG8_SB(1, 0), b3, voffB); PG8_STAGE(PG8_SB(1, 1), b3 + hstep, voffB); PG8_STAGE(PG8_SA(1, 0), a3, voffA);
;             PG8_WAIT_V(8); PG8_WAIT_L(0); PG8_BAR; PG8_MMA(1, 0, At, B0); PG8_MMA(1, 1, At, B1); PG8_BAR; PG8_SCHED;
	v_mfma_f32_16x16x32_bf16 v[56:59], v[172:175], v[188:191], v[56:59]
	v_mfma_f32_16x16x32_bf16 v[48:51], v[180:183], v[188:191], v[48:51]
	v_mfma_f32_16x16x32_bf16 v[40:43], v[172:175], v[196:199], v[40:43]
	v_mfma_f32_16x16x32_bf16 v[32:35], v[180:183], v[196:199], v[32:35]
	v_mfma_f32_16x16x32_bf16 v[24:27], v[172:175], v[204:207], v[24:27]
	v_mfma_f32_16x16x32_bf16 v[16:19], v[180:183], v[204:207], v[16:19]
	v_mfma_f32_16x16x32_bf16 v[8:11], v[172:175], v[212:215], v[8:11]
	v_mfma_f32_16x16x32_bf16 v[0:3], v[180:183], v[212:215], v[0:3]
	s_setprio 0
	s_add_i32 s53, 0, 0x18000
	s_add_i32 s54, 0, 0x1c000
	v_add_u32_e32 v164, s53, v151
	v_add_u32_e32 v180, s54, v151
	ds_read_b128 v[146:149], v164
	ds_read_b128 v[156:159], v164 offset:1024
	ds_read_b128 v[160:163], v164 offset:2048
	ds_read_b128 v[164:167], v164 offset:3072
	ds_read_b128 v[168:171], v180
	ds_read_b128 v[172:175], v180 offset:1024
	ds_read_b128 v[176:179], v180 offset:2048
	ds_read_b128 v[180:183], v180 offset:3072
	s_add_u32 s26, s26, 0x80000
	s_addc_u32 s27, s27, 0
	s_mov_b32 m0, s34
	v_lshl_add_u64 v[224:225], s[26:27], 0, v[136:137]
	ds_read_b128 v[184:187], v155 offset:32768
	ds_read_b128 v[188:191], v155 offset:33792
	ds_read_b128 v[192:195], v155 offset:34816
	ds_read_b128 v[196:199], v155 offset:35840
	ds_read_b128 v[200:203], v155 offset:36864
	ds_read_b128 v[204:207], v155 offset:37888
	ds_read_b128 v[208:211], v155 offset:38912
	ds_read_b128 v[212:215], v155 offset:39936
	global_load_lds_dwordx4 v[224:225], off
	v_lshl_add_u64 v[224:225], s[26:27], 0, v[132:133]
	s_mov_b32 m0, s35
	s_nop 0
	global_load_lds_dwordx4 v[224:225], off
	s_waitcnt vmcnt(8)
	s_waitcnt lgkmcnt(0)
	s_barrier
	s_setprio 1
	s_waitcnt lgkmcnt(0)
	v_mfma_f32_16x16x32_bf16 v[124:127], v[146:149], v[184:187], v[124:127]
	v_mfma_f32_16x16x32_bf16 v[116:119], v[160:163], v[184:187], v[116:119]
	v_mfma_f32_16x16x32_bf16 v[108:111], v[146:149], v[192:195], v[108:111]
	v_mfma_f32_16x16x32_bf16 v[100:103], v[160:163], v[192:195], v[100:103]
	v_mfma_f32_16x16x32_bf16 v[92:95], v[146:149], v[200:203], v[92:95]
	v_mfma_f32_16x16x32_bf16 v[84:87], v[160:163], v[200:203], v[84:87]
	v_mfma_f32_16x16x32_bf16 v[76:79], v[146:149], v[208:211], v[76:79]
	v_mfma_f32_16x16x32_bf16 v[68:71], v[160:163], v[208:211], v[68:71]
	v_mfma_f32_16x16x32_bf16 v[124:127], v[156:159], v[188:191], v[124:127]
	v_mfma_f32_16x16x32_bf16 v[116:119], v[164:167], v[188:191], v[116:119]
	v_mfma_f32_16x16x32_bf16 v[108:111], v[156:159], v[196:199], v[108:111]
	v_mfma_f32_16x16x32_bf16 v[100:103], v[164:167], v[196:199], v[100:103]
	v_mfma_f32_16x16x32_bf16 v[92:95], v[156:159], v[204:207], v[92:95]
	v_mfma_f32_16x16x32_bf16 v[84:87], v[164:167], v[204:207], v[84:87]
	v_mfma_f32_16x16x32_bf16 v[76:79], v[156:159], v[212:215], v[76:79]
	v_mfma_f32_16x16x32_bf16 v[68:71], v[164:167], v[212:215], v[68:71]
	s_setprio 0
	s_setprio 1
	v_mfma_f32_16x16x32_bf16 v[120:123], v[168:171], v[184:187], v[120:123]
	v_mfma_f32_16x16x32_bf16 v[112:115], v[176:179], v[184:187], v[112:115]
	v_mfma_f32_16x16x32_bf16 v[104:107], v[168:171], v[192:195], v[104:107]
	v_mfma_f32_16x16x32_bf16 v[96:99], v[176:179], v[192:195], v[96:99]
	v_mfma_f32_16x16x32_bf16 v[88:91], v[168:171], v[200:203], v[88:91]
	v_mfma_f32_16x16x32_bf16 v[80:83], v[176:179], v[200:203], v[80:83]
	v_mfma_f32_16x16x32_bf16 v[72:75], v[168:171], v[208:211], v[72:75]
	v_mfma_f32_16x16x32_bf16 v[64:67], v[176:179], v[208:211], v[64:67]
	s_setprio 2
	s_barrier
; #define PG8_STAGE(bufoff, gbase, voff) do { _Pragma("unroll") for (int _i = 0; _i < 2; ++_i) \
;         __builtin_amdgcn_global_load_lds((const unsigned*)((const char*)(gbase) + (voff)[_i]), (PG8_LAS unsigned*)(lds + (bufoff) + ldsw + _i * 8192), 16, 0, 0); } while (0)
; #define PG8_LDA(dst, b, h) do { _Pragma("unroll") for (int m = 0; m < 4; ++m) _Pragma("unroll") for (int k = 0; k < 2; ++k) dst[m][k] = *(const PG8_LAS bf16x8*)(lds + PG8_SA(b, h) + aoff + m * 2048 + k * 1024); } while (0)
; #define PG8_WAIT_V(n) asm volatile("s_waitcnt vmcnt(" #n ")" ::: "memory")
; #define PG8_WAIT_L(n) asm volatile("s_waitcnt lgkmcnt(" #n ")" ::: "memory")
; template <class Epi, class Sched, bool ALIGN_EPI = false, bool SP2 = false>
; __device__ __forceinline__ void gemm_phase(PG8_LAS unsigned char* lds, const Gemm g, const Sched& S, const Epi& E) {
;     ...
;         for (int t = 0; t < nt; t += 2) {
;             const bool last = (t == nt - 2);
;             const char* a1 = cA + (size_t)(t + 1) * kstep;
;             const char* a2 = last ? nA : cA + (size_t)(t + 2) * kstep; const char* b2 = last ? nB : cB + (size_t)(t + 2) * kstep;
;             const char* a3 = a2 + kstep; const char* b3 = b2 + kstep;
;             if (last && has_next) S.a_ready(nxt);
;             if constexpr (SP2) {
;             PG8_LDB(B0, 0, 0); PG8_LDB(B1, 0, 1); PG8_SCHED; PG8_LDA(At, 0, 0); PG8_STAGE(PG8_SA(1, 1), a1 + hstep, voffA);
;             PG8_WAIT_V(8); PG8_WAIT_L(0); PG8_BAR; PG8_MMA(0, 0, At, B0); PG8_MMA(0, 1, At, B1); PG8_BAR; PG8_SCHED;
;             PG8_LDA(At, 0, 1); PG8_STAGE(PG8_SB(0, 0), b2, voffB); PG8_STAGE(PG8_SB(0, 1), b2 + hstep, voffB); PG8_STAGE(PG8_SA(0, 0), a2, voffA);
;             PG8_WAIT_V(8); PG8_WAIT_L(0); PG8_BAR; PG8_MMA(1, 0, At, B0); PG8_MMA(1, 1, At, B1); PG8_BAR; PG8_SCHED;
;             PG8_LDB(B0, 1, 0); PG8_LDB(B1, 1, 1); PG8_SCHED; PG8_LDA(At, 1, 0); PG8_STAGE(PG8_SA(0, 1), a2 + hstep, voffA);
;             PG8_WAIT_V(8); PG8_WAIT_L(0); PG8_BAR; PG8_MMA(0, 0, At, B0); PG8_MMA(0, 1, At, B1); PG8_BAR; PG8_SCHED;
;             PG8_LDA(At, 1, 1); PG8_STAGE(PG8_SB(1, 0), b3, voffB); PG8_STAGE(PG8_SB(1, 1), b3 + hstep, voffB); PG8_STAGE(PG8_SA(1, 0), a3, voffA);
;             PG8_WAIT_V(8); PG8_WAIT_L(0); PG8_BAR; PG8_MMA(1, 0, At, B0); PG8_MMA(1, 1, At, B1); PG8_BAR; PG8_SCHED;
;     ...
;         if constexpr (ALIGN_EPI) { if (wr == 0) PG8_BAR; }
	v_mfma_f32_16x16x32_bf16 v[120:123], v[172:175], v[188:191], v[120:123]
	v_mfma_f32_16x16x32_bf16 v[112:115], v[180:183], v[188:191], v[112:115]
	v_mfma_f32_16x16x32_bf16 v[104:107], v[172:175], v[196:199], v[104:107]
	v_mfma_f32_16x16x32_bf16 v[96:99], v[180:183], v[196:199], v[96:99]
	v_mfma_f32_16x16x32_bf16 v[88:91], v[172:175], v[204:207], v[88:91]
	v_mfma_f32_16x16x32_bf16 v[80:83], v[180:183], v[204:207], v[80:83]
	v_mfma_f32_16x16x32_bf16 v[72:75], v[172:175], v[212:215], v[72:75]
	v_mfma_f32_16x16x32_bf16 v[64:67], v[180:183], v[212:215], v[64:67]
	s_setprio 0
	s_add_i32 s26, s53, s28
	v_lshl_add_u64 v[216:217], v[216:217], 0, s[4:5]
	s_mov_b32 m0, s26
	ds_read_b128 v[184:187], v155 offset:49152
	ds_read_b128 v[188:191], v155 offset:50176
	ds_read_b128 v[192:195], v155 offset:51200
	ds_read_b128 v[196:199], v155 offset:52224
	ds_read_b128 v[200:203], v155 offset:53248
	ds_read_b128 v[204:207], v155 offset:54272
	ds_read_b128 v[208:211], v155 offset:55296
	ds_read_b128 v[212:215], v155 offset:56320
	global_load_lds_dwordx4 v[216:217], off
	s_add_i32 m0, s26, 0x2000
	s_add_u32 s24, s24, 0x80080
	v_lshl_add_u64 v[216:217], v[218:219], 0, s[4:5]
	s_addc_u32 s25, s25, 0
	s_add_i32 s26, s54, s28
	global_load_lds_dwordx4 v[216:217], off
	v_lshl_add_u64 v[216:217], s[24:25], 0, v[134:135]
	s_mov_b32 m0, s26
	s_nop 0
	global_load_lds_dwordx4 v[216:217], off
	v_lshl_add_u64 v[216:217], s[24:25], 0, v[130:131]
	s_add_i32 m0, s26, 0x2000
	s_nop 0
	global_load_lds_dwordx4 v[216:217], off
	v_lshl_add_u64 v[216:217], v[220:221], 0, s[4:5]
	s_mov_b32 m0, s37
	s_nop 0
	global_load_lds_dwordx4 v[216:217], off
	v_lshl_add_u64 v[216:217], v[222:223], 0, s[4:5]
	s_mov_b32 m0, s38
	s_nop 0
	global_load_lds_dwordx4 v[216:217], off
	s_waitcnt vmcnt(8)
	s_waitcnt lgkmcnt(0)
	s_barrier
	s_setprio 1
	s_waitcnt lgkmcnt(0)
	v_mfma_f32_16x16x32_bf16 v[60:63], v[146:149], v[184:187], v[60:63]
	v_mfma_f32_16x16x32_bf16 v[52:55], v[160:163], v[184:187], v[52:55]
	v_mfma_f32_16x16x32_bf16 v[44:47], v[146:149], v[192:195], v[44:47]
	v_mfma_f32_16x16x32_bf16 v[36:39], v[160:163], v[192:195], v[36:39]
	v_mfma_f32_16x16x32_bf16 v[28:31], v[146:149], v[200:203], v[28:31]
	v_mfma_f32_16x16x32_bf16 v[20:23], v[160:163], v[200:203], v[20:23]
	v_mfma_f32_16x16x32_bf16 v[12:15], v[146:149], v[208:211], v[12:15]
	v_mfma_f32_16x16x32_bf16 v[4:7], v[160:163], v[208:211], v[4:7]
	v_mfma_f32_16x16x32_bf16 v[60:63], v[156:159], v[188:191], v[60:63]
	v_mfma_f32_16x16x32_bf16 v[52:55], v[164:167], v[188:191], v[52:55]
	v_mfma_f32_16x16x32_bf16 v[44:47], v[156:159], v[196:199], v[44:47]
	v_mfma_f32_16x16x32_bf16 v[36:39], v[164:167], v[196:199], v[36:39]
	v_mfma_f32_16x16x32_bf16 v[28:31], v[156:159], v[204:207], v[28:31]
	v_mfma_f32_16x16x32_bf16 v[20:23], v[164:167], v[204:207], v[20:23]
	v_mfma_f32_16x16x32_bf16 v[12:15], v[156:159], v[212:215], v[12:15]
	v_mfma_f32_16x16x32_bf16 v[4:7], v[164:167], v[212:215], v[4:7]
	s_setprio 0
	s_setprio 1
	v_mfma_f32_16x16x32_bf16 v[56:59], v[168:171], v[184:187], v[56:59]
	v_mfma_f32_16x16x32_bf16 v[48:51], v[176:179], v[184:187], v[48:51]
	v_mfma_f32_16x16x32_bf16 v[40:43], v[168:171], v[192:195], v[40:43]
	v_mfma_f32_16x16x32_bf16 v[32:35], v[176:179], v[192:195], v[32:35]
	v_mfma_f32_16x16x32_bf16 v[24:27], v[168:171], v[200:203], v[24:27]
	v_mfma_f32_16x16x32_bf16 v[16:19], v[176:179], v[200:203], v[16:19]
	v_mfma_f32_16x16x32_bf16 v[8:11], v[168:171], v[208:211], v[8:11]
	v_mfma_f32_16x16x32_bf16 v[0:3], v[176:179], v[208:211], v[0:3]
	s_setprio 2
	s_barrier
	v_mfma_f32_16x16x32_bf16 v[56:59], v[172:175], v[188:191], v[56:59]
	v_mfma_f32_16x16x32_bf16 v[48:51], v[180:183], v[188:191], v[48:51]
	v_mfma_f32_16x16x32_bf16 v[40:43], v[172:175], v[196:199], v[40:43]
	v_mfma_f32_16x16x32_bf16 v[32:35], v[180:183], v[196:199], v[32:35]
	v_mfma_f32_16x16x32_bf16 v[24:27], v[172:175], v[204:207], v[24:27]
	v_mfma_f32_16x16x32_bf16 v[16:19], v[180:183], v[204:207], v[16:19]
	v_mfma_f32_16x16x32_bf16 v[8:11], v[172:175], v[212:215], v[8:11]
	v_mfma_f32_16x16x32_bf16 v[0:3], v[180:183], v[212:215], v[0:3]
	s_setprio 0
	s_add_i32 s52, s52, 2
	s_add_u32 s22, s22, 0x100
	s_addc_u32 s23, s23, 0
	s_add_u32 s47, s47, 0x100
	s_addc_u32 s51, s51, 0
	s_cmp_gt_u32 s52, 29
	s_cbranch_scc0 .LBB0_966
	s_and_b64 vcc, exec, s[10:11]
	s_cbranch_vccz .LBB0_969
	s_barrier

; #define PG8_STAGE(bufoff, gbase, voff) do { _Pragma("unroll") for (int _i = 0; _i < 2; ++_i) \
;         __builtin_amdgcn_global_load_lds((const unsigned*)((const char*)(gbase) + (voff)[_i]), (PG8_LAS unsigned*)(lds + (bufoff) + ldsw + _i * 8192), 16, 0, 0); } while (0)
; #define PG8_LDA(dst, b, h) do { _Pragma("unroll") for (int m = 0; m < 4; ++m) _Pragma("unroll") for (int k = 0; k < 2; ++k) dst[m][k] = *(const PG8_LAS bf16x8*)(lds + PG8_SA(b, h) + aoff + m * 2048 + k * 1024); } while (0)
; #define PG8_LDB(dst, b, h) do { _Pragma("unroll") for (int n = 0; n < 2; ++n) _Pragma("unroll") for (int k = 0; k < 2; ++k) dst[n][k] = *(const PG8_LAS bf16x8*)(lds + PG8_SB(b, h) + boff + n * 2048 + k * 1024); } while (0)
; #define PG8_BAR __builtin_amdgcn_s_barrier()
; template <class Epi, class Sched, bool ALIGN_EPI = false, bool SP2 = false>
; __device__ __forceinline__ void gemm_phase(PG8_LAS unsigned char* lds, const Gemm g, const Sched& S, const Epi& E) {
;     ...
;             const bool last = (t == nt - 2);
;             const char* a1 = cA + (size_t)(t + 1) * kstep;
;             const char* a2 = last ? nA : cA + (size_t)(t + 2) * kstep; const char* b2 = last ? nB : cB + (size_t)(t + 2) * kstep;
;             const char* a3 = a2 + kstep; const char* b3 = b2 + kstep;
;             if (last && has_next) S.a_ready(nxt);
;             if constexpr (SP2) {
;             PG8_LDB(B0, 0, 0); PG8_LDB(B1, 0, 1); PG8_SCHED; PG8_LDA(At, 0, 0); PG8_STAGE(PG8_SA(1, 1), a1 + hstep, voffA);
;             PG8_WAIT_V(8); PG8_WAIT_L(0); PG8_BAR; PG8_MMA(0, 0, At, B0); PG8_MMA(0, 1, At, B1); PG8_BAR; PG8_SCHED;
;             PG8_LDA(At, 0, 1); PG8_STAGE(PG8_SB(0, 0), b2, voffB); PG8_STAGE(PG8_SB(0, 1), b2 + hstep, voffB); PG8_STAGE(PG8_SA(0, 0), a2, voffA);
;             PG8_WAIT_V(8); PG8_WAIT_L(0); PG8_BAR; PG8_MMA(1, 0, At, B0); PG8_MMA(1, 1, At, B1); PG8_BAR; PG8_SCHED;
;             PG8_LDB(B0, 1, 0); PG8_LDB(B1, 1, 1); PG8_SCHED; PG8_LDA(At, 1, 0); PG8_STAGE(PG8_SA(0, 1), a2 + hstep, voffA);
;             PG8_WAIT_V(8); PG8_WAIT_L(0); PG8_BAR; PG8_MMA(0, 0, At, B0); PG8_MMA(0, 1, At, B1); PG8_BAR; PG8_SCHED;
;             PG8_LDA(At, 1, 1); PG8_STAGE(PG8_SB(1, 0), b3, voffB); PG8_STAGE(PG8_SB(1, 1), b3 + hstep, voffB); PG8_STAGE(PG8_SA(1, 0), a3, voffA);
;             PG8_WAIT_V(8); PG8_WAIT_L(0); PG8_BAR; PG8_MMA(1, 0, At, B0); PG8_MMA(1, 1, At, B1); PG8_BAR; PG8_SCHED;
.LBB0_1056:
	ds_read_b128 v[158:161], v155
	ds_read_b128 v[162:165], v155 offset:1024
	ds_read_b128 v[166:169], v155 offset:2048
	ds_read_b128 v[170:173], v155 offset:3072
	ds_read_b128 v[174:177], v156
	ds_read_b128 v[178:181], v156 offset:1024
	ds_read_b128 v[182:185], v156 offset:2048
	ds_read_b128 v[186:189], v156 offset:3072
	s_add_u32 s26, s24, 0xffea0080
	s_addc_u32 s27, s25, -1
	s_cmpk_eq_i32 s59, 0x54
	s_cselect_b32 s29, s21, s27
	s_cselect_b32 s28, s20, s26
	s_cselect_b32 s27, s23, s58
	s_cselect_b32 s26, s22, s57
	v_lshl_add_u64 v[222:223], s[24:25], 0, v[138:139]
	s_add_i32 m0, s35, 0xc000
	ds_read_b128 v[190:193], v157
	ds_read_b128 v[194:197], v157 offset:1024
	ds_read_b128 v[198:201], v157 offset:2048
	ds_read_b128 v[202:205], v157 offset:3072
	ds_read_b128 v[206:209], v157 offset:4096
	ds_read_b128 v[210:213], v157 offset:5120
	ds_read_b128 v[214:217], v157 offset:6144
	ds_read_b128 v[218:221], v157 offset:7168
	global_load_lds_dwordx4 v[222:223], off
	v_lshl_add_u64 v[222:223], s[24:25], 0, v[140:141]
	s_add_i32 m0, s35, 0xe000
	s_nop 0
	global_load_lds_dwordx4 v[222:223], off
	s_waitcnt vmcnt(8)
	s_waitcnt lgkmcnt(0)
	s_barrier
	s_setprio 1
	s_waitcnt lgkmcnt(0)
	v_mfma_f32_16x16x32_bf16 v[124:127], v[158:161], v[190:193], v[124:127]
	v_mfma_f32_16x16x32_bf16 v[120:123], v[166:169], v[190:193], v[120:123]
	v_mfma_f32_16x16x32_bf16 v[116:119], v[158:161], v[198:201], v[116:119]
	v_mfma_f32_16x16x32_bf16 v[112:115], v[166:169], v[198:201], v[112:115]
	v_mfma_f32_16x16x32_bf16 v[100:103], v[158:161], v[206:209], v[100:103]
	v_mfma_f32_16x16x32_bf16 v[96:99], v[166:169], v[206:209], v[96:99]
	v_mfma_f32_16x16x32_bf16 v[84:87], v[158:161], v[214:217], v[84:87]
	v_mfma_f32_16x16x32_bf16 v[80:83], v[166:169], v[214:217], v[80:83]
	v_mfma_f32_16x16x32_bf16 v[124:127], v[162:165], v[194:197], v[124:127]
	v_mfma_f32_16x16x32_bf16 v[120:123], v[170:173], v[194:197], v[120:123]
	v_mfma_f32_16x16x32_bf16 v[116:119], v[162:165], v[202:205], v[116:119]
	v_mfma_f32_16x16x32_bf16 v[112:115], v[170:173], v[202:205], v[112:115]
	v_mfma_f32_16x16x32_bf16 v[100:103], v[162:165], v[210:213], v[100:103]
	v_mfma_f32_16x16x32_bf16 v[96:99], v[170:173], v[210:213], v[96:99]
	v_mfma_f32_16x16x32_bf16 v[84:87], v[162:165], v[218:221], v[84:87]
	v_mfma_f32_16x16x32_bf16 v[80:83], v[170:173], v[218:221], v[80:83]
	s_setprio 0
	s_setprio 1
	v_mfma_f32_16x16x32_bf16 v[108:111], v[174:177], v[190:193], v[108:111]
	v_mfma_f32_16x16x32_bf16 v[104:107], v[182:185], v[190:193], v[104:107]
	v_mfma_f32_16x16x32_bf16 v[92:95], v[174:177], v[198:201], v[92:95]
	v_mfma_f32_16x16x32_bf16 v[88:91], v[182:185], v[198:201], v[88:91]
	v_mfma_f32_16x16x32_bf16 v[76:79], v[174:177], v[206:209], v[76:79]
	v_mfma_f32_16x16x32_bf16 v[72:75], v[182:185], v[206:209], v[72:75]
	v_mfma_f32_16x16x32_bf16 v[68:71], v[174:177], v[214:217], v[68:71]
	v_mfma_f32_16x16x32_bf16 v[64:67], v[182:185], v[214:217], v[64:67]
	s_setprio 2
	s_barrier
	v_mfma_f32_16x16x32_bf16 v[108:111], v[178:181], v[194:197], v[108:111]
	v_mfma_f32_16x16x32_bf16 v[104:107], v[186:189], v[194:197], v[104:107]
	v_mfma_f32_16x16x32_bf16 v[92:95], v[178:181], v[202:205], v[92:95]
	v_mfma_f32_16x16x32_bf16 v[88:91], v[186:189], v[202:205], v[88:91]
	v_mfma_f32_16x16x32_bf16 v[76:79], v[178:181], v[210:213], v[76:79]
	v_mfma_f32_16x16x32_bf16 v[72:75], v[186:189], v[210:213], v[72:75]
	v_mfma_f32_16x16x32_bf16 v[68:71], v[178:181], v[218:221], v[68:71]
	v_mfma_f32_16x16x32_bf16 v[64:67], v[186:189], v[218:221], v[64:67]
	s_setprio 0
	s_add_i32 s60, s44, s30
	v_lshl_add_u64 v[222:223], s[26:27], 0, v[132:133]
	s_mov_b32 m0, s60
	ds_read_b128 v[190:193], v157 offset:16384
	ds_read_b128 v[194:197], v157 offset:17408
	ds_read_b128 v[198:201], v157 offset:18432
	ds_read_b128 v[202:205], v157 offset:19456
	ds_read_b128 v[206:209], v157 offset:20480
	ds_read_b128 v[210:213], v157 offset:21504
	ds_read_b128 v[214:217], v157 offset:22528
	ds_read_b128 v[218:221], v157 offset:23552
	global_load_lds_dwordx4 v[222:223], off
	s_add_i32 m0, s60, 0x2000
	s_add_u32 s60, s26, 0x160000
	v_lshl_add_u64 v[224:225], s[26:27], 0, v[136:137]
	s_addc_u32 s61, s27, 0
	s_add_i32 s62, s45, s30
	global_load_lds_dwordx4 v[224:225], off
	v_lshl_add_u64 v[226:227], s[60:61], 0, v[132:133]
	s_mov_b32 m0, s62
	v_lshl_add_u64 v[228:229], s[28:29], 0, v[134:135]
	global_load_lds_dwordx4 v[226:227], off
	v_lshl_add_u64 v[226:227], s[60:61], 0, v[136:137]
	s_add_i32 m0, s62, 0x2000
	s_nop 0
	global_load_lds_dwordx4 v[226:227], off
	v_lshl_add_u64 v[226:227], s[28:29], 0, v[130:131]
	s_mov_b32 m0, s35
	s_nop 0
	global_load_lds_dwordx4 v[226:227], off
	s_mov_b32 m0, s36
	s_nop 0
	global_load_lds_dwordx4 v[228:229], off
	s_waitcnt vmcnt(8)
	s_waitcnt lgkmcnt(0)
	s_barrier
	s_setprio 1
	s_waitcnt lgkmcnt(0)
	v_mfma_f32_16x16x32_bf16 v[60:63], v[158:161], v[190:193], v[60:63]
	v_mfma_f32_16x16x32_bf16 v[56:59], v[166:169], v[190:193], v[56:59]
	v_mfma_f32_16x16x32_bf16 v[52:55], v[158:161], v[198:201], v[52:55]
	v_mfma_f32_16x16x32_bf16 v[48:51], v[166:169], v[198:201], v[48:51]
	v_mfma_f32_16x16x32_bf16 v[36:39], v[158:161], v[206:209], v[36:39]
	v_mfma_f32_16x16x32_bf16 v[32:35], v[166:169], v[206:209], v[32:35]
	v_mfma_f32_16x16x32_bf16 v[20:23], v[158:161], v[214:217], v[20:23]
	v_mfma_f32_16x16x32_bf16 v[16:19], v[166:169], v[214:217], v[16:19]
	v_mfma_f32_16x16x32_bf16 v[60:63], v[162:165], v[194:197], v[60:63]
	v_mfma_f32_16x16x32_bf16 v[56:59], v[170:173], v[194:197], v[56:59]
	v_mfma_f32_16x16x32_bf16 v[52:55], v[162:165], v[202:205], v[52:55]
	v_mfma_f32_16x16x32_bf16 v[48:51], v[170:173], v[202:205], v[48:51]
	v_mfma_f32_16x16x32_bf16 v[36:39], v[162:165], v[210:213], v[36:39]
	v_mfma_f32_16x16x32_bf16 v[32:35], v[170:173], v[210:213], v[32:35]
	v_mfma_f32_16x16x32_bf16 v[20:23], v[162:165], v[218:221], v[20:23]
	v_mfma_f32_16x16x32_bf16 v[16:19], v[170:173], v[218:221], v[16:19]
	s_setprio 0
	s_setprio 1
	v_mfma_f32_16x16x32_bf16 v[44:47], v[174:177], v[190:193], v[44:47]
	v_mfma_f32_16x16x32_bf16 v[40:43], v[182:185], v[190:193], v[40:43]
	v_mfma_f32_16x16x32_bf16 v[28:31], v[174:177], v[198:201], v[28:31]
	v_mfma_f32_16x16x32_bf16 v[24:27], v[182:185], v[198:201], v[24:27]
	v_mfma_f32_16x16x32_bf16 v[12:15], v[174:177], v[206:209], v[12:15]
	v_mfma_f32_16x16x32_bf16 v[8:11], v[182:185], v[206:209], v[8:11]
	v_mfma_f32_16x16x32_bf16 v[4:7], v[174:177], v[214:217], v[4:7]
	v_mfma_f32_16x16x32_bf16 v[0:3], v[182:185], v[214:217], v[0:3]
	s_setprio 2
	s_barrier
; #define PG8_STAGE(bufoff, gbase, voff) do { _Pragma("unroll") for (int _i = 0; _i < 2; ++_i) \
;         __builtin_amdgcn_global_load_lds((const unsigned*)((const char*)(gbase) + (voff)[_i]), (PG8_LAS unsigned*)(lds + (bufoff) + ldsw + _i * 8192), 16, 0, 0); } while (0)
; #define PG8_LDA(dst, b, h) do { _Pragma("unroll") for (int m = 0; m < 4; ++m) _Pragma("unroll") for (int k = 0; k < 2; ++k) dst[m][k] = *(const PG8_LAS bf16x8*)(lds + PG8_SA(b, h) + aoff + m * 2048 + k * 1024); } while (0)
; #define PG8_LDB(dst, b, h) do { _Pragma("unroll") for (int n = 0; n < 2; ++n) _Pragma("unroll") for (int k = 0; k < 2; ++k) dst[n][k] = *(const PG8_LAS bf16x8*)(lds + PG8_SB(b, h) + boff + n * 2048 + k * 1024); } while (0)
; #define PG8_BAR __builtin_amdgcn_s_barrier()
; template <class Epi, class Sched, bool ALIGN_EPI = false, bool SP2 = false>
; __device__ __forceinline__ void gemm_phase(PG8_LAS unsigned char* lds, const Gemm g, const Sched& S, const Epi& E) {
;     ...
;             const bool last = (t == nt - 2);
;             const char* a1 = cA + (size_t)(t + 1) * kstep;
;             const char* a2 = last ? nA : cA + (size_t)(t + 2) * kstep; const char* b2 = last ? nB : cB + (size_t)(t + 2) * kstep;
;             const char* a3 = a2 + kstep; const char* b3 = b2 + kstep;
;             if (last && has_next) S.a_ready(nxt);
;             if constexpr (SP2) {
;             PG8_LDB(B0, 0, 0); PG8_LDB(B1, 0, 1); PG8_SCHED; PG8_LDA(At, 0, 0); PG8_STAGE(PG8_SA(1, 1), a1 + hstep, voffA);
;             PG8_WAIT_V(8); PG8_WAIT_L(0); PG8_BAR; PG8_MMA(0, 0, At, B0); PG8_MMA(0, 1, At, B1); PG8_BAR; PG8_SCHED;
;             PG8_LDA(At, 0, 1); PG8_STAGE(PG8_SB(0, 0), b2, voffB); PG8_STAGE(PG8_SB(0, 1), b2 + hstep, voffB); PG8_STAGE(PG8_SA(0, 0), a2, voffA);
;             PG8_WAIT_V(8); PG8_WAIT_L(0); PG8_BAR; PG8_MMA(1, 0, At, B0); PG8_MMA(1, 1, At, B1); PG8_BAR; PG8_SCHED;
;             PG8_LDB(B0, 1, 0); PG8_LDB(B1, 1, 1); PG8_SCHED; PG8_LDA(At, 1, 0); PG8_STAGE(PG8_SA(0, 1), a2 + hstep, voffA);
;             PG8_WAIT_V(8); PG8_WAIT_L(0); PG8_BAR; PG8_MMA(0, 0, At, B0); PG8_MMA(0, 1, At, B1); PG8_BAR; PG8_SCHED;
;             PG8_LDA(At, 1, 1); PG8_STAGE(PG8_SB(1, 0), b3, voffB); PG8_STAGE(PG8_SB(1, 1), b3 + hstep, voffB); PG8_STAGE(PG8_SA(1, 0), a3, voffA);
;             PG8_WAIT_V(8); PG8_WAIT_L(0); PG8_BAR; PG8_MMA(1, 0, At, B0); PG8_MMA(1, 1, At, B1); PG8_BAR; PG8_SCHED;
	v_mfma_f32_16x16x32_bf16 v[44:47], v[178:181], v[194:197], v[44:47]
	v_mfma_f32_16x16x32_bf16 v[40:43], v[186:189], v[194:197], v[40:43]
	v_mfma_f32_16x16x32_bf16 v[28:31], v[178:181], v[202:205], v[28:31]
	v_mfma_f32_16x16x32_bf16 v[24:27], v[186:189], v[202:205], v[24:27]
	v_mfma_f32_16x16x32_bf16 v[12:15], v[178:181], v[210:213], v[12:15]
	v_mfma_f32_16x16x32_bf16 v[8:11], v[186:189], v[210:213], v[8:11]
	v_mfma_f32_16x16x32_bf16 v[4:7], v[178:181], v[218:221], v[4:7]
	v_mfma_f32_16x16x32_bf16 v[0:3], v[186:189], v[218:221], v[0:3]
	s_setprio 0
	s_add_i32 s60, 0, 0x18000
	s_add_i32 s61, 0, 0x1c000
	v_add_u32_e32 v170, s60, v153
	v_add_u32_e32 v186, s61, v153
	ds_read_b128 v[158:161], v170
	ds_read_b128 v[162:165], v170 offset:1024
	ds_read_b128 v[166:169], v170 offset:2048
	ds_read_b128 v[170:173], v170 offset:3072
	ds_read_b128 v[174:177], v186
	ds_read_b128 v[178:181], v186 offset:1024
	ds_read_b128 v[182:185], v186 offset:2048
	ds_read_b128 v[186:189], v186 offset:3072
	s_add_u32 s28, s28, 0x160000
	s_addc_u32 s29, s29, 0
	s_mov_b32 m0, s37
	v_lshl_add_u64 v[230:231], s[28:29], 0, v[130:131]
	ds_read_b128 v[190:193], v157 offset:32768
	ds_read_b128 v[194:197], v157 offset:33792
	ds_read_b128 v[198:201], v157 offset:34816
	ds_read_b128 v[202:205], v157 offset:35840
	ds_read_b128 v[206:209], v157 offset:36864
	ds_read_b128 v[210:213], v157 offset:37888
	ds_read_b128 v[214:217], v157 offset:38912
	ds_read_b128 v[218:221], v157 offset:39936
	global_load_lds_dwordx4 v[230:231], off
	v_lshl_add_u64 v[230:231], s[28:29], 0, v[134:135]
	s_mov_b32 m0, s38
	s_nop 0
	global_load_lds_dwordx4 v[230:231], off
	s_waitcnt vmcnt(8)
	s_waitcnt lgkmcnt(0)
	s_barrier
	s_setprio 1
	s_waitcnt lgkmcnt(0)
	v_mfma_f32_16x16x32_bf16 v[124:127], v[158:161], v[190:193], v[124:127]
	v_mfma_f32_16x16x32_bf16 v[120:123], v[166:169], v[190:193], v[120:123]
	v_mfma_f32_16x16x32_bf16 v[116:119], v[158:161], v[198:201], v[116:119]
	v_mfma_f32_16x16x32_bf16 v[112:115], v[166:169], v[198:201], v[112:115]
	v_mfma_f32_16x16x32_bf16 v[100:103], v[158:161], v[206:209], v[100:103]
	v_mfma_f32_16x16x32_bf16 v[96:99], v[166:169], v[206:209], v[96:99]
	v_mfma_f32_16x16x32_bf16 v[84:87], v[158:161], v[214:217], v[84:87]
	v_mfma_f32_16x16x32_bf16 v[80:83], v[166:169], v[214:217], v[80:83]
	v_mfma_f32_16x16x32_bf16 v[124:127], v[162:165], v[194:197], v[124:127]
	v_mfma_f32_16x16x32_bf16 v[120:123], v[170:173], v[194:197], v[120:123]
	v_mfma_f32_16x16x32_bf16 v[116:119], v[162:165], v[202:205], v[116:119]
	v_mfma_f32_16x16x32_bf16 v[112:115], v[170:173], v[202:205], v[112:115]
	v_mfma_f32_16x16x32_bf16 v[100:103], v[162:165], v[210:213], v[100:103]
	v_mfma_f32_16x16x32_bf16 v[96:99], v[170:173], v[210:213], v[96:99]
	v_mfma_f32_16x16x32_bf16 v[84:87], v[162:165], v[218:221], v[84:87]
	v_mfma_f32_16x16x32_bf16 v[80:83], v[170:173], v[218:221], v[80:83]
	s_setprio 0
	s_setprio 1
	v_mfma_f32_16x16x32_bf16 v[108:111], v[174:177], v[190:193], v[108:111]
	v_mfma_f32_16x16x32_bf16 v[104:107], v[182:185], v[190:193], v[104:107]
	v_mfma_f32_16x16x32_bf16 v[92:95], v[174:177], v[198:201], v[92:95]
	v_mfma_f32_16x16x32_bf16 v[88:91], v[182:185], v[198:201], v[88:91]
	v_mfma_f32_16x16x32_bf16 v[76:79], v[174:177], v[206:209], v[76:79]
	v_mfma_f32_16x16x32_bf16 v[72:75], v[182:185], v[206:209], v[72:75]
	v_mfma_f32_16x16x32_bf16 v[68:71], v[174:177], v[214:217], v[68:71]
	v_mfma_f32_16x16x32_bf16 v[64:67], v[182:185], v[214:217], v[64:67]
	s_setprio 2
	s_barrier
; #define PG8_STAGE(bufoff, gbase, voff) do { _Pragma("unroll") for (int _i = 0; _i < 2; ++_i) \
;         __builtin_amdgcn_global_load_lds((const unsigned*)((const char*)(gbase) + (voff)[_i]), (PG8_LAS unsigned*)(lds + (bufoff) + ldsw + _i * 8192), 16, 0, 0); } while (0)
; #define PG8_LDA(dst, b, h) do { _Pragma("unroll") for (int m = 0; m < 4; ++m) _Pragma("unroll") for (int k = 0; k < 2; ++k) dst[m][k] = *(const PG8_LAS bf16x8*)(lds + PG8_SA(b, h) + aoff + m * 2048 + k * 1024); } while (0)
; #define PG8_WAIT_V(n) asm volatile("s_waitcnt vmcnt(" #n ")" ::: "memory")
; #define PG8_WAIT_L(n) asm volatile("s_waitcnt lgkmcnt(" #n ")" ::: "memory")
; template <class Epi, class Sched, bool ALIGN_EPI = false, bool SP2 = false>
; __device__ __forceinline__ void gemm_phase(PG8_LAS unsigned char* lds, const Gemm g, const Sched& S, const Epi& E) {
;     ...
;         for (int t = 0; t < nt; t += 2) {
;             const bool last = (t == nt - 2);
;             const char* a1 = cA + (size_t)(t + 1) * kstep;
;             const char* a2 = last ? nA : cA + (size_t)(t + 2) * kstep; const char* b2 = last ? nB : cB + (size_t)(t + 2) * kstep;
;             const char* a3 = a2 + kstep; const char* b3 = b2 + kstep;
;             if (last && has_next) S.a_ready(nxt);
;             if constexpr (SP2) {
;             PG8_LDB(B0, 0, 0); PG8_LDB(B1, 0, 1); PG8_SCHED; PG8_LDA(At, 0, 0); PG8_STAGE(PG8_SA(1, 1), a1 + hstep, voffA);
;             PG8_WAIT_V(8); PG8_WAIT_L(0); PG8_BAR; PG8_MMA(0, 0, At, B0); PG8_MMA(0, 1, At, B1); PG8_BAR; PG8_SCHED;
;             PG8_LDA(At, 0, 1); PG8_STAGE(PG8_SB(0, 0), b2, voffB); PG8_STAGE(PG8_SB(0, 1), b2 + hstep, voffB); PG8_STAGE(PG8_SA(0, 0), a2, voffA);
;             PG8_WAIT_V(8); PG8_WAIT_L(0); PG8_BAR; PG8_MMA(1, 0, At, B0); PG8_MMA(1, 1, At, B1); PG8_BAR; PG8_SCHED;
;             PG8_LDB(B0, 1, 0); PG8_LDB(B1, 1, 1); PG8_SCHED; PG8_LDA(At, 1, 0); PG8_STAGE(PG8_SA(0, 1), a2 + hstep, voffA);
;             PG8_WAIT_V(8); PG8_WAIT_L(0); PG8_BAR; PG8_MMA(0, 0, At, B0); PG8_MMA(0, 1, At, B1); PG8_BAR; PG8_SCHED;
;             PG8_LDA(At, 1, 1); PG8_STAGE(PG8_SB(1, 0), b3, voffB); PG8_STAGE(PG8_SB(1, 1), b3 + hstep, voffB); PG8_STAGE(PG8_SA(1, 0), a3, voffA);
;             PG8_WAIT_V(8); PG8_WAIT_L(0); PG8_BAR; PG8_MMA(1, 0, At, B0); PG8_MMA(1, 1, At, B1); PG8_BAR; PG8_SCHED;
;     ...
;         if constexpr (ALIGN_EPI) { if (wr == 0) PG8_BAR; }
	v_mfma_f32_16x16x32_bf16 v[108:111], v[178:181], v[194:197], v[108:111]
	v_mfma_f32_16x16x32_bf16 v[104:107], v[186:189], v[194:197], v[104:107]
	v_mfma_f32_16x16x32_bf16 v[92:95], v[178:181], v[202:205], v[92:95]
	v_mfma_f32_16x16x32_bf16 v[88:91], v[186:189], v[202:205], v[88:91]
	v_mfma_f32_16x16x32_bf16 v[76:79], v[178:181], v[210:213], v[76:79]
	v_mfma_f32_16x16x32_bf16 v[72:75], v[186:189], v[210:213], v[72:75]
	v_mfma_f32_16x16x32_bf16 v[68:71], v[178:181], v[218:221], v[68:71]
	v_mfma_f32_16x16x32_bf16 v[64:67], v[186:189], v[218:221], v[64:67]
	s_setprio 0
	s_add_i32 s28, s60, s30
	v_lshl_add_u64 v[222:223], v[222:223], 0, s[4:5]
	s_mov_b32 m0, s28
	ds_read_b128 v[190:193], v157 offset:49152
	ds_read_b128 v[194:197], v157 offset:50176
	ds_read_b128 v[198:201], v157 offset:51200
	ds_read_b128 v[202:205], v157 offset:52224
	ds_read_b128 v[206:209], v157 offset:53248
	ds_read_b128 v[210:213], v157 offset:54272
	ds_read_b128 v[214:217], v157 offset:55296
	ds_read_b128 v[218:221], v157 offset:56320
	global_load_lds_dwordx4 v[222:223], off
	s_add_i32 m0, s28, 0x2000
	s_add_u32 s26, s26, 0x160080
	v_lshl_add_u64 v[222:223], v[224:225], 0, s[4:5]
	s_addc_u32 s27, s27, 0
	s_add_i32 s28, s61, s30
	global_load_lds_dwordx4 v[222:223], off
	v_lshl_add_u64 v[222:223], s[26:27], 0, v[132:133]
	s_mov_b32 m0, s28
	s_nop 0
	global_load_lds_dwordx4 v[222:223], off
	v_lshl_add_u64 v[222:223], s[26:27], 0, v[136:137]
	s_add_i32 m0, s28, 0x2000
	s_nop 0
	global_load_lds_dwordx4 v[222:223], off
	v_lshl_add_u64 v[222:223], v[226:227], 0, s[4:5]
	s_mov_b32 m0, s40
	s_nop 0
	global_load_lds_dwordx4 v[222:223], off
	v_lshl_add_u64 v[222:223], v[228:229], 0, s[4:5]
	s_mov_b32 m0, s41
	s_nop 0
	global_load_lds_dwordx4 v[222:223], off
	s_waitcnt vmcnt(8)
	s_waitcnt lgkmcnt(0)
	s_barrier
	s_setprio 1
	s_waitcnt lgkmcnt(0)
	v_mfma_f32_16x16x32_bf16 v[60:63], v[158:161], v[190:193], v[60:63]
	v_mfma_f32_16x16x32_bf16 v[56:59], v[166:169], v[190:193], v[56:59]
	v_mfma_f32_16x16x32_bf16 v[52:55], v[158:161], v[198:201], v[52:55]
	v_mfma_f32_16x16x32_bf16 v[48:51], v[166:169], v[198:201], v[48:51]
	v_mfma_f32_16x16x32_bf16 v[36:39], v[158:161], v[206:209], v[36:39]
	v_mfma_f32_16x16x32_bf16 v[32:35], v[166:169], v[206:209], v[32:35]
	v_mfma_f32_16x16x32_bf16 v[20:23], v[158:161], v[214:217], v[20:23]
	v_mfma_f32_16x16x32_bf16 v[16:19], v[166:169], v[214:217], v[16:19]
	v_mfma_f32_16x16x32_bf16 v[60:63], v[162:165], v[194:197], v[60:63]
	v_mfma_f32_16x16x32_bf16 v[56:59], v[170:173], v[194:197], v[56:59]
	v_mfma_f32_16x16x32_bf16 v[52:55], v[162:165], v[202:205], v[52:55]
	v_mfma_f32_16x16x32_bf16 v[48:51], v[170:173], v[202:205], v[48:51]
	v_mfma_f32_16x16x32_bf16 v[36:39], v[162:165], v[210:213], v[36:39]
	v_mfma_f32_16x16x32_bf16 v[32:35], v[170:173], v[210:213], v[32:35]
	v_mfma_f32_16x16x32_bf16 v[20:23], v[162:165], v[218:221], v[20:23]
	v_mfma_f32_16x16x32_bf16 v[16:19], v[170:173], v[218:221], v[16:19]
	s_setprio 0
	s_setprio 1
	v_mfma_f32_16x16x32_bf16 v[44:47], v[174:177], v[190:193], v[44:47]
	v_mfma_f32_16x16x32_bf16 v[40:43], v[182:185], v[190:193], v[40:43]
	v_mfma_f32_16x16x32_bf16 v[28:31], v[174:177], v[198:201], v[28:31]
	v_mfma_f32_16x16x32_bf16 v[24:27], v[182:185], v[198:201], v[24:27]
	v_mfma_f32_16x16x32_bf16 v[12:15], v[174:177], v[206:209], v[12:15]
	v_mfma_f32_16x16x32_bf16 v[8:11], v[182:185], v[206:209], v[8:11]
	v_mfma_f32_16x16x32_bf16 v[4:7], v[174:177], v[214:217], v[4:7]
	v_mfma_f32_16x16x32_bf16 v[0:3], v[182:185], v[214:217], v[0:3]
	s_setprio 2
	s_barrier
	v_mfma_f32_16x16x32_bf16 v[44:47], v[178:181], v[194:197], v[44:47]
	v_mfma_f32_16x16x32_bf16 v[40:43], v[186:189], v[194:197], v[40:43]
	v_mfma_f32_16x16x32_bf16 v[28:31], v[178:181], v[202:205], v[28:31]
	v_mfma_f32_16x16x32_bf16 v[24:27], v[186:189], v[202:205], v[24:27]
	v_mfma_f32_16x16x32_bf16 v[12:15], v[178:181], v[210:213], v[12:15]
	v_mfma_f32_16x16x32_bf16 v[8:11], v[186:189], v[210:213], v[8:11]
	v_mfma_f32_16x16x32_bf16 v[4:7], v[178:181], v[218:221], v[4:7]
	v_mfma_f32_16x16x32_bf16 v[0:3], v[186:189], v[218:221], v[0:3]
	s_setprio 0
	s_add_i32 s59, s59, 2
	s_add_u32 s24, s24, 0x100
	s_addc_u32 s25, s25, 0
	s_add_u32 s57, s57, 0x100
	s_addc_u32 s58, s58, 0
	s_cmpk_gt_u32 s59, 0x55
	s_cbranch_scc0 .LBB0_1056
	s_and_b64 vcc, exec, s[10:11]
	s_cbranch_vccz .LBB0_1059
	s_barrier

; #define PG8_STAGE(bufoff, gbase, voff) do { _Pragma("unroll") for (int _i = 0; _i < 2; ++_i) \
;         __builtin_amdgcn_global_load_lds((const unsigned*)((const char*)(gbase) + (voff)[_i]), (PG8_LAS unsigned*)(lds + (bufoff) + ldsw + _i * 8192), 16, 0, 0); } while (0)
; #define PG8_LDA(dst, b, h) do { _Pragma("unroll") for (int m = 0; m < 4; ++m) _Pragma("unroll") for (int k = 0; k < 2; ++k) dst[m][k] = *(const PG8_LAS bf16x8*)(lds + PG8_SA(b, h) + aoff + m * 2048 + k * 1024); } while (0)
; #define PG8_LDB(dst, b, h) do { _Pragma("unroll") for (int n = 0; n < 2; ++n) _Pragma("unroll") for (int k = 0; k < 2; ++k) dst[n][k] = *(const PG8_LAS bf16x8*)(lds + PG8_SB(b, h) + boff + n * 2048 + k * 1024); } while (0)
; template <class Epi, class Sched, bool ALIGN_EPI = false, bool SP2 = false>
; __device__ __forceinline__ void gemm_phase(PG8_LAS unsigned char* lds, const Gemm g, const Sched& S, const Epi& E) {
;     ...
;         for (int t = 0; t < nt; t += 2) {
;             const bool last = (t == nt - 2);
;             const char* a1 = cA + (size_t)(t + 1) * kstep;
;             const char* a2 = last ? nA : cA + (size_t)(t + 2) * kstep; const char* b2 = last ? nB : cB + (size_t)(t + 2) * kstep;
;             const char* a3 = a2 + kstep; const char* b3 = b2 + kstep;
;             if (last && has_next) S.a_ready(nxt);
;             if constexpr (SP2) {
;             PG8_LDB(B0, 0, 0); PG8_LDB(B1, 0, 1); PG8_SCHED; PG8_LDA(At, 0, 0); PG8_STAGE(PG8_SA(1, 1), a1 + hstep, voffA);
;             PG8_WAIT_V(8); PG8_WAIT_L(0); PG8_BAR; PG8_MMA(0, 0, At, B0); PG8_MMA(0, 1, At, B1); PG8_BAR; PG8_SCHED;
;             PG8_LDA(At, 0, 1); PG8_STAGE(PG8_SB(0, 0), b2, voffB); PG8_STAGE(PG8_SB(0, 1), b2 + hstep, voffB); PG8_STAGE(PG8_SA(0, 0), a2, voffA);
;             PG8_WAIT_V(8); PG8_WAIT_L(0); PG8_BAR; PG8_MMA(1, 0, At, B0); PG8_MMA(1, 1, At, B1); PG8_BAR; PG8_SCHED;
;             PG8_LDB(B0, 1, 0); PG8_LDB(B1, 1, 1); PG8_SCHED; PG8_LDA(At, 1, 0); PG8_STAGE(PG8_SA(0, 1), a2 + hstep, voffA);
;             PG8_WAIT_V(8); PG8_WAIT_L(0); PG8_BAR; PG8_MMA(0, 0, At, B0); PG8_MMA(0, 1, At, B1); PG8_BAR; PG8_SCHED;
;             PG8_LDA(At, 1, 1); PG8_STAGE(PG8_SB(1, 0), b3, voffB); PG8_STAGE(PG8_SB(1, 1), b3 + hstep, voffB); PG8_STAGE(PG8_SA(1, 0), a3, voffA);
;             PG8_WAIT_V(8); PG8_WAIT_L(0); PG8_BAR; PG8_MMA(1, 0, At, B0); PG8_MMA(1, 1, At, B1); PG8_BAR; PG8_SCHED;
.LBB0_1068:
	ds_read_b128 v[150:153], v139
	ds_read_b128 v[154:157], v139 offset:1024
	ds_read_b128 v[158:161], v139 offset:2048
	ds_read_b128 v[162:165], v139 offset:3072
	ds_read_b128 v[166:169], v145
	ds_read_b128 v[170:173], v145 offset:1024
	ds_read_b128 v[174:177], v145 offset:2048
	ds_read_b128 v[178:181], v145 offset:3072
	s_add_u32 s14, s10, s12
	s_addc_u32 s15, s11, s13
	s_add_u32 s14, s14, 0x13500100
	s_addc_u32 s15, s15, 0
	s_add_u32 s40, s26, s12
	s_addc_u32 s41, s27, s13
	s_cmpk_eq_i32 s12, 0x1500
	s_cselect_b32 s17, s5, s15
	s_cselect_b32 s16, s4, s14
	s_cselect_b32 s15, s3, s41
	s_cselect_b32 s14, s2, s40
	s_mov_b32 m0, s29
	v_lshl_add_u64 v[214:215], v[140:141], 0, s[12:13]
	ds_read_b128 v[182:185], v146
	ds_read_b128 v[186:189], v146 offset:1024
	ds_read_b128 v[190:193], v146 offset:2048
	ds_read_b128 v[194:197], v146 offset:3072
	ds_read_b128 v[198:201], v146 offset:4096
	ds_read_b128 v[202:205], v146 offset:5120
	ds_read_b128 v[206:209], v146 offset:6144
	ds_read_b128 v[210:213], v146 offset:7168
	global_load_lds_dwordx4 v[214:215], off
	v_lshl_add_u64 v[214:215], v[142:143], 0, s[12:13]
	s_mov_b32 m0, s30
	s_nop 0
	global_load_lds_dwordx4 v[214:215], off
	s_waitcnt vmcnt(8)
	s_waitcnt lgkmcnt(0)
	s_barrier
	s_setprio 1
	s_waitcnt lgkmcnt(0)
	v_mfma_f32_16x16x32_bf16 v[124:127], v[150:153], v[182:185], v[124:127]
	v_mfma_f32_16x16x32_bf16 v[120:123], v[158:161], v[182:185], v[120:123]
	v_mfma_f32_16x16x32_bf16 v[116:119], v[150:153], v[190:193], v[116:119]
	v_mfma_f32_16x16x32_bf16 v[112:115], v[158:161], v[190:193], v[112:115]
	v_mfma_f32_16x16x32_bf16 v[108:111], v[150:153], v[198:201], v[108:111]
	v_mfma_f32_16x16x32_bf16 v[104:107], v[158:161], v[198:201], v[104:107]
	v_mfma_f32_16x16x32_bf16 v[96:99], v[150:153], v[206:209], v[96:99]
	v_mfma_f32_16x16x32_bf16 v[88:91], v[158:161], v[206:209], v[88:91]
	v_mfma_f32_16x16x32_bf16 v[124:127], v[154:157], v[186:189], v[124:127]
	v_mfma_f32_16x16x32_bf16 v[120:123], v[162:165], v[186:189], v[120:123]
	v_mfma_f32_16x16x32_bf16 v[116:119], v[154:157], v[194:197], v[116:119]
	v_mfma_f32_16x16x32_bf16 v[112:115], v[162:165], v[194:197], v[112:115]
	v_mfma_f32_16x16x32_bf16 v[108:111], v[154:157], v[202:205], v[108:111]
	v_mfma_f32_16x16x32_bf16 v[104:107], v[162:165], v[202:205], v[104:107]
	v_mfma_f32_16x16x32_bf16 v[96:99], v[154:157], v[210:213], v[96:99]
	v_mfma_f32_16x16x32_bf16 v[88:91], v[162:165], v[210:213], v[88:91]
	s_setprio 0
	s_setprio 1
	v_mfma_f32_16x16x32_bf16 v[100:103], v[166:169], v[182:185], v[100:103]
	v_mfma_f32_16x16x32_bf16 v[92:95], v[174:177], v[182:185], v[92:95]
	v_mfma_f32_16x16x32_bf16 v[84:87], v[166:169], v[190:193], v[84:87]
	v_mfma_f32_16x16x32_bf16 v[80:83], v[174:177], v[190:193], v[80:83]
	v_mfma_f32_16x16x32_bf16 v[76:79], v[166:169], v[198:201], v[76:79]
	v_mfma_f32_16x16x32_bf16 v[72:75], v[174:177], v[198:201], v[72:75]
	v_mfma_f32_16x16x32_bf16 v[68:71], v[166:169], v[206:209], v[68:71]
	v_mfma_f32_16x16x32_bf16 v[64:67], v[174:177], v[206:209], v[64:67]
	s_setprio 2
	s_barrier
	v_mfma_f32_16x16x32_bf16 v[100:103], v[170:173], v[186:189], v[100:103]
	v_mfma_f32_16x16x32_bf16 v[92:95], v[178:181], v[186:189], v[92:95]
	v_mfma_f32_16x16x32_bf16 v[84:87], v[170:173], v[194:197], v[84:87]
	v_mfma_f32_16x16x32_bf16 v[80:83], v[178:181], v[194:197], v[80:83]
	v_mfma_f32_16x16x32_bf16 v[76:79], v[170:173], v[202:205], v[76:79]
	v_mfma_f32_16x16x32_bf16 v[72:75], v[178:181], v[202:205], v[72:75]
	v_mfma_f32_16x16x32_bf16 v[68:71], v[170:173], v[210:213], v[68:71]
	v_mfma_f32_16x16x32_bf16 v[64:67], v[178:181], v[210:213], v[64:67]
	s_setprio 0
	s_mov_b32 m0, s31
	v_lshl_add_u64 v[214:215], s[14:15], 0, v[132:133]
	s_add_u32 s40, s14, 0x160000
	ds_read_b128 v[182:185], v146 offset:16384
	ds_read_b128 v[186:189], v146 offset:17408
	ds_read_b128 v[190:193], v146 offset:18432
	ds_read_b128 v[194:197], v146 offset:19456
	ds_read_b128 v[198:201], v146 offset:20480
	ds_read_b128 v[202:205], v146 offset:21504
	ds_read_b128 v[206:209], v146 offset:22528
	ds_read_b128 v[210:213], v146 offset:23552
	global_load_lds_dwordx4 v[214:215], off
	v_lshl_add_u64 v[216:217], s[14:15], 0, v[136:137]
	s_mov_b32 m0, s33
	s_addc_u32 s41, s15, 0
	global_load_lds_dwordx4 v[216:217], off
	v_lshl_add_u64 v[218:219], s[40:41], 0, v[132:133]
	s_mov_b32 m0, s34
	v_lshl_add_u64 v[220:221], s[16:17], 0, v[134:135]
	global_load_lds_dwordx4 v[218:219], off
	v_lshl_add_u64 v[218:219], s[40:41], 0, v[136:137]
	s_mov_b32 m0, s35
	s_nop 0
	global_load_lds_dwordx4 v[218:219], off
	v_lshl_add_u64 v[218:219], s[16:17], 0, v[130:131]
	s_mov_b32 m0, s19
	s_nop 0
	global_load_lds_dwordx4 v[218:219], off
	s_mov_b32 m0, s20
	s_nop 0
	global_load_lds_dwordx4 v[220:221], off
	s_waitcnt vmcnt(8)
	s_waitcnt lgkmcnt(0)
	s_barrier
	s_setprio 1
	s_waitcnt lgkmcnt(0)
	v_mfma_f32_16x16x32_bf16 v[60:63], v[150:153], v[182:185], v[60:63]
	v_mfma_f32_16x16x32_bf16 v[56:59], v[158:161], v[182:185], v[56:59]
	v_mfma_f32_16x16x32_bf16 v[52:55], v[150:153], v[190:193], v[52:55]
	v_mfma_f32_16x16x32_bf16 v[48:51], v[158:161], v[190:193], v[48:51]
	v_mfma_f32_16x16x32_bf16 v[44:47], v[150:153], v[198:201], v[44:47]
	v_mfma_f32_16x16x32_bf16 v[40:43], v[158:161], v[198:201], v[40:43]
	v_mfma_f32_16x16x32_bf16 v[32:35], v[150:153], v[206:209], v[32:35]
	v_mfma_f32_16x16x32_bf16 v[24:27], v[158:161], v[206:209], v[24:27]
	v_mfma_f32_16x16x32_bf16 v[60:63], v[154:157], v[186:189], v[60:63]
	v_mfma_f32_16x16x32_bf16 v[56:59], v[162:165], v[186:189], v[56:59]
	v_mfma_f32_16x16x32_bf16 v[52:55], v[154:157], v[194:197], v[52:55]
	v_mfma_f32_16x16x32_bf16 v[48:51], v[162:165], v[194:197], v[48:51]
	v_mfma_f32_16x16x32_bf16 v[44:47], v[154:157], v[202:205], v[44:47]
	v_mfma_f32_16x16x32_bf16 v[40:43], v[162:165], v[202:205], v[40:43]
	v_mfma_f32_16x16x32_bf16 v[32:35], v[154:157], v[210:213], v[32:35]
	v_mfma_f32_16x16x32_bf16 v[24:27], v[162:165], v[210:213], v[24:27]
	s_setprio 0
	s_setprio 1
	v_mfma_f32_16x16x32_bf16 v[36:39], v[166:169], v[182:185], v[36:39]
	v_mfma_f32_16x16x32_bf16 v[28:31], v[174:177], v[182:185], v[28:31]
	v_mfma_f32_16x16x32_bf16 v[20:23], v[166:169], v[190:193], v[20:23]
	v_mfma_f32_16x16x32_bf16 v[16:19], v[174:177], v[190:193], v[16:19]
	v_mfma_f32_16x16x32_bf16 v[12:15], v[166:169], v[198:201], v[12:15]
	v_mfma_f32_16x16x32_bf16 v[8:11], v[174:177], v[198:201], v[8:11]
	v_mfma_f32_16x16x32_bf16 v[4:7], v[166:169], v[206:209], v[4:7]
	v_mfma_f32_16x16x32_bf16 v[0:3], v[174:177], v[206:209], v[0:3]
	s_setprio 2
	s_barrier
; #define PG8_STAGE(bufoff, gbase, voff) do { _Pragma("unroll") for (int _i = 0; _i < 2; ++_i) \
;         __builtin_amdgcn_global_load_lds((const unsigned*)((const char*)(gbase) + (voff)[_i]), (PG8_LAS unsigned*)(lds + (bufoff) + ldsw + _i * 8192), 16, 0, 0); } while (0)
; #define PG8_LDA(dst, b, h) do { _Pragma("unroll") for (int m = 0; m < 4; ++m) _Pragma("unroll") for (int k = 0; k < 2; ++k) dst[m][k] = *(const PG8_LAS bf16x8*)(lds + PG8_SA(b, h) + aoff + m * 2048 + k * 1024); } while (0)
; #define PG8_LDB(dst, b, h) do { _Pragma("unroll") for (int n = 0; n < 2; ++n) _Pragma("unroll") for (int k = 0; k < 2; ++k) dst[n][k] = *(const PG8_LAS bf16x8*)(lds + PG8_SB(b, h) + boff + n * 2048 + k * 1024); } while (0)
; #define PG8_BAR __builtin_amdgcn_s_barrier()
; template <class Epi, class Sched, bool ALIGN_EPI = false, bool SP2 = false>
; __device__ __forceinline__ void gemm_phase(PG8_LAS unsigned char* lds, const Gemm g, const Sched& S, const Epi& E) {
;     ...
;             const bool last = (t == nt - 2);
;             const char* a1 = cA + (size_t)(t + 1) * kstep;
;             const char* a2 = last ? nA : cA + (size_t)(t + 2) * kstep; const char* b2 = last ? nB : cB + (size_t)(t + 2) * kstep;
;             const char* a3 = a2 + kstep; const char* b3 = b2 + kstep;
;             if (last && has_next) S.a_ready(nxt);
;             if constexpr (SP2) {
;             PG8_LDB(B0, 0, 0); PG8_LDB(B1, 0, 1); PG8_SCHED; PG8_LDA(At, 0, 0); PG8_STAGE(PG8_SA(1, 1), a1 + hstep, voffA);
;             PG8_WAIT_V(8); PG8_WAIT_L(0); PG8_BAR; PG8_MMA(0, 0, At, B0); PG8_MMA(0, 1, At, B1); PG8_BAR; PG8_SCHED;
;             PG8_LDA(At, 0, 1); PG8_STAGE(PG8_SB(0, 0), b2, voffB); PG8_STAGE(PG8_SB(0, 1), b2 + hstep, voffB); PG8_STAGE(PG8_SA(0, 0), a2, voffA);
;             PG8_WAIT_V(8); PG8_WAIT_L(0); PG8_BAR; PG8_MMA(1, 0, At, B0); PG8_MMA(1, 1, At, B1); PG8_BAR; PG8_SCHED;
;             PG8_LDB(B0, 1, 0); PG8_LDB(B1, 1, 1); PG8_SCHED; PG8_LDA(At, 1, 0); PG8_STAGE(PG8_SA(0, 1), a2 + hstep, voffA);
;             PG8_WAIT_V(8); PG8_WAIT_L(0); PG8_BAR; PG8_MMA(0, 0, At, B0); PG8_MMA(0, 1, At, B1); PG8_BAR; PG8_SCHED;
;             PG8_LDA(At, 1, 1); PG8_STAGE(PG8_SB(1, 0), b3, voffB); PG8_STAGE(PG8_SB(1, 1), b3 + hstep, voffB); PG8_STAGE(PG8_SA(1, 0), a3, voffA);
;             PG8_WAIT_V(8); PG8_WAIT_L(0); PG8_BAR; PG8_MMA(1, 0, At, B0); PG8_MMA(1, 1, At, B1); PG8_BAR; PG8_SCHED;
	v_mfma_f32_16x16x32_bf16 v[36:39], v[170:173], v[186:189], v[36:39]
	v_mfma_f32_16x16x32_bf16 v[28:31], v[178:181], v[186:189], v[28:31]
	v_mfma_f32_16x16x32_bf16 v[20:23], v[170:173], v[194:197], v[20:23]
	v_mfma_f32_16x16x32_bf16 v[16:19], v[178:181], v[194:197], v[16:19]
	v_mfma_f32_16x16x32_bf16 v[12:15], v[170:173], v[202:205], v[12:15]
	v_mfma_f32_16x16x32_bf16 v[8:11], v[178:181], v[202:205], v[8:11]
	v_mfma_f32_16x16x32_bf16 v[4:7], v[170:173], v[210:213], v[4:7]
	v_mfma_f32_16x16x32_bf16 v[0:3], v[178:181], v[210:213], v[0:3]
	s_setprio 0
	ds_read_b128 v[150:153], v147
	ds_read_b128 v[154:157], v147 offset:1024
	ds_read_b128 v[158:161], v147 offset:2048
	ds_read_b128 v[162:165], v147 offset:3072
	ds_read_b128 v[166:169], v148
	ds_read_b128 v[170:173], v148 offset:1024
	ds_read_b128 v[174:177], v148 offset:2048
	ds_read_b128 v[178:181], v148 offset:3072
	s_add_u32 s16, s16, 0x160000
	s_addc_u32 s17, s17, 0
	s_mov_b32 m0, s21
	v_lshl_add_u64 v[222:223], s[16:17], 0, v[130:131]
	ds_read_b128 v[182:185], v146 offset:32768
	ds_read_b128 v[186:189], v146 offset:33792
	ds_read_b128 v[190:193], v146 offset:34816
	ds_read_b128 v[194:197], v146 offset:35840
	ds_read_b128 v[198:201], v146 offset:36864
	ds_read_b128 v[202:205], v146 offset:37888
	ds_read_b128 v[206:209], v146 offset:38912
	ds_read_b128 v[210:213], v146 offset:39936
	global_load_lds_dwordx4 v[222:223], off
	v_lshl_add_u64 v[222:223], s[16:17], 0, v[134:135]
	s_mov_b32 m0, s22
	s_nop 0
	global_load_lds_dwordx4 v[222:223], off
	s_waitcnt vmcnt(8)
	s_waitcnt lgkmcnt(0)
	s_barrier
	s_setprio 1
	s_waitcnt lgkmcnt(0)
	v_mfma_f32_16x16x32_bf16 v[124:127], v[150:153], v[182:185], v[124:127]
	v_mfma_f32_16x16x32_bf16 v[120:123], v[158:161], v[182:185], v[120:123]
	v_mfma_f32_16x16x32_bf16 v[116:119], v[150:153], v[190:193], v[116:119]
	v_mfma_f32_16x16x32_bf16 v[112:115], v[158:161], v[190:193], v[112:115]
	v_mfma_f32_16x16x32_bf16 v[108:111], v[150:153], v[198:201], v[108:111]
	v_mfma_f32_16x16x32_bf16 v[104:107], v[158:161], v[198:201], v[104:107]
	v_mfma_f32_16x16x32_bf16 v[96:99], v[150:153], v[206:209], v[96:99]
	v_mfma_f32_16x16x32_bf16 v[88:91], v[158:161], v[206:209], v[88:91]
	v_mfma_f32_16x16x32_bf16 v[124:127], v[154:157], v[186:189], v[124:127]
	v_mfma_f32_16x16x32_bf16 v[120:123], v[162:165], v[186:189], v[120:123]
	v_mfma_f32_16x16x32_bf16 v[116:119], v[154:157], v[194:197], v[116:119]
	v_mfma_f32_16x16x32_bf16 v[112:115], v[162:165], v[194:197], v[112:115]
	v_mfma_f32_16x16x32_bf16 v[108:111], v[154:157], v[202:205], v[108:111]
	v_mfma_f32_16x16x32_bf16 v[104:107], v[162:165], v[202:205], v[104:107]
	v_mfma_f32_16x16x32_bf16 v[96:99], v[154:157], v[210:213], v[96:99]
	v_mfma_f32_16x16x32_bf16 v[88:91], v[162:165], v[210:213], v[88:91]
	s_setprio 0
	s_setprio 1
	v_mfma_f32_16x16x32_bf16 v[100:103], v[166:169], v[182:185], v[100:103]
	v_mfma_f32_16x16x32_bf16 v[92:95], v[174:177], v[182:185], v[92:95]
	v_mfma_f32_16x16x32_bf16 v[84:87], v[166:169], v[190:193], v[84:87]
	v_mfma_f32_16x16x32_bf16 v[80:83], v[174:177], v[190:193], v[80:83]
	v_mfma_f32_16x16x32_bf16 v[76:79], v[166:169], v[198:201], v[76:79]
	v_mfma_f32_16x16x32_bf16 v[72:75], v[174:177], v[198:201], v[72:75]
	v_mfma_f32_16x16x32_bf16 v[68:71], v[166:169], v[206:209], v[68:71]
	v_mfma_f32_16x16x32_bf16 v[64:67], v[174:177], v[206:209], v[64:67]
	s_setprio 2
	s_barrier
; #define PG8_STAGE(bufoff, gbase, voff) do { _Pragma("unroll") for (int _i = 0; _i < 2; ++_i) \
;         __builtin_amdgcn_global_load_lds((const unsigned*)((const char*)(gbase) + (voff)[_i]), (PG8_LAS unsigned*)(lds + (bufoff) + ldsw + _i * 8192), 16, 0, 0); } while (0)
; #define PG8_LDA(dst, b, h) do { _Pragma("unroll") for (int m = 0; m < 4; ++m) _Pragma("unroll") for (int k = 0; k < 2; ++k) dst[m][k] = *(const PG8_LAS bf16x8*)(lds + PG8_SA(b, h) + aoff + m * 2048 + k * 1024); } while (0)
; #define PG8_WAIT_V(n) asm volatile("s_waitcnt vmcnt(" #n ")" ::: "memory")
; #define PG8_WAIT_L(n) asm volatile("s_waitcnt lgkmcnt(" #n ")" ::: "memory")
; template <class Epi, class Sched, bool ALIGN_EPI = false, bool SP2 = false>
; __device__ __forceinline__ void gemm_phase(PG8_LAS unsigned char* lds, const Gemm g, const Sched& S, const Epi& E) {
;     ...
;         for (int t = 0; t < nt; t += 2) {
;             const bool last = (t == nt - 2);
;             const char* a1 = cA + (size_t)(t + 1) * kstep;
;             const char* a2 = last ? nA : cA + (size_t)(t + 2) * kstep; const char* b2 = last ? nB : cB + (size_t)(t + 2) * kstep;
;             const char* a3 = a2 + kstep; const char* b3 = b2 + kstep;
;             if (last && has_next) S.a_ready(nxt);
;             if constexpr (SP2) {
;             PG8_LDB(B0, 0, 0); PG8_LDB(B1, 0, 1); PG8_SCHED; PG8_LDA(At, 0, 0); PG8_STAGE(PG8_SA(1, 1), a1 + hstep, voffA);
;             PG8_WAIT_V(8); PG8_WAIT_L(0); PG8_BAR; PG8_MMA(0, 0, At, B0); PG8_MMA(0, 1, At, B1); PG8_BAR; PG8_SCHED;
;             PG8_LDA(At, 0, 1); PG8_STAGE(PG8_SB(0, 0), b2, voffB); PG8_STAGE(PG8_SB(0, 1), b2 + hstep, voffB); PG8_STAGE(PG8_SA(0, 0), a2, voffA);
;             PG8_WAIT_V(8); PG8_WAIT_L(0); PG8_BAR; PG8_MMA(1, 0, At, B0); PG8_MMA(1, 1, At, B1); PG8_BAR; PG8_SCHED;
;             PG8_LDB(B0, 1, 0); PG8_LDB(B1, 1, 1); PG8_SCHED; PG8_LDA(At, 1, 0); PG8_STAGE(PG8_SA(0, 1), a2 + hstep, voffA);
;             PG8_WAIT_V(8); PG8_WAIT_L(0); PG8_BAR; PG8_MMA(0, 0, At, B0); PG8_MMA(0, 1, At, B1); PG8_BAR; PG8_SCHED;
;             PG8_LDA(At, 1, 1); PG8_STAGE(PG8_SB(1, 0), b3, voffB); PG8_STAGE(PG8_SB(1, 1), b3 + hstep, voffB); PG8_STAGE(PG8_SA(1, 0), a3, voffA);
;             PG8_WAIT_V(8); PG8_WAIT_L(0); PG8_BAR; PG8_MMA(1, 0, At, B0); PG8_MMA(1, 1, At, B1); PG8_BAR; PG8_SCHED;
;     ...
;         if constexpr (ALIGN_EPI) { if (wr == 0) PG8_BAR; }
	v_mfma_f32_16x16x32_bf16 v[100:103], v[170:173], v[186:189], v[100:103]
	v_mfma_f32_16x16x32_bf16 v[92:95], v[178:181], v[186:189], v[92:95]
	v_mfma_f32_16x16x32_bf16 v[84:87], v[170:173], v[194:197], v[84:87]
	v_mfma_f32_16x16x32_bf16 v[80:83], v[178:181], v[194:197], v[80:83]
	v_mfma_f32_16x16x32_bf16 v[76:79], v[170:173], v[202:205], v[76:79]
	v_mfma_f32_16x16x32_bf16 v[72:75], v[178:181], v[202:205], v[72:75]
	v_mfma_f32_16x16x32_bf16 v[68:71], v[170:173], v[210:213], v[68:71]
	v_mfma_f32_16x16x32_bf16 v[64:67], v[178:181], v[210:213], v[64:67]
	s_setprio 0
	s_mov_b32 m0, s36
	v_lshl_add_u64 v[214:215], v[214:215], 0, s[6:7]
	s_add_u32 s14, s14, 0x160080
	ds_read_b128 v[182:185], v146 offset:49152
	ds_read_b128 v[186:189], v146 offset:50176
	ds_read_b128 v[190:193], v146 offset:51200
	ds_read_b128 v[194:197], v146 offset:52224
	ds_read_b128 v[198:201], v146 offset:53248
	ds_read_b128 v[202:205], v146 offset:54272
	ds_read_b128 v[206:209], v146 offset:55296
	ds_read_b128 v[210:213], v146 offset:56320
	global_load_lds_dwordx4 v[214:215], off
	v_lshl_add_u64 v[214:215], v[216:217], 0, s[6:7]
	s_mov_b32 m0, s37
	s_addc_u32 s15, s15, 0
	global_load_lds_dwordx4 v[214:215], off
	v_lshl_add_u64 v[214:215], s[14:15], 0, v[132:133]
	s_mov_b32 m0, s38
	s_nop 0
	global_load_lds_dwordx4 v[214:215], off
	v_lshl_add_u64 v[214:215], s[14:15], 0, v[136:137]
	s_mov_b32 m0, s39
	s_nop 0
	global_load_lds_dwordx4 v[214:215], off
	v_lshl_add_u64 v[214:215], v[218:219], 0, s[6:7]
	s_mov_b32 m0, s24
	s_nop 0
	global_load_lds_dwordx4 v[214:215], off
	v_lshl_add_u64 v[214:215], v[220:221], 0, s[6:7]
	s_mov_b32 m0, s25
	s_nop 0
	global_load_lds_dwordx4 v[214:215], off
	s_waitcnt vmcnt(8)
	s_waitcnt lgkmcnt(0)
	s_barrier
	s_setprio 1
	s_waitcnt lgkmcnt(0)
	v_mfma_f32_16x16x32_bf16 v[60:63], v[150:153], v[182:185], v[60:63]
	v_mfma_f32_16x16x32_bf16 v[56:59], v[158:161], v[182:185], v[56:59]
	v_mfma_f32_16x16x32_bf16 v[52:55], v[150:153], v[190:193], v[52:55]
	v_mfma_f32_16x16x32_bf16 v[48:51], v[158:161], v[190:193], v[48:51]
	v_mfma_f32_16x16x32_bf16 v[44:47], v[150:153], v[198:201], v[44:47]
	v_mfma_f32_16x16x32_bf16 v[40:43], v[158:161], v[198:201], v[40:43]
	v_mfma_f32_16x16x32_bf16 v[32:35], v[150:153], v[206:209], v[32:35]
	v_mfma_f32_16x16x32_bf16 v[24:27], v[158:161], v[206:209], v[24:27]
	v_mfma_f32_16x16x32_bf16 v[60:63], v[154:157], v[186:189], v[60:63]
	v_mfma_f32_16x16x32_bf16 v[56:59], v[162:165], v[186:189], v[56:59]
	v_mfma_f32_16x16x32_bf16 v[52:55], v[154:157], v[194:197], v[52:55]
	v_mfma_f32_16x16x32_bf16 v[48:51], v[162:165], v[194:197], v[48:51]
	v_mfma_f32_16x16x32_bf16 v[44:47], v[154:157], v[202:205], v[44:47]
	v_mfma_f32_16x16x32_bf16 v[40:43], v[162:165], v[202:205], v[40:43]
	v_mfma_f32_16x16x32_bf16 v[32:35], v[154:157], v[210:213], v[32:35]
	v_mfma_f32_16x16x32_bf16 v[24:27], v[162:165], v[210:213], v[24:27]
	s_setprio 0
	s_setprio 1
	v_mfma_f32_16x16x32_bf16 v[36:39], v[166:169], v[182:185], v[36:39]
	v_mfma_f32_16x16x32_bf16 v[28:31], v[174:177], v[182:185], v[28:31]
	v_mfma_f32_16x16x32_bf16 v[20:23], v[166:169], v[190:193], v[20:23]
	v_mfma_f32_16x16x32_bf16 v[16:19], v[174:177], v[190:193], v[16:19]
	v_mfma_f32_16x16x32_bf16 v[12:15], v[166:169], v[198:201], v[12:15]
	v_mfma_f32_16x16x32_bf16 v[8:11], v[174:177], v[198:201], v[8:11]
	v_mfma_f32_16x16x32_bf16 v[4:7], v[166:169], v[206:209], v[4:7]
	v_mfma_f32_16x16x32_bf16 v[0:3], v[174:177], v[206:209], v[0:3]
	s_setprio 2
	s_barrier
	v_mfma_f32_16x16x32_bf16 v[36:39], v[170:173], v[186:189], v[36:39]
	v_mfma_f32_16x16x32_bf16 v[28:31], v[178:181], v[186:189], v[28:31]
	v_mfma_f32_16x16x32_bf16 v[20:23], v[170:173], v[194:197], v[20:23]
	v_mfma_f32_16x16x32_bf16 v[16:19], v[178:181], v[194:197], v[16:19]
	v_mfma_f32_16x16x32_bf16 v[12:15], v[170:173], v[202:205], v[12:15]
	v_mfma_f32_16x16x32_bf16 v[8:11], v[178:181], v[202:205], v[8:11]
	v_mfma_f32_16x16x32_bf16 v[4:7], v[170:173], v[210:213], v[4:7]
	v_mfma_f32_16x16x32_bf16 v[0:3], v[178:181], v[210:213], v[0:3]
	s_setprio 0
	s_add_i32 s28, s28, 2
	s_add_u32 s12, s12, 0x100
	s_addc_u32 s13, s13, 0
	s_cmp_gt_u32 s28, 41
	s_cbranch_scc0 .LBB0_1068
	s_cmpk_lt_u32 s18, 0x100
	s_cbranch_scc0 .LBB0_1071
	s_barrier

; #define PG8_STAGE(bufoff, gbase, voff) do { _Pragma("unroll") for (int _i = 0; _i < 2; ++_i) \
;         __builtin_amdgcn_global_load_lds((const unsigned*)((const char*)(gbase) + (voff)[_i]), (PG8_LAS unsigned*)(lds + (bufoff) + ldsw + _i * 8192), 16, 0, 0); } while (0)
; #define PG8_LDA(dst, b, h) do { _Pragma("unroll") for (int m = 0; m < 4; ++m) _Pragma("unroll") for (int k = 0; k < 2; ++k) dst[m][k] = *(const PG8_LAS bf16x8*)(lds + PG8_SA(b, h) + aoff + m * 2048 + k * 1024); } while (0)
; #define PG8_LDB(dst, b, h) do { _Pragma("unroll") for (int n = 0; n < 2; ++n) _Pragma("unroll") for (int k = 0; k < 2; ++k) dst[n][k] = *(const PG8_LAS bf16x8*)(lds + PG8_SB(b, h) + boff + n * 2048 + k * 1024); } while (0)
; #define PG8_BAR __builtin_amdgcn_s_barrier()
; template <class Epi, class Sched, bool ALIGN_EPI = false, bool SP2 = false>
; __device__ __forceinline__ void gemm_phase(PG8_LAS unsigned char* lds, const Gemm g, const Sched& S, const Epi& E) {
;     ...
;             const bool last = (t == nt - 2);
;             const char* a1 = cA + (size_t)(t + 1) * kstep;
;             const char* a2 = last ? nA : cA + (size_t)(t + 2) * kstep; const char* b2 = last ? nB : cB + (size_t)(t + 2) * kstep;
;             const char* a3 = a2 + kstep; const char* b3 = b2 + kstep;
;             if (last && has_next) S.a_ready(nxt);
;             if constexpr (SP2) {
;             PG8_LDB(B0, 0, 0); PG8_LDB(B1, 0, 1); PG8_SCHED; PG8_LDA(At, 0, 0); PG8_STAGE(PG8_SA(1, 1), a1 + hstep, voffA);
;             PG8_WAIT_V(8); PG8_WAIT_L(0); PG8_BAR; PG8_MMA(0, 0, At, B0); PG8_MMA(0, 1, At, B1); PG8_BAR; PG8_SCHED;
;             PG8_LDA(At, 0, 1); PG8_STAGE(PG8_SB(0, 0), b2, voffB); PG8_STAGE(PG8_SB(0, 1), b2 + hstep, voffB); PG8_STAGE(PG8_SA(0, 0), a2, voffA);
;             PG8_WAIT_V(8); PG8_WAIT_L(0); PG8_BAR; PG8_MMA(1, 0, At, B0); PG8_MMA(1, 1, At, B1); PG8_BAR; PG8_SCHED;
;             PG8_LDB(B0, 1, 0); PG8_LDB(B1, 1, 1); PG8_SCHED; PG8_LDA(At, 1, 0); PG8_STAGE(PG8_SA(0, 1), a2 + hstep, voffA);
;             PG8_WAIT_V(8); PG8_WAIT_L(0); PG8_BAR; PG8_MMA(0, 0, At, B0); PG8_MMA(0, 1, At, B1); PG8_BAR; PG8_SCHED;
;             PG8_LDA(At, 1, 1); PG8_STAGE(PG8_SB(1, 0), b3, voffB); PG8_STAGE(PG8_SB(1, 1), b3 + hstep, voffB); PG8_STAGE(PG8_SA(1, 0), a3, voffA);
;             PG8_WAIT_V(8); PG8_WAIT_L(0); PG8_BAR; PG8_MMA(1, 0, At, B0); PG8_MMA(1, 1, At, B1); PG8_BAR; PG8_SCHED;
.LBB0_1260:
	ds_read_b128 v[146:149], v129
	ds_read_b128 v[158:161], v129 offset:1024
	ds_read_b128 v[162:165], v129 offset:2048
	ds_read_b128 v[166:169], v129 offset:3072
	ds_read_b128 v[170:173], v155
	ds_read_b128 v[174:177], v155 offset:1024
	ds_read_b128 v[178:181], v155 offset:2048
	ds_read_b128 v[182:185], v155 offset:3072
	s_add_u32 s34, s30, 0xfff80080
	s_addc_u32 s35, s31, -1
	s_cmp_eq_u32 s57, 28
	s_cselect_b32 s37, s23, s35
	s_cselect_b32 s36, s53, s34
	s_cselect_b32 s35, s21, s56
	s_cselect_b32 s34, s54, s55
	v_lshl_add_u64 v[150:151], s[30:31], 0, v[138:139]
	s_add_i32 m0, s29, 0xc000
	ds_read_b128 v[186:189], v156
	ds_read_b128 v[190:193], v156 offset:1024
	ds_read_b128 v[194:197], v156 offset:2048
	ds_read_b128 v[198:201], v156 offset:3072
	ds_read_b128 v[202:205], v156 offset:4096
	ds_read_b128 v[206:209], v156 offset:5120
	ds_read_b128 v[210:213], v156 offset:6144
	ds_read_b128 v[214:217], v156 offset:7168
	global_load_lds_dwordx4 v[150:151], off
	v_lshl_add_u64 v[150:151], s[30:31], 0, v[140:141]
	s_add_i32 m0, s29, 0xe000
	s_nop 0
	global_load_lds_dwordx4 v[150:151], off
	s_waitcnt vmcnt(8)
	s_waitcnt lgkmcnt(0)
	s_barrier
	s_setprio 1
	s_waitcnt lgkmcnt(0)
	v_mfma_f32_16x16x32_bf16 v[124:127], v[146:149], v[186:189], v[124:127]
	v_mfma_f32_16x16x32_bf16 v[120:123], v[162:165], v[186:189], v[120:123]
	v_mfma_f32_16x16x32_bf16 v[108:111], v[146:149], v[194:197], v[108:111]
	v_mfma_f32_16x16x32_bf16 v[104:107], v[162:165], v[194:197], v[104:107]
	v_mfma_f32_16x16x32_bf16 v[92:95], v[146:149], v[202:205], v[92:95]
	v_mfma_f32_16x16x32_bf16 v[88:91], v[162:165], v[202:205], v[88:91]
	v_mfma_f32_16x16x32_bf16 v[76:79], v[146:149], v[210:213], v[76:79]
	v_mfma_f32_16x16x32_bf16 v[72:75], v[162:165], v[210:213], v[72:75]
	v_mfma_f32_16x16x32_bf16 v[124:127], v[158:161], v[190:193], v[124:127]
	v_mfma_f32_16x16x32_bf16 v[120:123], v[166:169], v[190:193], v[120:123]
	v_mfma_f32_16x16x32_bf16 v[108:111], v[158:161], v[198:201], v[108:111]
	v_mfma_f32_16x16x32_bf16 v[104:107], v[166:169], v[198:201], v[104:107]
	v_mfma_f32_16x16x32_bf16 v[92:95], v[158:161], v[206:209], v[92:95]
	v_mfma_f32_16x16x32_bf16 v[88:91], v[166:169], v[206:209], v[88:91]
	v_mfma_f32_16x16x32_bf16 v[76:79], v[158:161], v[214:217], v[76:79]
	v_mfma_f32_16x16x32_bf16 v[72:75], v[166:169], v[214:217], v[72:75]
	s_setprio 0
	s_setprio 1
	v_mfma_f32_16x16x32_bf16 v[116:119], v[170:173], v[186:189], v[116:119]
	v_mfma_f32_16x16x32_bf16 v[112:115], v[178:181], v[186:189], v[112:115]
	v_mfma_f32_16x16x32_bf16 v[100:103], v[170:173], v[194:197], v[100:103]
	v_mfma_f32_16x16x32_bf16 v[96:99], v[178:181], v[194:197], v[96:99]
	v_mfma_f32_16x16x32_bf16 v[84:87], v[170:173], v[202:205], v[84:87]
	v_mfma_f32_16x16x32_bf16 v[80:83], v[178:181], v[202:205], v[80:83]
	v_mfma_f32_16x16x32_bf16 v[68:71], v[170:173], v[210:213], v[68:71]
	v_mfma_f32_16x16x32_bf16 v[64:67], v[178:181], v[210:213], v[64:67]
	s_setprio 2
	s_barrier
	v_mfma_f32_16x16x32_bf16 v[116:119], v[174:177], v[190:193], v[116:119]
	v_mfma_f32_16x16x32_bf16 v[112:115], v[182:185], v[190:193], v[112:115]
	v_mfma_f32_16x16x32_bf16 v[100:103], v[174:177], v[198:201], v[100:103]
	v_mfma_f32_16x16x32_bf16 v[96:99], v[182:185], v[198:201], v[96:99]
	v_mfma_f32_16x16x32_bf16 v[84:87], v[174:177], v[206:209], v[84:87]
	v_mfma_f32_16x16x32_bf16 v[80:83], v[182:185], v[206:209], v[80:83]
	v_mfma_f32_16x16x32_bf16 v[68:71], v[174:177], v[214:217], v[68:71]
	v_mfma_f32_16x16x32_bf16 v[64:67], v[182:185], v[214:217], v[64:67]
	s_setprio 0
	s_add_i32 s58, s50, s33
	v_lshl_add_u64 v[150:151], s[34:35], 0, v[134:135]
	s_mov_b32 m0, s58
	ds_read_b128 v[186:189], v156 offset:16384
	ds_read_b128 v[190:193], v156 offset:17408
	ds_read_b128 v[194:197], v156 offset:18432
	ds_read_b128 v[198:201], v156 offset:19456
	ds_read_b128 v[202:205], v156 offset:20480
	ds_read_b128 v[206:209], v156 offset:21504
	ds_read_b128 v[210:213], v156 offset:22528
	ds_read_b128 v[214:217], v156 offset:23552
	global_load_lds_dwordx4 v[150:151], off
	s_add_i32 m0, s58, 0x2000
	s_add_u32 s58, s34, 0x80000
	v_lshl_add_u64 v[218:219], s[34:35], 0, v[130:131]
	s_addc_u32 s59, s35, 0
	s_add_i32 s60, s51, s33
	global_load_lds_dwordx4 v[218:219], off
	v_lshl_add_u64 v[220:221], s[58:59], 0, v[134:135]
	s_mov_b32 m0, s60
	v_lshl_add_u64 v[222:223], s[36:37], 0, v[132:133]
	global_load_lds_dwordx4 v[220:221], off
	v_lshl_add_u64 v[220:221], s[58:59], 0, v[130:131]
	s_add_i32 m0, s60, 0x2000
	s_nop 0
	global_load_lds_dwordx4 v[220:221], off
	v_lshl_add_u64 v[220:221], s[36:37], 0, v[136:137]
	s_mov_b32 m0, s29
	s_nop 0
	global_load_lds_dwordx4 v[220:221], off
	s_mov_b32 m0, s40
	s_nop 0
	global_load_lds_dwordx4 v[222:223], off
	s_waitcnt vmcnt(8)
	s_waitcnt lgkmcnt(0)
	s_barrier
	s_setprio 1
	s_waitcnt lgkmcnt(0)
	v_mfma_f32_16x16x32_bf16 v[60:63], v[146:149], v[186:189], v[60:63]
	v_mfma_f32_16x16x32_bf16 v[56:59], v[162:165], v[186:189], v[56:59]
	v_mfma_f32_16x16x32_bf16 v[44:47], v[146:149], v[194:197], v[44:47]
	v_mfma_f32_16x16x32_bf16 v[40:43], v[162:165], v[194:197], v[40:43]
	v_mfma_f32_16x16x32_bf16 v[28:31], v[146:149], v[202:205], v[28:31]
	v_mfma_f32_16x16x32_bf16 v[24:27], v[162:165], v[202:205], v[24:27]
	v_mfma_f32_16x16x32_bf16 v[12:15], v[146:149], v[210:213], v[12:15]
	v_mfma_f32_16x16x32_bf16 v[8:11], v[162:165], v[210:213], v[8:11]
	v_mfma_f32_16x16x32_bf16 v[60:63], v[158:161], v[190:193], v[60:63]
	v_mfma_f32_16x16x32_bf16 v[56:59], v[166:169], v[190:193], v[56:59]
	v_mfma_f32_16x16x32_bf16 v[44:47], v[158:161], v[198:201], v[44:47]
	v_mfma_f32_16x16x32_bf16 v[40:43], v[166:169], v[198:201], v[40:43]
	v_mfma_f32_16x16x32_bf16 v[28:31], v[158:161], v[206:209], v[28:31]
	v_mfma_f32_16x16x32_bf16 v[24:27], v[166:169], v[206:209], v[24:27]
	v_mfma_f32_16x16x32_bf16 v[12:15], v[158:161], v[214:217], v[12:15]
	v_mfma_f32_16x16x32_bf16 v[8:11], v[166:169], v[214:217], v[8:11]
	s_setprio 0
	s_setprio 1
	v_mfma_f32_16x16x32_bf16 v[52:55], v[170:173], v[186:189], v[52:55]
	v_mfma_f32_16x16x32_bf16 v[48:51], v[178:181], v[186:189], v[48:51]
	v_mfma_f32_16x16x32_bf16 v[36:39], v[170:173], v[194:197], v[36:39]
	v_mfma_f32_16x16x32_bf16 v[32:35], v[178:181], v[194:197], v[32:35]
	v_mfma_f32_16x16x32_bf16 v[20:23], v[170:173], v[202:205], v[20:23]
	v_mfma_f32_16x16x32_bf16 v[16:19], v[178:181], v[202:205], v[16:19]
	v_mfma_f32_16x16x32_bf16 v[4:7], v[170:173], v[210:213], v[4:7]
	v_mfma_f32_16x16x32_bf16 v[0:3], v[178:181], v[210:213], v[0:3]
	s_setprio 2
	s_barrier
; #define PG8_STAGE(bufoff, gbase, voff) do { _Pragma("unroll") for (int _i = 0; _i < 2; ++_i) \
;         __builtin_amdgcn_global_load_lds((const unsigned*)((const char*)(gbase) + (voff)[_i]), (PG8_LAS unsigned*)(lds + (bufoff) + ldsw + _i * 8192), 16, 0, 0); } while (0)
; #define PG8_LDA(dst, b, h) do { _Pragma("unroll") for (int m = 0; m < 4; ++m) _Pragma("unroll") for (int k = 0; k < 2; ++k) dst[m][k] = *(const PG8_LAS bf16x8*)(lds + PG8_SA(b, h) + aoff + m * 2048 + k * 1024); } while (0)
; #define PG8_LDB(dst, b, h) do { _Pragma("unroll") for (int n = 0; n < 2; ++n) _Pragma("unroll") for (int k = 0; k < 2; ++k) dst[n][k] = *(const PG8_LAS bf16x8*)(lds + PG8_SB(b, h) + boff + n * 2048 + k * 1024); } while (0)
; #define PG8_BAR __builtin_amdgcn_s_barrier()
; template <class Epi, class Sched, bool ALIGN_EPI = false, bool SP2 = false>
; __device__ __forceinline__ void gemm_phase(PG8_LAS unsigned char* lds, const Gemm g, const Sched& S, const Epi& E) {
;     ...
;             const bool last = (t == nt - 2);
;             const char* a1 = cA + (size_t)(t + 1) * kstep;
;             const char* a2 = last ? nA : cA + (size_t)(t + 2) * kstep; const char* b2 = last ? nB : cB + (size_t)(t + 2) * kstep;
;             const char* a3 = a2 + kstep; const char* b3 = b2 + kstep;
;             if (last && has_next) S.a_ready(nxt);
;             if constexpr (SP2) {
;             PG8_LDB(B0, 0, 0); PG8_LDB(B1, 0, 1); PG8_SCHED; PG8_LDA(At, 0, 0); PG8_STAGE(PG8_SA(1, 1), a1 + hstep, voffA);
;             PG8_WAIT_V(8); PG8_WAIT_L(0); PG8_BAR; PG8_MMA(0, 0, At, B0); PG8_MMA(0, 1, At, B1); PG8_BAR; PG8_SCHED;
;             PG8_LDA(At, 0, 1); PG8_STAGE(PG8_SB(0, 0), b2, voffB); PG8_STAGE(PG8_SB(0, 1), b2 + hstep, voffB); PG8_STAGE(PG8_SA(0, 0), a2, voffA);
;             PG8_WAIT_V(8); PG8_WAIT_L(0); PG8_BAR; PG8_MMA(1, 0, At, B0); PG8_MMA(1, 1, At, B1); PG8_BAR; PG8_SCHED;
;             PG8_LDB(B0, 1, 0); PG8_LDB(B1, 1, 1); PG8_SCHED; PG8_LDA(At, 1, 0); PG8_STAGE(PG8_SA(0, 1), a2 + hstep, voffA);
;             PG8_WAIT_V(8); PG8_WAIT_L(0); PG8_BAR; PG8_MMA(0, 0, At, B0); PG8_MMA(0, 1, At, B1); PG8_BAR; PG8_SCHED;
;             PG8_LDA(At, 1, 1); PG8_STAGE(PG8_SB(1, 0), b3, voffB); PG8_STAGE(PG8_SB(1, 1), b3 + hstep, voffB); PG8_STAGE(PG8_SA(1, 0), a3, voffA);
;             PG8_WAIT_V(8); PG8_WAIT_L(0); PG8_BAR; PG8_MMA(1, 0, At, B0); PG8_MMA(1, 1, At, B1); PG8_BAR; PG8_SCHED;
	v_mfma_f32_16x16x32_bf16 v[52:55], v[174:177], v[190:193], v[52:55]
	v_mfma_f32_16x16x32_bf16 v[48:51], v[182:185], v[190:193], v[48:51]
	v_mfma_f32_16x16x32_bf16 v[36:39], v[174:177], v[198:201], v[36:39]
	v_mfma_f32_16x16x32_bf16 v[32:35], v[182:185], v[198:201], v[32:35]
	v_mfma_f32_16x16x32_bf16 v[20:23], v[174:177], v[206:209], v[20:23]
	v_mfma_f32_16x16x32_bf16 v[16:19], v[182:185], v[206:209], v[16:19]
	v_mfma_f32_16x16x32_bf16 v[4:7], v[174:177], v[214:217], v[4:7]
	v_mfma_f32_16x16x32_bf16 v[0:3], v[182:185], v[214:217], v[0:3]
	s_setprio 0
	s_add_i32 s58, 0, 0x18000
	v_add_u32_e32 v157, s58, v153
	s_add_i32 s59, 0, 0x1c000
	ds_read_b128 v[146:149], v157
	ds_read_b128 v[158:161], v157 offset:1024
	ds_read_b128 v[162:165], v157 offset:2048
	ds_read_b128 v[166:169], v157 offset:3072
	v_add_u32_e32 v157, s59, v153
	ds_read_b128 v[170:173], v157
	ds_read_b128 v[174:177], v157 offset:1024
	ds_read_b128 v[178:181], v157 offset:2048
	ds_read_b128 v[182:185], v157 offset:3072
	s_add_u32 s36, s36, 0x80000
	s_addc_u32 s37, s37, 0
	s_mov_b32 m0, s41
	v_lshl_add_u64 v[224:225], s[36:37], 0, v[136:137]
	ds_read_b128 v[186:189], v156 offset:32768
	ds_read_b128 v[190:193], v156 offset:33792
	ds_read_b128 v[194:197], v156 offset:34816
	ds_read_b128 v[198:201], v156 offset:35840
	ds_read_b128 v[202:205], v156 offset:36864
	ds_read_b128 v[206:209], v156 offset:37888
	ds_read_b128 v[210:213], v156 offset:38912
	ds_read_b128 v[214:217], v156 offset:39936
	global_load_lds_dwordx4 v[224:225], off
	v_lshl_add_u64 v[224:225], s[36:37], 0, v[132:133]
	s_mov_b32 m0, s42
	s_nop 0
	global_load_lds_dwordx4 v[224:225], off
	s_waitcnt vmcnt(8)
	s_waitcnt lgkmcnt(0)
	s_barrier
	s_setprio 1
	s_waitcnt lgkmcnt(0)
	v_mfma_f32_16x16x32_bf16 v[124:127], v[146:149], v[186:189], v[124:127]
	v_mfma_f32_16x16x32_bf16 v[120:123], v[162:165], v[186:189], v[120:123]
	v_mfma_f32_16x16x32_bf16 v[108:111], v[146:149], v[194:197], v[108:111]
	v_mfma_f32_16x16x32_bf16 v[104:107], v[162:165], v[194:197], v[104:107]
	v_mfma_f32_16x16x32_bf16 v[92:95], v[146:149], v[202:205], v[92:95]
	v_mfma_f32_16x16x32_bf16 v[88:91], v[162:165], v[202:205], v[88:91]
	v_mfma_f32_16x16x32_bf16 v[76:79], v[146:149], v[210:213], v[76:79]
	v_mfma_f32_16x16x32_bf16 v[72:75], v[162:165], v[210:213], v[72:75]
	v_mfma_f32_16x16x32_bf16 v[124:127], v[158:161], v[190:193], v[124:127]
	v_mfma_f32_16x16x32_bf16 v[120:123], v[166:169], v[190:193], v[120:123]
	v_mfma_f32_16x16x32_bf16 v[108:111], v[158:161], v[198:201], v[108:111]
	v_mfma_f32_16x16x32_bf16 v[104:107], v[166:169], v[198:201], v[104:107]
	v_mfma_f32_16x16x32_bf16 v[92:95], v[158:161], v[206:209], v[92:95]
	v_mfma_f32_16x16x32_bf16 v[88:91], v[166:169], v[206:209], v[88:91]
	v_mfma_f32_16x16x32_bf16 v[76:79], v[158:161], v[214:217], v[76:79]
	v_mfma_f32_16x16x32_bf16 v[72:75], v[166:169], v[214:217], v[72:75]
	s_setprio 0
	s_setprio 1
	v_mfma_f32_16x16x32_bf16 v[116:119], v[170:173], v[186:189], v[116:119]
	v_mfma_f32_16x16x32_bf16 v[112:115], v[178:181], v[186:189], v[112:115]
	v_mfma_f32_16x16x32_bf16 v[100:103], v[170:173], v[194:197], v[100:103]
	v_mfma_f32_16x16x32_bf16 v[96:99], v[178:181], v[194:197], v[96:99]
	v_mfma_f32_16x16x32_bf16 v[84:87], v[170:173], v[202:205], v[84:87]
	v_mfma_f32_16x16x32_bf16 v[80:83], v[178:181], v[202:205], v[80:83]
	v_mfma_f32_16x16x32_bf16 v[68:71], v[170:173], v[210:213], v[68:71]
	v_mfma_f32_16x16x32_bf16 v[64:67], v[178:181], v[210:213], v[64:67]
	s_setprio 2
	s_barrier
; #define PG8_STAGE(bufoff, gbase, voff) do { _Pragma("unroll") for (int _i = 0; _i < 2; ++_i) \
;         __builtin_amdgcn_global_load_lds((const unsigned*)((const char*)(gbase) + (voff)[_i]), (PG8_LAS unsigned*)(lds + (bufoff) + ldsw + _i * 8192), 16, 0, 0); } while (0)
; #define PG8_LDA(dst, b, h) do { _Pragma("unroll") for (int m = 0; m < 4; ++m) _Pragma("unroll") for (int k = 0; k < 2; ++k) dst[m][k] = *(const PG8_LAS bf16x8*)(lds + PG8_SA(b, h) + aoff + m * 2048 + k * 1024); } while (0)
; #define PG8_WAIT_V(n) asm volatile("s_waitcnt vmcnt(" #n ")" ::: "memory")
; #define PG8_WAIT_L(n) asm volatile("s_waitcnt lgkmcnt(" #n ")" ::: "memory")
; template <class Epi, class Sched, bool ALIGN_EPI = false, bool SP2 = false>
; __device__ __forceinline__ void gemm_phase(PG8_LAS unsigned char* lds, const Gemm g, const Sched& S, const Epi& E) {
;     ...
;         for (int t = 0; t < nt; t += 2) {
;             const bool last = (t == nt - 2);
;             const char* a1 = cA + (size_t)(t + 1) * kstep;
;             const char* a2 = last ? nA : cA + (size_t)(t + 2) * kstep; const char* b2 = last ? nB : cB + (size_t)(t + 2) * kstep;
;             const char* a3 = a2 + kstep; const char* b3 = b2 + kstep;
;             if (last && has_next) S.a_ready(nxt);
;             if constexpr (SP2) {
;             PG8_LDB(B0, 0, 0); PG8_LDB(B1, 0, 1); PG8_SCHED; PG8_LDA(At, 0, 0); PG8_STAGE(PG8_SA(1, 1), a1 + hstep, voffA);
;             PG8_WAIT_V(8); PG8_WAIT_L(0); PG8_BAR; PG8_MMA(0, 0, At, B0); PG8_MMA(0, 1, At, B1); PG8_BAR; PG8_SCHED;
;             PG8_LDA(At, 0, 1); PG8_STAGE(PG8_SB(0, 0), b2, voffB); PG8_STAGE(PG8_SB(0, 1), b2 + hstep, voffB); PG8_STAGE(PG8_SA(0, 0), a2, voffA);
;             PG8_WAIT_V(8); PG8_WAIT_L(0); PG8_BAR; PG8_MMA(1, 0, At, B0); PG8_MMA(1, 1, At, B1); PG8_BAR; PG8_SCHED;
;             PG8_LDB(B0, 1, 0); PG8_LDB(B1, 1, 1); PG8_SCHED; PG8_LDA(At, 1, 0); PG8_STAGE(PG8_SA(0, 1), a2 + hstep, voffA);
;             PG8_WAIT_V(8); PG8_WAIT_L(0); PG8_BAR; PG8_MMA(0, 0, At, B0); PG8_MMA(0, 1, At, B1); PG8_BAR; PG8_SCHED;
;             PG8_LDA(At, 1, 1); PG8_STAGE(PG8_SB(1, 0), b3, voffB); PG8_STAGE(PG8_SB(1, 1), b3 + hstep, voffB); PG8_STAGE(PG8_SA(1, 0), a3, voffA);
;             PG8_WAIT_V(8); PG8_WAIT_L(0); PG8_BAR; PG8_MMA(1, 0, At, B0); PG8_MMA(1, 1, At, B1); PG8_BAR; PG8_SCHED;
;     ...
;         if constexpr (ALIGN_EPI) { if (wr == 0) PG8_BAR; }
	v_mfma_f32_16x16x32_bf16 v[116:119], v[174:177], v[190:193], v[116:119]
	v_mfma_f32_16x16x32_bf16 v[112:115], v[182:185], v[190:193], v[112:115]
	v_mfma_f32_16x16x32_bf16 v[100:103], v[174:177], v[198:201], v[100:103]
	v_mfma_f32_16x16x32_bf16 v[96:99], v[182:185], v[198:201], v[96:99]
	v_mfma_f32_16x16x32_bf16 v[84:87], v[174:177], v[206:209], v[84:87]
	v_mfma_f32_16x16x32_bf16 v[80:83], v[182:185], v[206:209], v[80:83]
	v_mfma_f32_16x16x32_bf16 v[68:71], v[174:177], v[214:217], v[68:71]
	v_mfma_f32_16x16x32_bf16 v[64:67], v[182:185], v[214:217], v[64:67]
	s_setprio 0
	s_add_i32 s36, s58, s33
	v_lshl_add_u64 v[150:151], v[150:151], 0, s[10:11]
	s_mov_b32 m0, s36
	ds_read_b128 v[186:189], v156 offset:49152
	ds_read_b128 v[190:193], v156 offset:50176
	ds_read_b128 v[194:197], v156 offset:51200
	ds_read_b128 v[198:201], v156 offset:52224
	ds_read_b128 v[202:205], v156 offset:53248
	ds_read_b128 v[206:209], v156 offset:54272
	ds_read_b128 v[210:213], v156 offset:55296
	ds_read_b128 v[214:217], v156 offset:56320
	global_load_lds_dwordx4 v[150:151], off
	s_add_i32 m0, s36, 0x2000
	s_add_u32 s34, s34, 0x80080
	v_lshl_add_u64 v[150:151], v[218:219], 0, s[10:11]
	s_addc_u32 s35, s35, 0
	s_add_i32 s36, s59, s33
	global_load_lds_dwordx4 v[150:151], off
	v_lshl_add_u64 v[150:151], s[34:35], 0, v[134:135]
	s_mov_b32 m0, s36
	s_nop 0
	global_load_lds_dwordx4 v[150:151], off
	v_lshl_add_u64 v[150:151], s[34:35], 0, v[130:131]
	s_add_i32 m0, s36, 0x2000
	s_nop 0
	global_load_lds_dwordx4 v[150:151], off
	v_lshl_add_u64 v[150:151], v[220:221], 0, s[10:11]
	s_mov_b32 m0, s44
	s_nop 0
	global_load_lds_dwordx4 v[150:151], off
	v_lshl_add_u64 v[150:151], v[222:223], 0, s[10:11]
	s_mov_b32 m0, s45
	s_nop 0
	global_load_lds_dwordx4 v[150:151], off
	s_waitcnt vmcnt(8)
	s_waitcnt lgkmcnt(0)
	s_barrier
	s_setprio 1
	s_waitcnt lgkmcnt(0)
	v_mfma_f32_16x16x32_bf16 v[60:63], v[146:149], v[186:189], v[60:63]
	v_mfma_f32_16x16x32_bf16 v[56:59], v[162:165], v[186:189], v[56:59]
	v_mfma_f32_16x16x32_bf16 v[44:47], v[146:149], v[194:197], v[44:47]
	v_mfma_f32_16x16x32_bf16 v[40:43], v[162:165], v[194:197], v[40:43]
	v_mfma_f32_16x16x32_bf16 v[28:31], v[146:149], v[202:205], v[28:31]
	v_mfma_f32_16x16x32_bf16 v[24:27], v[162:165], v[202:205], v[24:27]
	v_mfma_f32_16x16x32_bf16 v[12:15], v[146:149], v[210:213], v[12:15]
	v_mfma_f32_16x16x32_bf16 v[8:11], v[162:165], v[210:213], v[8:11]
	v_mfma_f32_16x16x32_bf16 v[60:63], v[158:161], v[190:193], v[60:63]
	v_mfma_f32_16x16x32_bf16 v[56:59], v[166:169], v[190:193], v[56:59]
	v_mfma_f32_16x16x32_bf16 v[44:47], v[158:161], v[198:201], v[44:47]
	v_mfma_f32_16x16x32_bf16 v[40:43], v[166:169], v[198:201], v[40:43]
	v_mfma_f32_16x16x32_bf16 v[28:31], v[158:161], v[206:209], v[28:31]
	v_mfma_f32_16x16x32_bf16 v[24:27], v[166:169], v[206:209], v[24:27]
	v_mfma_f32_16x16x32_bf16 v[12:15], v[158:161], v[214:217], v[12:15]
	v_mfma_f32_16x16x32_bf16 v[8:11], v[166:169], v[214:217], v[8:11]
	s_setprio 0
	s_setprio 1
	v_mfma_f32_16x16x32_bf16 v[52:55], v[170:173], v[186:189], v[52:55]
	v_mfma_f32_16x16x32_bf16 v[48:51], v[178:181], v[186:189], v[48:51]
	v_mfma_f32_16x16x32_bf16 v[36:39], v[170:173], v[194:197], v[36:39]
	v_mfma_f32_16x16x32_bf16 v[32:35], v[178:181], v[194:197], v[32:35]
	v_mfma_f32_16x16x32_bf16 v[20:23], v[170:173], v[202:205], v[20:23]
	v_mfma_f32_16x16x32_bf16 v[16:19], v[178:181], v[202:205], v[16:19]
	v_mfma_f32_16x16x32_bf16 v[4:7], v[170:173], v[210:213], v[4:7]
	v_mfma_f32_16x16x32_bf16 v[0:3], v[178:181], v[210:213], v[0:3]
	s_setprio 2
	s_barrier
	v_mfma_f32_16x16x32_bf16 v[52:55], v[174:177], v[190:193], v[52:55]
	v_mfma_f32_16x16x32_bf16 v[48:51], v[182:185], v[190:193], v[48:51]
	v_mfma_f32_16x16x32_bf16 v[36:39], v[174:177], v[198:201], v[36:39]
	v_mfma_f32_16x16x32_bf16 v[32:35], v[182:185], v[198:201], v[32:35]
	v_mfma_f32_16x16x32_bf16 v[20:23], v[174:177], v[206:209], v[20:23]
	v_mfma_f32_16x16x32_bf16 v[16:19], v[182:185], v[206:209], v[16:19]
	v_mfma_f32_16x16x32_bf16 v[4:7], v[174:177], v[214:217], v[4:7]
	v_mfma_f32_16x16x32_bf16 v[0:3], v[182:185], v[214:217], v[0:3]
	s_setprio 0
	s_add_i32 s57, s57, 2
	s_add_u32 s30, s30, 0x100
	s_addc_u32 s31, s31, 0
	s_add_u32 s55, s55, 0x100
	s_addc_u32 s56, s56, 0
	s_cmp_gt_u32 s57, 29
	s_cbranch_scc0 .LBB0_1260
	s_and_b64 vcc, exec, s[12:13]
	s_cbranch_vccz .LBB0_1263
	s_barrier
